# prep step 4: forward substitution rewritten by hand (single row buffer refilled behind the FMAs, packed f32 FMA, SGPR store addressing)
# speedup vs baseline: 1.0183x; 1.0183x over previous
.Lfs_start:
	v_readlane_b32 s22, v253, 47
	v_readlane_b32 s23, v253, 48
	v_mov_b32_e32 v233, 0xcc00
	s_lshl_b64 s[0:1], s[14:15], 10
	v_readlane_b32 s11, v253, 49
	s_nop 1
	s_add_u32 s0, s11, s0
	v_readlane_b32 s11, v253, 50
	s_nop 1
	s_addc_u32 s1, s11, s1
	s_lshl_b32 s11, s53, 1
	s_add_u32 s0, s0, s11
	s_addc_u32 s1, s1, 0
	ds_read_u16 v106, v9 offset:0
	ds_read_u16 v107, v9 offset:272
	ds_read_u16 v108, v9 offset:544
	ds_read_u16 v109, v9 offset:816
	ds_read_u16 v110, v9 offset:1088
	ds_read_u16 v111, v9 offset:1360
	ds_read_u16 v112, v9 offset:1632
	ds_read_u16 v113, v9 offset:1904
	ds_read_u16 v114, v9 offset:2176
	ds_read_u16 v115, v9 offset:2448
	ds_read_u16 v116, v9 offset:2720
	ds_read_u16 v117, v9 offset:2992
	ds_read_u16 v118, v9 offset:3264
	ds_read_u16 v119, v9 offset:3536
	ds_read_u16 v120, v9 offset:3808
	ds_read_u16 v121, v9 offset:4080
	ds_read_u16 v122, v9 offset:4352
	ds_read_u16 v123, v9 offset:4624
	ds_read_u16 v124, v9 offset:4896
	ds_read_u16 v125, v9 offset:5168
	ds_read_u16 v126, v9 offset:5440
	ds_read_u16 v127, v9 offset:5712
	ds_read_u16 v128, v9 offset:5984
	ds_read_u16 v129, v9 offset:6256
	ds_read_u16 v130, v9 offset:6528
	ds_read_u16 v131, v9 offset:6800
	ds_read_u16 v132, v9 offset:7072
	ds_read_u16 v133, v9 offset:7344
	ds_read_u16 v134, v9 offset:7616
	ds_read_u16 v135, v9 offset:7888
	ds_read_u16 v136, v9 offset:8160
	ds_read_u16 v137, v9 offset:8432
	ds_read_u16 v138, v9 offset:8704
	ds_read_u16 v139, v9 offset:8976
	ds_read_u16 v140, v9 offset:9248
	ds_read_u16 v141, v9 offset:9520
	ds_read_u16 v142, v9 offset:9792
	ds_read_u16 v143, v9 offset:10064
	ds_read_u16 v144, v9 offset:10336
	ds_read_u16 v145, v9 offset:10608
	ds_read_u16 v146, v9 offset:10880
	ds_read_u16 v147, v9 offset:11152
	ds_read_u16 v148, v9 offset:11424
	ds_read_u16 v149, v9 offset:11696
	ds_read_u16 v150, v9 offset:11968
	ds_read_u16 v151, v9 offset:12240
	ds_read_u16 v152, v9 offset:12512
	ds_read_u16 v153, v9 offset:12784
	ds_read_u16 v154, v9 offset:13056
	ds_read_u16 v155, v9 offset:13328
	ds_read_u16 v180, v9 offset:13600
	ds_read_u16 v181, v9 offset:13872
	ds_read_u16 v182, v9 offset:14144
	ds_read_u16 v183, v9 offset:14416
	ds_read_u16 v184, v9 offset:14688
	ds_read_u16 v185, v9 offset:14960
	ds_read_u16 v186, v9 offset:15232
	ds_read_u16 v187, v9 offset:15504
	ds_read_u16 v188, v9 offset:15776
	ds_read_u16 v189, v9 offset:16048
	ds_read_u16 v190, v9 offset:16320
	ds_read_u16 v191, v9 offset:16592
	ds_read_u16 v192, v9 offset:16864
	ds_read_u16 v193, v9 offset:17136
	ds_read_b128 v[30:33], v233 offset:17664
	ds_read_b128 v[34:37], v233 offset:17680
	ds_read_b128 v[38:41], v233 offset:17696
	ds_read_b128 v[42:45], v233 offset:17712
	ds_read_b128 v[46:49], v233 offset:17728
	ds_read_b128 v[50:53], v233 offset:17744
	ds_read_b128 v[54:57], v233 offset:17760
	ds_read_b128 v[58:61], v233 offset:17776
	ds_read_b128 v[62:65], v233 offset:18176
	ds_read_b128 v[66:69], v233 offset:18192
	ds_read_b128 v[70:73], v233 offset:18208
	ds_read_b128 v[194:197], v233 offset:18224
	ds_read_b128 v[198:201], v233 offset:18240
	ds_read_b128 v[202:205], v233 offset:18256
	ds_read_b128 v[206:209], v233 offset:18272
	ds_read_b128 v[226:229], v233 offset:18288
	s_waitcnt lgkmcnt(0)
	v_cndmask_b32_e64 v62, 1.0, v62, s[22:23]
	v_lshlrev_b32_e32 v106, 16, v106
	v_mul_f32_e32 v30, v30, v62
	v_mul_f32_e32 v106, v30, v106
	v_cndmask_b32_e64 v63, 1.0, v63, s[22:23]
	v_lshlrev_b32_e32 v107, 16, v107
	v_mul_f32_e32 v31, v31, v63
	v_mul_f32_e32 v107, v31, v107
	v_cndmask_b32_e64 v64, 1.0, v64, s[22:23]
	v_lshlrev_b32_e32 v108, 16, v108
	v_mul_f32_e32 v32, v32, v64
	v_mul_f32_e32 v108, v32, v108
	v_cndmask_b32_e64 v65, 1.0, v65, s[22:23]
	v_lshlrev_b32_e32 v109, 16, v109
	v_mul_f32_e32 v33, v33, v65
	v_mul_f32_e32 v109, v33, v109
	v_cndmask_b32_e64 v66, 1.0, v66, s[22:23]
	v_lshlrev_b32_e32 v110, 16, v110
	v_mul_f32_e32 v34, v34, v66
	v_mul_f32_e32 v110, v34, v110
	v_cndmask_b32_e64 v67, 1.0, v67, s[22:23]
	v_lshlrev_b32_e32 v111, 16, v111
	v_mul_f32_e32 v35, v35, v67
	v_mul_f32_e32 v111, v35, v111
	v_cndmask_b32_e64 v68, 1.0, v68, s[22:23]
	v_lshlrev_b32_e32 v112, 16, v112
	v_mul_f32_e32 v36, v36, v68
	v_mul_f32_e32 v112, v36, v112
	v_cndmask_b32_e64 v69, 1.0, v69, s[22:23]
	v_lshlrev_b32_e32 v113, 16, v113
	v_mul_f32_e32 v37, v37, v69
	v_mul_f32_e32 v113, v37, v113
	v_cndmask_b32_e64 v70, 1.0, v70, s[22:23]
	v_lshlrev_b32_e32 v114, 16, v114
	v_mul_f32_e32 v38, v38, v70
	v_mul_f32_e32 v114, v38, v114
	v_cndmask_b32_e64 v71, 1.0, v71, s[22:23]
	v_lshlrev_b32_e32 v115, 16, v115
	v_mul_f32_e32 v39, v39, v71
	v_mul_f32_e32 v115, v39, v115
	v_cndmask_b32_e64 v72, 1.0, v72, s[22:23]
	v_lshlrev_b32_e32 v116, 16, v116
	v_mul_f32_e32 v40, v40, v72
	v_mul_f32_e32 v116, v40, v116
	v_cndmask_b32_e64 v73, 1.0, v73, s[22:23]
	v_lshlrev_b32_e32 v117, 16, v117
	v_mul_f32_e32 v41, v41, v73
	v_mul_f32_e32 v117, v41, v117
	v_cndmask_b32_e64 v194, 1.0, v194, s[22:23]
	v_lshlrev_b32_e32 v118, 16, v118
	v_mul_f32_e32 v42, v42, v194
	v_mul_f32_e32 v118, v42, v118
	v_cndmask_b32_e64 v195, 1.0, v195, s[22:23]
	v_lshlrev_b32_e32 v119, 16, v119
	v_mul_f32_e32 v43, v43, v195
	v_mul_f32_e32 v119, v43, v119
	v_cndmask_b32_e64 v196, 1.0, v196, s[22:23]
	v_lshlrev_b32_e32 v120, 16, v120
	v_mul_f32_e32 v44, v44, v196
	v_mul_f32_e32 v120, v44, v120
	v_cndmask_b32_e64 v197, 1.0, v197, s[22:23]
	v_lshlrev_b32_e32 v121, 16, v121
	v_mul_f32_e32 v45, v45, v197
	v_mul_f32_e32 v121, v45, v121
	v_cndmask_b32_e64 v198, 1.0, v198, s[22:23]
	v_lshlrev_b32_e32 v122, 16, v122
	v_mul_f32_e32 v46, v46, v198
	v_mul_f32_e32 v122, v46, v122
	v_cndmask_b32_e64 v199, 1.0, v199, s[22:23]
	v_lshlrev_b32_e32 v123, 16, v123
	v_mul_f32_e32 v47, v47, v199
	v_mul_f32_e32 v123, v47, v123
	v_cndmask_b32_e64 v200, 1.0, v200, s[22:23]
	v_lshlrev_b32_e32 v124, 16, v124
	v_mul_f32_e32 v48, v48, v200
	v_mul_f32_e32 v124, v48, v124
	v_cndmask_b32_e64 v201, 1.0, v201, s[22:23]
	v_lshlrev_b32_e32 v125, 16, v125
	v_mul_f32_e32 v49, v49, v201
	v_mul_f32_e32 v125, v49, v125
	v_cndmask_b32_e64 v202, 1.0, v202, s[22:23]
	v_lshlrev_b32_e32 v126, 16, v126
	v_mul_f32_e32 v50, v50, v202
	v_mul_f32_e32 v126, v50, v126
	v_cndmask_b32_e64 v203, 1.0, v203, s[22:23]
	v_lshlrev_b32_e32 v127, 16, v127
	v_mul_f32_e32 v51, v51, v203
	v_mul_f32_e32 v127, v51, v127
	v_cndmask_b32_e64 v204, 1.0, v204, s[22:23]
	v_lshlrev_b32_e32 v128, 16, v128
	v_mul_f32_e32 v52, v52, v204
	v_mul_f32_e32 v128, v52, v128
	v_cndmask_b32_e64 v205, 1.0, v205, s[22:23]
	v_lshlrev_b32_e32 v129, 16, v129
	v_mul_f32_e32 v53, v53, v205
	v_mul_f32_e32 v129, v53, v129
	v_cndmask_b32_e64 v206, 1.0, v206, s[22:23]
	v_lshlrev_b32_e32 v130, 16, v130
	v_mul_f32_e32 v54, v54, v206
	v_mul_f32_e32 v130, v54, v130
	v_cndmask_b32_e64 v207, 1.0, v207, s[22:23]
	v_lshlrev_b32_e32 v131, 16, v131
	v_mul_f32_e32 v55, v55, v207
	v_mul_f32_e32 v131, v55, v131
	v_cndmask_b32_e64 v208, 1.0, v208, s[22:23]
	v_lshlrev_b32_e32 v132, 16, v132
	v_mul_f32_e32 v56, v56, v208
	v_mul_f32_e32 v132, v56, v132
	v_cndmask_b32_e64 v209, 1.0, v209, s[22:23]
	v_lshlrev_b32_e32 v133, 16, v133
	v_mul_f32_e32 v57, v57, v209
	v_mul_f32_e32 v133, v57, v133
	v_cndmask_b32_e64 v226, 1.0, v226, s[22:23]
	v_lshlrev_b32_e32 v134, 16, v134
	v_mul_f32_e32 v58, v58, v226
	v_mul_f32_e32 v134, v58, v134
	v_cndmask_b32_e64 v227, 1.0, v227, s[22:23]
	v_lshlrev_b32_e32 v135, 16, v135
	v_mul_f32_e32 v59, v59, v227
	v_mul_f32_e32 v135, v59, v135
	v_cndmask_b32_e64 v228, 1.0, v228, s[22:23]
	v_lshlrev_b32_e32 v136, 16, v136
	v_mul_f32_e32 v60, v60, v228
	v_mul_f32_e32 v136, v60, v136
	v_cndmask_b32_e64 v229, 1.0, v229, s[22:23]
	v_lshlrev_b32_e32 v137, 16, v137
	v_mul_f32_e32 v61, v61, v229
	v_mul_f32_e32 v137, v61, v137
	ds_read_b128 v[30:33], v233 offset:17792
	ds_read_b128 v[34:37], v233 offset:17808
	ds_read_b128 v[38:41], v233 offset:17824
	ds_read_b128 v[42:45], v233 offset:17840
	ds_read_b128 v[46:49], v233 offset:17856
	ds_read_b128 v[50:53], v233 offset:17872
	ds_read_b128 v[54:57], v233 offset:17888
	ds_read_b128 v[58:61], v233 offset:17904
	ds_read_b128 v[62:65], v233 offset:18304
	ds_read_b128 v[66:69], v233 offset:18320
	ds_read_b128 v[70:73], v233 offset:18336
	ds_read_b128 v[194:197], v233 offset:18352
	ds_read_b128 v[198:201], v233 offset:18368
	ds_read_b128 v[202:205], v233 offset:18384
	ds_read_b128 v[206:209], v233 offset:18400
	ds_read_b128 v[226:229], v233 offset:18416
	s_waitcnt lgkmcnt(0)
	v_cndmask_b32_e64 v62, 1.0, v62, s[22:23]
	v_lshlrev_b32_e32 v138, 16, v138
	v_mul_f32_e32 v30, v30, v62
	v_mul_f32_e32 v138, v30, v138
	v_cndmask_b32_e64 v63, 1.0, v63, s[22:23]
	v_lshlrev_b32_e32 v139, 16, v139
	v_mul_f32_e32 v31, v31, v63
	v_mul_f32_e32 v139, v31, v139
	v_cndmask_b32_e64 v64, 1.0, v64, s[22:23]
	v_lshlrev_b32_e32 v140, 16, v140
	v_mul_f32_e32 v32, v32, v64
	v_mul_f32_e32 v140, v32, v140
	v_cndmask_b32_e64 v65, 1.0, v65, s[22:23]
	v_lshlrev_b32_e32 v141, 16, v141
	v_mul_f32_e32 v33, v33, v65
	v_mul_f32_e32 v141, v33, v141
	v_cndmask_b32_e64 v66, 1.0, v66, s[22:23]
	v_lshlrev_b32_e32 v142, 16, v142
	v_mul_f32_e32 v34, v34, v66
	v_mul_f32_e32 v142, v34, v142
	v_cndmask_b32_e64 v67, 1.0, v67, s[22:23]
	v_lshlrev_b32_e32 v143, 16, v143
	v_mul_f32_e32 v35, v35, v67
	v_mul_f32_e32 v143, v35, v143
	v_cndmask_b32_e64 v68, 1.0, v68, s[22:23]
	v_lshlrev_b32_e32 v144, 16, v144
	v_mul_f32_e32 v36, v36, v68
	v_mul_f32_e32 v144, v36, v144
	v_cndmask_b32_e64 v69, 1.0, v69, s[22:23]
	v_lshlrev_b32_e32 v145, 16, v145
	v_mul_f32_e32 v37, v37, v69
	v_mul_f32_e32 v145, v37, v145
	v_cndmask_b32_e64 v70, 1.0, v70, s[22:23]
	v_lshlrev_b32_e32 v146, 16, v146
	v_mul_f32_e32 v38, v38, v70
	v_mul_f32_e32 v146, v38, v146
	v_cndmask_b32_e64 v71, 1.0, v71, s[22:23]
	v_lshlrev_b32_e32 v147, 16, v147
	v_mul_f32_e32 v39, v39, v71
	v_mul_f32_e32 v147, v39, v147
	v_cndmask_b32_e64 v72, 1.0, v72, s[22:23]
	v_lshlrev_b32_e32 v148, 16, v148
	v_mul_f32_e32 v40, v40, v72
	v_mul_f32_e32 v148, v40, v148
	v_cndmask_b32_e64 v73, 1.0, v73, s[22:23]
	v_lshlrev_b32_e32 v149, 16, v149
	v_mul_f32_e32 v41, v41, v73
	v_mul_f32_e32 v149, v41, v149
	v_cndmask_b32_e64 v194, 1.0, v194, s[22:23]
	v_lshlrev_b32_e32 v150, 16, v150
	v_mul_f32_e32 v42, v42, v194
	v_mul_f32_e32 v150, v42, v150
	v_cndmask_b32_e64 v195, 1.0, v195, s[22:23]
	v_lshlrev_b32_e32 v151, 16, v151
	v_mul_f32_e32 v43, v43, v195
	v_mul_f32_e32 v151, v43, v151
	v_cndmask_b32_e64 v196, 1.0, v196, s[22:23]
	v_lshlrev_b32_e32 v152, 16, v152
	v_mul_f32_e32 v44, v44, v196
	v_mul_f32_e32 v152, v44, v152
	v_cndmask_b32_e64 v197, 1.0, v197, s[22:23]
	v_lshlrev_b32_e32 v153, 16, v153
	v_mul_f32_e32 v45, v45, v197
	v_mul_f32_e32 v153, v45, v153
	v_cndmask_b32_e64 v198, 1.0, v198, s[22:23]
	v_lshlrev_b32_e32 v154, 16, v154
	v_mul_f32_e32 v46, v46, v198
	v_mul_f32_e32 v154, v46, v154
	v_cndmask_b32_e64 v199, 1.0, v199, s[22:23]
	v_lshlrev_b32_e32 v155, 16, v155
	v_mul_f32_e32 v47, v47, v199
	v_mul_f32_e32 v155, v47, v155
	v_cndmask_b32_e64 v200, 1.0, v200, s[22:23]
	v_lshlrev_b32_e32 v180, 16, v180
	v_mul_f32_e32 v48, v48, v200
	v_mul_f32_e32 v180, v48, v180
	v_cndmask_b32_e64 v201, 1.0, v201, s[22:23]
	v_lshlrev_b32_e32 v181, 16, v181
	v_mul_f32_e32 v49, v49, v201
	v_mul_f32_e32 v181, v49, v181
	v_cndmask_b32_e64 v202, 1.0, v202, s[22:23]
	v_lshlrev_b32_e32 v182, 16, v182
	v_mul_f32_e32 v50, v50, v202
	v_mul_f32_e32 v182, v50, v182
	v_cndmask_b32_e64 v203, 1.0, v203, s[22:23]
	v_lshlrev_b32_e32 v183, 16, v183
	v_mul_f32_e32 v51, v51, v203
	v_mul_f32_e32 v183, v51, v183
	v_cndmask_b32_e64 v204, 1.0, v204, s[22:23]
	v_lshlrev_b32_e32 v184, 16, v184
	v_mul_f32_e32 v52, v52, v204
	v_mul_f32_e32 v184, v52, v184
	v_cndmask_b32_e64 v205, 1.0, v205, s[22:23]
	v_lshlrev_b32_e32 v185, 16, v185
	v_mul_f32_e32 v53, v53, v205
	v_mul_f32_e32 v185, v53, v185
	v_cndmask_b32_e64 v206, 1.0, v206, s[22:23]
	v_lshlrev_b32_e32 v186, 16, v186
	v_mul_f32_e32 v54, v54, v206
	v_mul_f32_e32 v186, v54, v186
	v_cndmask_b32_e64 v207, 1.0, v207, s[22:23]
	v_lshlrev_b32_e32 v187, 16, v187
	v_mul_f32_e32 v55, v55, v207
	v_mul_f32_e32 v187, v55, v187
	v_cndmask_b32_e64 v208, 1.0, v208, s[22:23]
	v_lshlrev_b32_e32 v188, 16, v188
	v_mul_f32_e32 v56, v56, v208
	v_mul_f32_e32 v188, v56, v188
	v_cndmask_b32_e64 v209, 1.0, v209, s[22:23]
	v_lshlrev_b32_e32 v189, 16, v189
	v_mul_f32_e32 v57, v57, v209
	v_mul_f32_e32 v189, v57, v189
	v_cndmask_b32_e64 v226, 1.0, v226, s[22:23]
	v_lshlrev_b32_e32 v190, 16, v190
	v_mul_f32_e32 v58, v58, v226
	v_mul_f32_e32 v190, v58, v190
	v_cndmask_b32_e64 v227, 1.0, v227, s[22:23]
	v_lshlrev_b32_e32 v191, 16, v191
	v_mul_f32_e32 v59, v59, v227
	v_mul_f32_e32 v191, v59, v191
	v_cndmask_b32_e64 v228, 1.0, v228, s[22:23]
	v_lshlrev_b32_e32 v192, 16, v192
	v_mul_f32_e32 v60, v60, v228
	v_mul_f32_e32 v192, v60, v192
	v_cndmask_b32_e64 v229, 1.0, v229, s[22:23]
	v_lshlrev_b32_e32 v193, 16, v193
	v_mul_f32_e32 v61, v61, v229
	v_mul_f32_e32 v193, v61, v193
	ds_read_b128 v[30:33], v233 offset:0
	ds_read_b128 v[34:37], v233 offset:16
	ds_read_b128 v[38:41], v233 offset:32
	ds_read_b128 v[42:45], v233 offset:48
	ds_read_b128 v[46:49], v233 offset:64
	ds_read_b128 v[50:53], v233 offset:80
	ds_read_b128 v[54:57], v233 offset:96
	ds_read_b128 v[58:61], v233 offset:112
	ds_read_b128 v[62:65], v233 offset:128
	ds_read_b128 v[66:69], v233 offset:144
	ds_read_b128 v[70:73], v233 offset:160
	ds_read_b128 v[194:197], v233 offset:176
	ds_read_b128 v[198:201], v233 offset:192
	ds_read_b128 v[202:205], v233 offset:208
	ds_read_b128 v[206:209], v233 offset:224
	ds_read_b128 v[226:229], v233 offset:240
	v_mov_b32_e32 v230, v106
	v_cvt_pk_bf16_f32 v232, v230, v230
	global_store_short v28, v232, s[0:1]
	s_add_u32 s0, s0, 0x400
	s_addc_u32 s1, s1, 0
	s_waitcnt lgkmcnt(14)
	v_pk_fma_f32 v[106:107], v[30:31], v[230:231], v[106:107] op_sel_hi:[1,0,1] neg_lo:[0,1,0] neg_hi:[0,1,0]
	v_pk_fma_f32 v[108:109], v[32:33], v[230:231], v[108:109] op_sel_hi:[1,0,1] neg_lo:[0,1,0] neg_hi:[0,1,0]
	ds_read_b128 v[30:33], v233 offset:272
	v_pk_fma_f32 v[110:111], v[34:35], v[230:231], v[110:111] op_sel_hi:[1,0,1] neg_lo:[0,1,0] neg_hi:[0,1,0]
	v_pk_fma_f32 v[112:113], v[36:37], v[230:231], v[112:113] op_sel_hi:[1,0,1] neg_lo:[0,1,0] neg_hi:[0,1,0]
	ds_read_b128 v[34:37], v233 offset:288
	s_waitcnt lgkmcnt(14)
	v_pk_fma_f32 v[114:115], v[38:39], v[230:231], v[114:115] op_sel_hi:[1,0,1] neg_lo:[0,1,0] neg_hi:[0,1,0]
	v_pk_fma_f32 v[116:117], v[40:41], v[230:231], v[116:117] op_sel_hi:[1,0,1] neg_lo:[0,1,0] neg_hi:[0,1,0]
	ds_read_b128 v[38:41], v233 offset:304
	v_pk_fma_f32 v[118:119], v[42:43], v[230:231], v[118:119] op_sel_hi:[1,0,1] neg_lo:[0,1,0] neg_hi:[0,1,0]
	v_pk_fma_f32 v[120:121], v[44:45], v[230:231], v[120:121] op_sel_hi:[1,0,1] neg_lo:[0,1,0] neg_hi:[0,1,0]
	ds_read_b128 v[42:45], v233 offset:320
	s_waitcnt lgkmcnt(14)
	v_pk_fma_f32 v[122:123], v[46:47], v[230:231], v[122:123] op_sel_hi:[1,0,1] neg_lo:[0,1,0] neg_hi:[0,1,0]
	v_pk_fma_f32 v[124:125], v[48:49], v[230:231], v[124:125] op_sel_hi:[1,0,1] neg_lo:[0,1,0] neg_hi:[0,1,0]
	ds_read_b128 v[46:49], v233 offset:336
	v_pk_fma_f32 v[126:127], v[50:51], v[230:231], v[126:127] op_sel_hi:[1,0,1] neg_lo:[0,1,0] neg_hi:[0,1,0]
	v_pk_fma_f32 v[128:129], v[52:53], v[230:231], v[128:129] op_sel_hi:[1,0,1] neg_lo:[0,1,0] neg_hi:[0,1,0]
	ds_read_b128 v[50:53], v233 offset:352
	s_waitcnt lgkmcnt(14)
	v_pk_fma_f32 v[130:131], v[54:55], v[230:231], v[130:131] op_sel_hi:[1,0,1] neg_lo:[0,1,0] neg_hi:[0,1,0]
	v_pk_fma_f32 v[132:133], v[56:57], v[230:231], v[132:133] op_sel_hi:[1,0,1] neg_lo:[0,1,0] neg_hi:[0,1,0]
	ds_read_b128 v[54:57], v233 offset:368
	v_pk_fma_f32 v[134:135], v[58:59], v[230:231], v[134:135] op_sel_hi:[1,0,1] neg_lo:[0,1,0] neg_hi:[0,1,0]
	v_pk_fma_f32 v[136:137], v[60:61], v[230:231], v[136:137] op_sel_hi:[1,0,1] neg_lo:[0,1,0] neg_hi:[0,1,0]
	ds_read_b128 v[58:61], v233 offset:384
	s_waitcnt lgkmcnt(14)
	v_pk_fma_f32 v[138:139], v[62:63], v[230:231], v[138:139] op_sel_hi:[1,0,1] neg_lo:[0,1,0] neg_hi:[0,1,0]
	v_pk_fma_f32 v[140:141], v[64:65], v[230:231], v[140:141] op_sel_hi:[1,0,1] neg_lo:[0,1,0] neg_hi:[0,1,0]
	ds_read_b128 v[62:65], v233 offset:400
	v_pk_fma_f32 v[142:143], v[66:67], v[230:231], v[142:143] op_sel_hi:[1,0,1] neg_lo:[0,1,0] neg_hi:[0,1,0]
	v_pk_fma_f32 v[144:145], v[68:69], v[230:231], v[144:145] op_sel_hi:[1,0,1] neg_lo:[0,1,0] neg_hi:[0,1,0]
	ds_read_b128 v[66:69], v233 offset:416
	s_waitcnt lgkmcnt(14)
	v_pk_fma_f32 v[146:147], v[70:71], v[230:231], v[146:147] op_sel_hi:[1,0,1] neg_lo:[0,1,0] neg_hi:[0,1,0]
	v_pk_fma_f32 v[148:149], v[72:73], v[230:231], v[148:149] op_sel_hi:[1,0,1] neg_lo:[0,1,0] neg_hi:[0,1,0]
	ds_read_b128 v[70:73], v233 offset:432
	v_pk_fma_f32 v[150:151], v[194:195], v[230:231], v[150:151] op_sel_hi:[1,0,1] neg_lo:[0,1,0] neg_hi:[0,1,0]
	v_pk_fma_f32 v[152:153], v[196:197], v[230:231], v[152:153] op_sel_hi:[1,0,1] neg_lo:[0,1,0] neg_hi:[0,1,0]
	ds_read_b128 v[194:197], v233 offset:448
	s_waitcnt lgkmcnt(14)
	v_pk_fma_f32 v[154:155], v[198:199], v[230:231], v[154:155] op_sel_hi:[1,0,1] neg_lo:[0,1,0] neg_hi:[0,1,0]
	v_pk_fma_f32 v[180:181], v[200:201], v[230:231], v[180:181] op_sel_hi:[1,0,1] neg_lo:[0,1,0] neg_hi:[0,1,0]
	ds_read_b128 v[198:201], v233 offset:464
	v_pk_fma_f32 v[182:183], v[202:203], v[230:231], v[182:183] op_sel_hi:[1,0,1] neg_lo:[0,1,0] neg_hi:[0,1,0]
	v_pk_fma_f32 v[184:185], v[204:205], v[230:231], v[184:185] op_sel_hi:[1,0,1] neg_lo:[0,1,0] neg_hi:[0,1,0]
	ds_read_b128 v[202:205], v233 offset:480
	s_waitcnt lgkmcnt(14)
	v_pk_fma_f32 v[186:187], v[206:207], v[230:231], v[186:187] op_sel_hi:[1,0,1] neg_lo:[0,1,0] neg_hi:[0,1,0]
	v_pk_fma_f32 v[188:189], v[208:209], v[230:231], v[188:189] op_sel_hi:[1,0,1] neg_lo:[0,1,0] neg_hi:[0,1,0]
	ds_read_b128 v[206:209], v233 offset:496
	v_pk_fma_f32 v[190:191], v[226:227], v[230:231], v[190:191] op_sel_hi:[1,0,1] neg_lo:[0,1,0] neg_hi:[0,1,0]
	v_pk_fma_f32 v[192:193], v[228:229], v[230:231], v[192:193] op_sel_hi:[1,0,1] neg_lo:[0,1,0] neg_hi:[0,1,0]
	ds_read_b128 v[226:229], v233 offset:512
	v_mov_b32_e32 v230, v107
	v_cvt_pk_bf16_f32 v232, v230, v230
	global_store_short v28, v232, s[0:1]
	s_add_u32 s0, s0, 0x400
	s_addc_u32 s1, s1, 0
	s_waitcnt lgkmcnt(14)
	v_pk_fma_f32 v[108:109], v[32:33], v[230:231], v[108:109] op_sel_hi:[1,0,1] neg_lo:[0,1,0] neg_hi:[0,1,0]
	ds_read_b128 v[30:33], v233 offset:544
	v_pk_fma_f32 v[110:111], v[34:35], v[230:231], v[110:111] op_sel_hi:[1,0,1] neg_lo:[0,1,0] neg_hi:[0,1,0]
	v_pk_fma_f32 v[112:113], v[36:37], v[230:231], v[112:113] op_sel_hi:[1,0,1] neg_lo:[0,1,0] neg_hi:[0,1,0]
	ds_read_b128 v[34:37], v233 offset:560
	s_waitcnt lgkmcnt(14)
	v_pk_fma_f32 v[114:115], v[38:39], v[230:231], v[114:115] op_sel_hi:[1,0,1] neg_lo:[0,1,0] neg_hi:[0,1,0]
	v_pk_fma_f32 v[116:117], v[40:41], v[230:231], v[116:117] op_sel_hi:[1,0,1] neg_lo:[0,1,0] neg_hi:[0,1,0]
	ds_read_b128 v[38:41], v233 offset:576
	v_pk_fma_f32 v[118:119], v[42:43], v[230:231], v[118:119] op_sel_hi:[1,0,1] neg_lo:[0,1,0] neg_hi:[0,1,0]
	v_pk_fma_f32 v[120:121], v[44:45], v[230:231], v[120:121] op_sel_hi:[1,0,1] neg_lo:[0,1,0] neg_hi:[0,1,0]
	ds_read_b128 v[42:45], v233 offset:592
	s_waitcnt lgkmcnt(14)
	v_pk_fma_f32 v[122:123], v[46:47], v[230:231], v[122:123] op_sel_hi:[1,0,1] neg_lo:[0,1,0] neg_hi:[0,1,0]
	v_pk_fma_f32 v[124:125], v[48:49], v[230:231], v[124:125] op_sel_hi:[1,0,1] neg_lo:[0,1,0] neg_hi:[0,1,0]
	ds_read_b128 v[46:49], v233 offset:608
	v_pk_fma_f32 v[126:127], v[50:51], v[230:231], v[126:127] op_sel_hi:[1,0,1] neg_lo:[0,1,0] neg_hi:[0,1,0]
	v_pk_fma_f32 v[128:129], v[52:53], v[230:231], v[128:129] op_sel_hi:[1,0,1] neg_lo:[0,1,0] neg_hi:[0,1,0]
	ds_read_b128 v[50:53], v233 offset:624
	s_waitcnt lgkmcnt(14)
	v_pk_fma_f32 v[130:131], v[54:55], v[230:231], v[130:131] op_sel_hi:[1,0,1] neg_lo:[0,1,0] neg_hi:[0,1,0]
	v_pk_fma_f32 v[132:133], v[56:57], v[230:231], v[132:133] op_sel_hi:[1,0,1] neg_lo:[0,1,0] neg_hi:[0,1,0]
	ds_read_b128 v[54:57], v233 offset:640
	v_pk_fma_f32 v[134:135], v[58:59], v[230:231], v[134:135] op_sel_hi:[1,0,1] neg_lo:[0,1,0] neg_hi:[0,1,0]
	v_pk_fma_f32 v[136:137], v[60:61], v[230:231], v[136:137] op_sel_hi:[1,0,1] neg_lo:[0,1,0] neg_hi:[0,1,0]
	ds_read_b128 v[58:61], v233 offset:656
	s_waitcnt lgkmcnt(14)
	v_pk_fma_f32 v[138:139], v[62:63], v[230:231], v[138:139] op_sel_hi:[1,0,1] neg_lo:[0,1,0] neg_hi:[0,1,0]
	v_pk_fma_f32 v[140:141], v[64:65], v[230:231], v[140:141] op_sel_hi:[1,0,1] neg_lo:[0,1,0] neg_hi:[0,1,0]
	ds_read_b128 v[62:65], v233 offset:672
	v_pk_fma_f32 v[142:143], v[66:67], v[230:231], v[142:143] op_sel_hi:[1,0,1] neg_lo:[0,1,0] neg_hi:[0,1,0]
	v_pk_fma_f32 v[144:145], v[68:69], v[230:231], v[144:145] op_sel_hi:[1,0,1] neg_lo:[0,1,0] neg_hi:[0,1,0]
	ds_read_b128 v[66:69], v233 offset:688
	s_waitcnt lgkmcnt(14)
	v_pk_fma_f32 v[146:147], v[70:71], v[230:231], v[146:147] op_sel_hi:[1,0,1] neg_lo:[0,1,0] neg_hi:[0,1,0]
	v_pk_fma_f32 v[148:149], v[72:73], v[230:231], v[148:149] op_sel_hi:[1,0,1] neg_lo:[0,1,0] neg_hi:[0,1,0]
	ds_read_b128 v[70:73], v233 offset:704
	v_pk_fma_f32 v[150:151], v[194:195], v[230:231], v[150:151] op_sel_hi:[1,0,1] neg_lo:[0,1,0] neg_hi:[0,1,0]
	v_pk_fma_f32 v[152:153], v[196:197], v[230:231], v[152:153] op_sel_hi:[1,0,1] neg_lo:[0,1,0] neg_hi:[0,1,0]
	ds_read_b128 v[194:197], v233 offset:720
	s_waitcnt lgkmcnt(14)
	v_pk_fma_f32 v[154:155], v[198:199], v[230:231], v[154:155] op_sel_hi:[1,0,1] neg_lo:[0,1,0] neg_hi:[0,1,0]
	v_pk_fma_f32 v[180:181], v[200:201], v[230:231], v[180:181] op_sel_hi:[1,0,1] neg_lo:[0,1,0] neg_hi:[0,1,0]
	ds_read_b128 v[198:201], v233 offset:736
	v_pk_fma_f32 v[182:183], v[202:203], v[230:231], v[182:183] op_sel_hi:[1,0,1] neg_lo:[0,1,0] neg_hi:[0,1,0]
	v_pk_fma_f32 v[184:185], v[204:205], v[230:231], v[184:185] op_sel_hi:[1,0,1] neg_lo:[0,1,0] neg_hi:[0,1,0]
	ds_read_b128 v[202:205], v233 offset:752
	s_waitcnt lgkmcnt(14)
	v_pk_fma_f32 v[186:187], v[206:207], v[230:231], v[186:187] op_sel_hi:[1,0,1] neg_lo:[0,1,0] neg_hi:[0,1,0]
	v_pk_fma_f32 v[188:189], v[208:209], v[230:231], v[188:189] op_sel_hi:[1,0,1] neg_lo:[0,1,0] neg_hi:[0,1,0]
	ds_read_b128 v[206:209], v233 offset:768
	v_pk_fma_f32 v[190:191], v[226:227], v[230:231], v[190:191] op_sel_hi:[1,0,1] neg_lo:[0,1,0] neg_hi:[0,1,0]
	v_pk_fma_f32 v[192:193], v[228:229], v[230:231], v[192:193] op_sel_hi:[1,0,1] neg_lo:[0,1,0] neg_hi:[0,1,0]
	ds_read_b128 v[226:229], v233 offset:784
	v_mov_b32_e32 v230, v108
	v_cvt_pk_bf16_f32 v232, v230, v230
	global_store_short v28, v232, s[0:1]
	s_add_u32 s0, s0, 0x400
	s_addc_u32 s1, s1, 0
	s_waitcnt lgkmcnt(14)
	v_pk_fma_f32 v[108:109], v[32:33], v[230:231], v[108:109] op_sel_hi:[1,0,1] neg_lo:[0,1,0] neg_hi:[0,1,0]
	v_pk_fma_f32 v[110:111], v[34:35], v[230:231], v[110:111] op_sel_hi:[1,0,1] neg_lo:[0,1,0] neg_hi:[0,1,0]
	v_pk_fma_f32 v[112:113], v[36:37], v[230:231], v[112:113] op_sel_hi:[1,0,1] neg_lo:[0,1,0] neg_hi:[0,1,0]
	ds_read_b128 v[34:37], v233 offset:832
	s_waitcnt lgkmcnt(13)
	v_pk_fma_f32 v[114:115], v[38:39], v[230:231], v[114:115] op_sel_hi:[1,0,1] neg_lo:[0,1,0] neg_hi:[0,1,0]
	v_pk_fma_f32 v[116:117], v[40:41], v[230:231], v[116:117] op_sel_hi:[1,0,1] neg_lo:[0,1,0] neg_hi:[0,1,0]
	ds_read_b128 v[38:41], v233 offset:848
	v_pk_fma_f32 v[118:119], v[42:43], v[230:231], v[118:119] op_sel_hi:[1,0,1] neg_lo:[0,1,0] neg_hi:[0,1,0]
	v_pk_fma_f32 v[120:121], v[44:45], v[230:231], v[120:121] op_sel_hi:[1,0,1] neg_lo:[0,1,0] neg_hi:[0,1,0]
	ds_read_b128 v[42:45], v233 offset:864
	s_waitcnt lgkmcnt(13)
	v_pk_fma_f32 v[122:123], v[46:47], v[230:231], v[122:123] op_sel_hi:[1,0,1] neg_lo:[0,1,0] neg_hi:[0,1,0]
	v_pk_fma_f32 v[124:125], v[48:49], v[230:231], v[124:125] op_sel_hi:[1,0,1] neg_lo:[0,1,0] neg_hi:[0,1,0]
	ds_read_b128 v[46:49], v233 offset:880
	v_pk_fma_f32 v[126:127], v[50:51], v[230:231], v[126:127] op_sel_hi:[1,0,1] neg_lo:[0,1,0] neg_hi:[0,1,0]
	v_pk_fma_f32 v[128:129], v[52:53], v[230:231], v[128:129] op_sel_hi:[1,0,1] neg_lo:[0,1,0] neg_hi:[0,1,0]
	ds_read_b128 v[50:53], v233 offset:896
	s_waitcnt lgkmcnt(13)
	v_pk_fma_f32 v[130:131], v[54:55], v[230:231], v[130:131] op_sel_hi:[1,0,1] neg_lo:[0,1,0] neg_hi:[0,1,0]
	v_pk_fma_f32 v[132:133], v[56:57], v[230:231], v[132:133] op_sel_hi:[1,0,1] neg_lo:[0,1,0] neg_hi:[0,1,0]
	ds_read_b128 v[54:57], v233 offset:912
	v_pk_fma_f32 v[134:135], v[58:59], v[230:231], v[134:135] op_sel_hi:[1,0,1] neg_lo:[0,1,0] neg_hi:[0,1,0]
	v_pk_fma_f32 v[136:137], v[60:61], v[230:231], v[136:137] op_sel_hi:[1,0,1] neg_lo:[0,1,0] neg_hi:[0,1,0]
	ds_read_b128 v[58:61], v233 offset:928
	s_waitcnt lgkmcnt(13)
	v_pk_fma_f32 v[138:139], v[62:63], v[230:231], v[138:139] op_sel_hi:[1,0,1] neg_lo:[0,1,0] neg_hi:[0,1,0]
	v_pk_fma_f32 v[140:141], v[64:65], v[230:231], v[140:141] op_sel_hi:[1,0,1] neg_lo:[0,1,0] neg_hi:[0,1,0]
	ds_read_b128 v[62:65], v233 offset:944
	v_pk_fma_f32 v[142:143], v[66:67], v[230:231], v[142:143] op_sel_hi:[1,0,1] neg_lo:[0,1,0] neg_hi:[0,1,0]
	v_pk_fma_f32 v[144:145], v[68:69], v[230:231], v[144:145] op_sel_hi:[1,0,1] neg_lo:[0,1,0] neg_hi:[0,1,0]
	ds_read_b128 v[66:69], v233 offset:960
	s_waitcnt lgkmcnt(13)
	v_pk_fma_f32 v[146:147], v[70:71], v[230:231], v[146:147] op_sel_hi:[1,0,1] neg_lo:[0,1,0] neg_hi:[0,1,0]
	v_pk_fma_f32 v[148:149], v[72:73], v[230:231], v[148:149] op_sel_hi:[1,0,1] neg_lo:[0,1,0] neg_hi:[0,1,0]
	ds_read_b128 v[70:73], v233 offset:976
	v_pk_fma_f32 v[150:151], v[194:195], v[230:231], v[150:151] op_sel_hi:[1,0,1] neg_lo:[0,1,0] neg_hi:[0,1,0]
	v_pk_fma_f32 v[152:153], v[196:197], v[230:231], v[152:153] op_sel_hi:[1,0,1] neg_lo:[0,1,0] neg_hi:[0,1,0]
	ds_read_b128 v[194:197], v233 offset:992
	s_waitcnt lgkmcnt(13)
	v_pk_fma_f32 v[154:155], v[198:199], v[230:231], v[154:155] op_sel_hi:[1,0,1] neg_lo:[0,1,0] neg_hi:[0,1,0]
	v_pk_fma_f32 v[180:181], v[200:201], v[230:231], v[180:181] op_sel_hi:[1,0,1] neg_lo:[0,1,0] neg_hi:[0,1,0]
	ds_read_b128 v[198:201], v233 offset:1008
	v_pk_fma_f32 v[182:183], v[202:203], v[230:231], v[182:183] op_sel_hi:[1,0,1] neg_lo:[0,1,0] neg_hi:[0,1,0]
	v_pk_fma_f32 v[184:185], v[204:205], v[230:231], v[184:185] op_sel_hi:[1,0,1] neg_lo:[0,1,0] neg_hi:[0,1,0]
	ds_read_b128 v[202:205], v233 offset:1024
	s_waitcnt lgkmcnt(13)
	v_pk_fma_f32 v[186:187], v[206:207], v[230:231], v[186:187] op_sel_hi:[1,0,1] neg_lo:[0,1,0] neg_hi:[0,1,0]
	v_pk_fma_f32 v[188:189], v[208:209], v[230:231], v[188:189] op_sel_hi:[1,0,1] neg_lo:[0,1,0] neg_hi:[0,1,0]
	ds_read_b128 v[206:209], v233 offset:1040
	v_pk_fma_f32 v[190:191], v[226:227], v[230:231], v[190:191] op_sel_hi:[1,0,1] neg_lo:[0,1,0] neg_hi:[0,1,0]
	v_pk_fma_f32 v[192:193], v[228:229], v[230:231], v[192:193] op_sel_hi:[1,0,1] neg_lo:[0,1,0] neg_hi:[0,1,0]
	ds_read_b128 v[226:229], v233 offset:1056
	v_mov_b32_e32 v230, v109
	v_cvt_pk_bf16_f32 v232, v230, v230
	global_store_short v28, v232, s[0:1]
	s_add_u32 s0, s0, 0x400
	s_addc_u32 s1, s1, 0
	s_waitcnt lgkmcnt(13)
	v_pk_fma_f32 v[110:111], v[34:35], v[230:231], v[110:111] op_sel_hi:[1,0,1] neg_lo:[0,1,0] neg_hi:[0,1,0]
	v_pk_fma_f32 v[112:113], v[36:37], v[230:231], v[112:113] op_sel_hi:[1,0,1] neg_lo:[0,1,0] neg_hi:[0,1,0]
	ds_read_b128 v[34:37], v233 offset:1104
	v_pk_fma_f32 v[114:115], v[38:39], v[230:231], v[114:115] op_sel_hi:[1,0,1] neg_lo:[0,1,0] neg_hi:[0,1,0]
	v_pk_fma_f32 v[116:117], v[40:41], v[230:231], v[116:117] op_sel_hi:[1,0,1] neg_lo:[0,1,0] neg_hi:[0,1,0]
	ds_read_b128 v[38:41], v233 offset:1120
	s_waitcnt lgkmcnt(13)
	v_pk_fma_f32 v[118:119], v[42:43], v[230:231], v[118:119] op_sel_hi:[1,0,1] neg_lo:[0,1,0] neg_hi:[0,1,0]
	v_pk_fma_f32 v[120:121], v[44:45], v[230:231], v[120:121] op_sel_hi:[1,0,1] neg_lo:[0,1,0] neg_hi:[0,1,0]
	ds_read_b128 v[42:45], v233 offset:1136
	v_pk_fma_f32 v[122:123], v[46:47], v[230:231], v[122:123] op_sel_hi:[1,0,1] neg_lo:[0,1,0] neg_hi:[0,1,0]
	v_pk_fma_f32 v[124:125], v[48:49], v[230:231], v[124:125] op_sel_hi:[1,0,1] neg_lo:[0,1,0] neg_hi:[0,1,0]
	ds_read_b128 v[46:49], v233 offset:1152
	s_waitcnt lgkmcnt(13)
	v_pk_fma_f32 v[126:127], v[50:51], v[230:231], v[126:127] op_sel_hi:[1,0,1] neg_lo:[0,1,0] neg_hi:[0,1,0]
	v_pk_fma_f32 v[128:129], v[52:53], v[230:231], v[128:129] op_sel_hi:[1,0,1] neg_lo:[0,1,0] neg_hi:[0,1,0]
	ds_read_b128 v[50:53], v233 offset:1168
	v_pk_fma_f32 v[130:131], v[54:55], v[230:231], v[130:131] op_sel_hi:[1,0,1] neg_lo:[0,1,0] neg_hi:[0,1,0]
	v_pk_fma_f32 v[132:133], v[56:57], v[230:231], v[132:133] op_sel_hi:[1,0,1] neg_lo:[0,1,0] neg_hi:[0,1,0]
	ds_read_b128 v[54:57], v233 offset:1184
	s_waitcnt lgkmcnt(13)
	v_pk_fma_f32 v[134:135], v[58:59], v[230:231], v[134:135] op_sel_hi:[1,0,1] neg_lo:[0,1,0] neg_hi:[0,1,0]
	v_pk_fma_f32 v[136:137], v[60:61], v[230:231], v[136:137] op_sel_hi:[1,0,1] neg_lo:[0,1,0] neg_hi:[0,1,0]
	ds_read_b128 v[58:61], v233 offset:1200
	v_pk_fma_f32 v[138:139], v[62:63], v[230:231], v[138:139] op_sel_hi:[1,0,1] neg_lo:[0,1,0] neg_hi:[0,1,0]
	v_pk_fma_f32 v[140:141], v[64:65], v[230:231], v[140:141] op_sel_hi:[1,0,1] neg_lo:[0,1,0] neg_hi:[0,1,0]
	ds_read_b128 v[62:65], v233 offset:1216
	s_waitcnt lgkmcnt(13)
	v_pk_fma_f32 v[142:143], v[66:67], v[230:231], v[142:143] op_sel_hi:[1,0,1] neg_lo:[0,1,0] neg_hi:[0,1,0]
	v_pk_fma_f32 v[144:145], v[68:69], v[230:231], v[144:145] op_sel_hi:[1,0,1] neg_lo:[0,1,0] neg_hi:[0,1,0]
	ds_read_b128 v[66:69], v233 offset:1232
	v_pk_fma_f32 v[146:147], v[70:71], v[230:231], v[146:147] op_sel_hi:[1,0,1] neg_lo:[0,1,0] neg_hi:[0,1,0]
	v_pk_fma_f32 v[148:149], v[72:73], v[230:231], v[148:149] op_sel_hi:[1,0,1] neg_lo:[0,1,0] neg_hi:[0,1,0]
	ds_read_b128 v[70:73], v233 offset:1248
	s_waitcnt lgkmcnt(13)
	v_pk_fma_f32 v[150:151], v[194:195], v[230:231], v[150:151] op_sel_hi:[1,0,1] neg_lo:[0,1,0] neg_hi:[0,1,0]
	v_pk_fma_f32 v[152:153], v[196:197], v[230:231], v[152:153] op_sel_hi:[1,0,1] neg_lo:[0,1,0] neg_hi:[0,1,0]
	ds_read_b128 v[194:197], v233 offset:1264
	v_pk_fma_f32 v[154:155], v[198:199], v[230:231], v[154:155] op_sel_hi:[1,0,1] neg_lo:[0,1,0] neg_hi:[0,1,0]
	v_pk_fma_f32 v[180:181], v[200:201], v[230:231], v[180:181] op_sel_hi:[1,0,1] neg_lo:[0,1,0] neg_hi:[0,1,0]
	ds_read_b128 v[198:201], v233 offset:1280
	s_waitcnt lgkmcnt(13)
	v_pk_fma_f32 v[182:183], v[202:203], v[230:231], v[182:183] op_sel_hi:[1,0,1] neg_lo:[0,1,0] neg_hi:[0,1,0]
	v_pk_fma_f32 v[184:185], v[204:205], v[230:231], v[184:185] op_sel_hi:[1,0,1] neg_lo:[0,1,0] neg_hi:[0,1,0]
	ds_read_b128 v[202:205], v233 offset:1296
	v_pk_fma_f32 v[186:187], v[206:207], v[230:231], v[186:187] op_sel_hi:[1,0,1] neg_lo:[0,1,0] neg_hi:[0,1,0]
	v_pk_fma_f32 v[188:189], v[208:209], v[230:231], v[188:189] op_sel_hi:[1,0,1] neg_lo:[0,1,0] neg_hi:[0,1,0]
	ds_read_b128 v[206:209], v233 offset:1312
	s_waitcnt lgkmcnt(14)
	v_pk_fma_f32 v[190:191], v[226:227], v[230:231], v[190:191] op_sel_hi:[1,0,1] neg_lo:[0,1,0] neg_hi:[0,1,0]
	v_pk_fma_f32 v[192:193], v[228:229], v[230:231], v[192:193] op_sel_hi:[1,0,1] neg_lo:[0,1,0] neg_hi:[0,1,0]
	ds_read_b128 v[226:229], v233 offset:1328
	v_mov_b32_e32 v230, v110
	v_cvt_pk_bf16_f32 v232, v230, v230
	global_store_short v28, v232, s[0:1]
	s_add_u32 s0, s0, 0x400
	s_addc_u32 s1, s1, 0
	s_waitcnt lgkmcnt(13)
	v_pk_fma_f32 v[110:111], v[34:35], v[230:231], v[110:111] op_sel_hi:[1,0,1] neg_lo:[0,1,0] neg_hi:[0,1,0]
	v_pk_fma_f32 v[112:113], v[36:37], v[230:231], v[112:113] op_sel_hi:[1,0,1] neg_lo:[0,1,0] neg_hi:[0,1,0]
	ds_read_b128 v[34:37], v233 offset:1376
	v_pk_fma_f32 v[114:115], v[38:39], v[230:231], v[114:115] op_sel_hi:[1,0,1] neg_lo:[0,1,0] neg_hi:[0,1,0]
	v_pk_fma_f32 v[116:117], v[40:41], v[230:231], v[116:117] op_sel_hi:[1,0,1] neg_lo:[0,1,0] neg_hi:[0,1,0]
	ds_read_b128 v[38:41], v233 offset:1392
	s_waitcnt lgkmcnt(13)
	v_pk_fma_f32 v[118:119], v[42:43], v[230:231], v[118:119] op_sel_hi:[1,0,1] neg_lo:[0,1,0] neg_hi:[0,1,0]
	v_pk_fma_f32 v[120:121], v[44:45], v[230:231], v[120:121] op_sel_hi:[1,0,1] neg_lo:[0,1,0] neg_hi:[0,1,0]
	ds_read_b128 v[42:45], v233 offset:1408
	v_pk_fma_f32 v[122:123], v[46:47], v[230:231], v[122:123] op_sel_hi:[1,0,1] neg_lo:[0,1,0] neg_hi:[0,1,0]
	v_pk_fma_f32 v[124:125], v[48:49], v[230:231], v[124:125] op_sel_hi:[1,0,1] neg_lo:[0,1,0] neg_hi:[0,1,0]
	ds_read_b128 v[46:49], v233 offset:1424
	s_waitcnt lgkmcnt(13)
	v_pk_fma_f32 v[126:127], v[50:51], v[230:231], v[126:127] op_sel_hi:[1,0,1] neg_lo:[0,1,0] neg_hi:[0,1,0]
	v_pk_fma_f32 v[128:129], v[52:53], v[230:231], v[128:129] op_sel_hi:[1,0,1] neg_lo:[0,1,0] neg_hi:[0,1,0]
	ds_read_b128 v[50:53], v233 offset:1440
	v_pk_fma_f32 v[130:131], v[54:55], v[230:231], v[130:131] op_sel_hi:[1,0,1] neg_lo:[0,1,0] neg_hi:[0,1,0]
	v_pk_fma_f32 v[132:133], v[56:57], v[230:231], v[132:133] op_sel_hi:[1,0,1] neg_lo:[0,1,0] neg_hi:[0,1,0]
	ds_read_b128 v[54:57], v233 offset:1456
	s_waitcnt lgkmcnt(13)
	v_pk_fma_f32 v[134:135], v[58:59], v[230:231], v[134:135] op_sel_hi:[1,0,1] neg_lo:[0,1,0] neg_hi:[0,1,0]
	v_pk_fma_f32 v[136:137], v[60:61], v[230:231], v[136:137] op_sel_hi:[1,0,1] neg_lo:[0,1,0] neg_hi:[0,1,0]
	ds_read_b128 v[58:61], v233 offset:1472
	v_pk_fma_f32 v[138:139], v[62:63], v[230:231], v[138:139] op_sel_hi:[1,0,1] neg_lo:[0,1,0] neg_hi:[0,1,0]
	v_pk_fma_f32 v[140:141], v[64:65], v[230:231], v[140:141] op_sel_hi:[1,0,1] neg_lo:[0,1,0] neg_hi:[0,1,0]
	ds_read_b128 v[62:65], v233 offset:1488
	s_waitcnt lgkmcnt(13)
	v_pk_fma_f32 v[142:143], v[66:67], v[230:231], v[142:143] op_sel_hi:[1,0,1] neg_lo:[0,1,0] neg_hi:[0,1,0]
	v_pk_fma_f32 v[144:145], v[68:69], v[230:231], v[144:145] op_sel_hi:[1,0,1] neg_lo:[0,1,0] neg_hi:[0,1,0]
	ds_read_b128 v[66:69], v233 offset:1504
	v_pk_fma_f32 v[146:147], v[70:71], v[230:231], v[146:147] op_sel_hi:[1,0,1] neg_lo:[0,1,0] neg_hi:[0,1,0]
	v_pk_fma_f32 v[148:149], v[72:73], v[230:231], v[148:149] op_sel_hi:[1,0,1] neg_lo:[0,1,0] neg_hi:[0,1,0]
	ds_read_b128 v[70:73], v233 offset:1520
	s_waitcnt lgkmcnt(13)
	v_pk_fma_f32 v[150:151], v[194:195], v[230:231], v[150:151] op_sel_hi:[1,0,1] neg_lo:[0,1,0] neg_hi:[0,1,0]
	v_pk_fma_f32 v[152:153], v[196:197], v[230:231], v[152:153] op_sel_hi:[1,0,1] neg_lo:[0,1,0] neg_hi:[0,1,0]
	ds_read_b128 v[194:197], v233 offset:1536
	v_pk_fma_f32 v[154:155], v[198:199], v[230:231], v[154:155] op_sel_hi:[1,0,1] neg_lo:[0,1,0] neg_hi:[0,1,0]
	v_pk_fma_f32 v[180:181], v[200:201], v[230:231], v[180:181] op_sel_hi:[1,0,1] neg_lo:[0,1,0] neg_hi:[0,1,0]
	ds_read_b128 v[198:201], v233 offset:1552
	s_waitcnt lgkmcnt(13)
	v_pk_fma_f32 v[182:183], v[202:203], v[230:231], v[182:183] op_sel_hi:[1,0,1] neg_lo:[0,1,0] neg_hi:[0,1,0]
	v_pk_fma_f32 v[184:185], v[204:205], v[230:231], v[184:185] op_sel_hi:[1,0,1] neg_lo:[0,1,0] neg_hi:[0,1,0]
	ds_read_b128 v[202:205], v233 offset:1568
	v_pk_fma_f32 v[186:187], v[206:207], v[230:231], v[186:187] op_sel_hi:[1,0,1] neg_lo:[0,1,0] neg_hi:[0,1,0]
	v_pk_fma_f32 v[188:189], v[208:209], v[230:231], v[188:189] op_sel_hi:[1,0,1] neg_lo:[0,1,0] neg_hi:[0,1,0]
	ds_read_b128 v[206:209], v233 offset:1584
	s_waitcnt lgkmcnt(14)
	v_pk_fma_f32 v[190:191], v[226:227], v[230:231], v[190:191] op_sel_hi:[1,0,1] neg_lo:[0,1,0] neg_hi:[0,1,0]
	v_pk_fma_f32 v[192:193], v[228:229], v[230:231], v[192:193] op_sel_hi:[1,0,1] neg_lo:[0,1,0] neg_hi:[0,1,0]
	ds_read_b128 v[226:229], v233 offset:1600
	v_mov_b32_e32 v230, v111
	v_cvt_pk_bf16_f32 v232, v230, v230
	global_store_short v28, v232, s[0:1]
	s_add_u32 s0, s0, 0x400
	s_addc_u32 s1, s1, 0
	s_waitcnt lgkmcnt(13)
	v_pk_fma_f32 v[112:113], v[36:37], v[230:231], v[112:113] op_sel_hi:[1,0,1] neg_lo:[0,1,0] neg_hi:[0,1,0]
	ds_read_b128 v[34:37], v233 offset:1648
	v_pk_fma_f32 v[114:115], v[38:39], v[230:231], v[114:115] op_sel_hi:[1,0,1] neg_lo:[0,1,0] neg_hi:[0,1,0]
	v_pk_fma_f32 v[116:117], v[40:41], v[230:231], v[116:117] op_sel_hi:[1,0,1] neg_lo:[0,1,0] neg_hi:[0,1,0]
	ds_read_b128 v[38:41], v233 offset:1664
	s_waitcnt lgkmcnt(13)
	v_pk_fma_f32 v[118:119], v[42:43], v[230:231], v[118:119] op_sel_hi:[1,0,1] neg_lo:[0,1,0] neg_hi:[0,1,0]
	v_pk_fma_f32 v[120:121], v[44:45], v[230:231], v[120:121] op_sel_hi:[1,0,1] neg_lo:[0,1,0] neg_hi:[0,1,0]
	ds_read_b128 v[42:45], v233 offset:1680
	v_pk_fma_f32 v[122:123], v[46:47], v[230:231], v[122:123] op_sel_hi:[1,0,1] neg_lo:[0,1,0] neg_hi:[0,1,0]
	v_pk_fma_f32 v[124:125], v[48:49], v[230:231], v[124:125] op_sel_hi:[1,0,1] neg_lo:[0,1,0] neg_hi:[0,1,0]
	ds_read_b128 v[46:49], v233 offset:1696
	s_waitcnt lgkmcnt(13)
	v_pk_fma_f32 v[126:127], v[50:51], v[230:231], v[126:127] op_sel_hi:[1,0,1] neg_lo:[0,1,0] neg_hi:[0,1,0]
	v_pk_fma_f32 v[128:129], v[52:53], v[230:231], v[128:129] op_sel_hi:[1,0,1] neg_lo:[0,1,0] neg_hi:[0,1,0]
	ds_read_b128 v[50:53], v233 offset:1712
	v_pk_fma_f32 v[130:131], v[54:55], v[230:231], v[130:131] op_sel_hi:[1,0,1] neg_lo:[0,1,0] neg_hi:[0,1,0]
	v_pk_fma_f32 v[132:133], v[56:57], v[230:231], v[132:133] op_sel_hi:[1,0,1] neg_lo:[0,1,0] neg_hi:[0,1,0]
	ds_read_b128 v[54:57], v233 offset:1728
	s_waitcnt lgkmcnt(13)
	v_pk_fma_f32 v[134:135], v[58:59], v[230:231], v[134:135] op_sel_hi:[1,0,1] neg_lo:[0,1,0] neg_hi:[0,1,0]
	v_pk_fma_f32 v[136:137], v[60:61], v[230:231], v[136:137] op_sel_hi:[1,0,1] neg_lo:[0,1,0] neg_hi:[0,1,0]
	ds_read_b128 v[58:61], v233 offset:1744
	v_pk_fma_f32 v[138:139], v[62:63], v[230:231], v[138:139] op_sel_hi:[1,0,1] neg_lo:[0,1,0] neg_hi:[0,1,0]
	v_pk_fma_f32 v[140:141], v[64:65], v[230:231], v[140:141] op_sel_hi:[1,0,1] neg_lo:[0,1,0] neg_hi:[0,1,0]
	ds_read_b128 v[62:65], v233 offset:1760
	s_waitcnt lgkmcnt(13)
	v_pk_fma_f32 v[142:143], v[66:67], v[230:231], v[142:143] op_sel_hi:[1,0,1] neg_lo:[0,1,0] neg_hi:[0,1,0]
	v_pk_fma_f32 v[144:145], v[68:69], v[230:231], v[144:145] op_sel_hi:[1,0,1] neg_lo:[0,1,0] neg_hi:[0,1,0]
	ds_read_b128 v[66:69], v233 offset:1776
	v_pk_fma_f32 v[146:147], v[70:71], v[230:231], v[146:147] op_sel_hi:[1,0,1] neg_lo:[0,1,0] neg_hi:[0,1,0]
	v_pk_fma_f32 v[148:149], v[72:73], v[230:231], v[148:149] op_sel_hi:[1,0,1] neg_lo:[0,1,0] neg_hi:[0,1,0]
	ds_read_b128 v[70:73], v233 offset:1792
	s_waitcnt lgkmcnt(13)
	v_pk_fma_f32 v[150:151], v[194:195], v[230:231], v[150:151] op_sel_hi:[1,0,1] neg_lo:[0,1,0] neg_hi:[0,1,0]
	v_pk_fma_f32 v[152:153], v[196:197], v[230:231], v[152:153] op_sel_hi:[1,0,1] neg_lo:[0,1,0] neg_hi:[0,1,0]
	ds_read_b128 v[194:197], v233 offset:1808
	v_pk_fma_f32 v[154:155], v[198:199], v[230:231], v[154:155] op_sel_hi:[1,0,1] neg_lo:[0,1,0] neg_hi:[0,1,0]
	v_pk_fma_f32 v[180:181], v[200:201], v[230:231], v[180:181] op_sel_hi:[1,0,1] neg_lo:[0,1,0] neg_hi:[0,1,0]
	ds_read_b128 v[198:201], v233 offset:1824
	s_waitcnt lgkmcnt(13)
	v_pk_fma_f32 v[182:183], v[202:203], v[230:231], v[182:183] op_sel_hi:[1,0,1] neg_lo:[0,1,0] neg_hi:[0,1,0]
	v_pk_fma_f32 v[184:185], v[204:205], v[230:231], v[184:185] op_sel_hi:[1,0,1] neg_lo:[0,1,0] neg_hi:[0,1,0]
	ds_read_b128 v[202:205], v233 offset:1840
	v_pk_fma_f32 v[186:187], v[206:207], v[230:231], v[186:187] op_sel_hi:[1,0,1] neg_lo:[0,1,0] neg_hi:[0,1,0]
	v_pk_fma_f32 v[188:189], v[208:209], v[230:231], v[188:189] op_sel_hi:[1,0,1] neg_lo:[0,1,0] neg_hi:[0,1,0]
	ds_read_b128 v[206:209], v233 offset:1856
	s_waitcnt lgkmcnt(14)
	v_pk_fma_f32 v[190:191], v[226:227], v[230:231], v[190:191] op_sel_hi:[1,0,1] neg_lo:[0,1,0] neg_hi:[0,1,0]
	v_pk_fma_f32 v[192:193], v[228:229], v[230:231], v[192:193] op_sel_hi:[1,0,1] neg_lo:[0,1,0] neg_hi:[0,1,0]
	ds_read_b128 v[226:229], v233 offset:1872
	v_mov_b32_e32 v230, v112
	v_cvt_pk_bf16_f32 v232, v230, v230
	global_store_short v28, v232, s[0:1]
	s_add_u32 s0, s0, 0x400
	s_addc_u32 s1, s1, 0
	s_waitcnt lgkmcnt(13)
	v_pk_fma_f32 v[112:113], v[36:37], v[230:231], v[112:113] op_sel_hi:[1,0,1] neg_lo:[0,1,0] neg_hi:[0,1,0]
	v_pk_fma_f32 v[114:115], v[38:39], v[230:231], v[114:115] op_sel_hi:[1,0,1] neg_lo:[0,1,0] neg_hi:[0,1,0]
	v_pk_fma_f32 v[116:117], v[40:41], v[230:231], v[116:117] op_sel_hi:[1,0,1] neg_lo:[0,1,0] neg_hi:[0,1,0]
	ds_read_b128 v[38:41], v233 offset:1936
	s_waitcnt lgkmcnt(12)
	v_pk_fma_f32 v[118:119], v[42:43], v[230:231], v[118:119] op_sel_hi:[1,0,1] neg_lo:[0,1,0] neg_hi:[0,1,0]
	v_pk_fma_f32 v[120:121], v[44:45], v[230:231], v[120:121] op_sel_hi:[1,0,1] neg_lo:[0,1,0] neg_hi:[0,1,0]
	ds_read_b128 v[42:45], v233 offset:1952
	v_pk_fma_f32 v[122:123], v[46:47], v[230:231], v[122:123] op_sel_hi:[1,0,1] neg_lo:[0,1,0] neg_hi:[0,1,0]
	v_pk_fma_f32 v[124:125], v[48:49], v[230:231], v[124:125] op_sel_hi:[1,0,1] neg_lo:[0,1,0] neg_hi:[0,1,0]
	ds_read_b128 v[46:49], v233 offset:1968
	s_waitcnt lgkmcnt(12)
	v_pk_fma_f32 v[126:127], v[50:51], v[230:231], v[126:127] op_sel_hi:[1,0,1] neg_lo:[0,1,0] neg_hi:[0,1,0]
	v_pk_fma_f32 v[128:129], v[52:53], v[230:231], v[128:129] op_sel_hi:[1,0,1] neg_lo:[0,1,0] neg_hi:[0,1,0]
	ds_read_b128 v[50:53], v233 offset:1984
	v_pk_fma_f32 v[130:131], v[54:55], v[230:231], v[130:131] op_sel_hi:[1,0,1] neg_lo:[0,1,0] neg_hi:[0,1,0]
	v_pk_fma_f32 v[132:133], v[56:57], v[230:231], v[132:133] op_sel_hi:[1,0,1] neg_lo:[0,1,0] neg_hi:[0,1,0]
	ds_read_b128 v[54:57], v233 offset:2000
	s_waitcnt lgkmcnt(12)
	v_pk_fma_f32 v[134:135], v[58:59], v[230:231], v[134:135] op_sel_hi:[1,0,1] neg_lo:[0,1,0] neg_hi:[0,1,0]
	v_pk_fma_f32 v[136:137], v[60:61], v[230:231], v[136:137] op_sel_hi:[1,0,1] neg_lo:[0,1,0] neg_hi:[0,1,0]
	ds_read_b128 v[58:61], v233 offset:2016
	v_pk_fma_f32 v[138:139], v[62:63], v[230:231], v[138:139] op_sel_hi:[1,0,1] neg_lo:[0,1,0] neg_hi:[0,1,0]
	v_pk_fma_f32 v[140:141], v[64:65], v[230:231], v[140:141] op_sel_hi:[1,0,1] neg_lo:[0,1,0] neg_hi:[0,1,0]
	ds_read_b128 v[62:65], v233 offset:2032
	s_waitcnt lgkmcnt(12)
	v_pk_fma_f32 v[142:143], v[66:67], v[230:231], v[142:143] op_sel_hi:[1,0,1] neg_lo:[0,1,0] neg_hi:[0,1,0]
	v_pk_fma_f32 v[144:145], v[68:69], v[230:231], v[144:145] op_sel_hi:[1,0,1] neg_lo:[0,1,0] neg_hi:[0,1,0]
	ds_read_b128 v[66:69], v233 offset:2048
	v_pk_fma_f32 v[146:147], v[70:71], v[230:231], v[146:147] op_sel_hi:[1,0,1] neg_lo:[0,1,0] neg_hi:[0,1,0]
	v_pk_fma_f32 v[148:149], v[72:73], v[230:231], v[148:149] op_sel_hi:[1,0,1] neg_lo:[0,1,0] neg_hi:[0,1,0]
	ds_read_b128 v[70:73], v233 offset:2064
	s_waitcnt lgkmcnt(12)
	v_pk_fma_f32 v[150:151], v[194:195], v[230:231], v[150:151] op_sel_hi:[1,0,1] neg_lo:[0,1,0] neg_hi:[0,1,0]
	v_pk_fma_f32 v[152:153], v[196:197], v[230:231], v[152:153] op_sel_hi:[1,0,1] neg_lo:[0,1,0] neg_hi:[0,1,0]
	ds_read_b128 v[194:197], v233 offset:2080
	v_pk_fma_f32 v[154:155], v[198:199], v[230:231], v[154:155] op_sel_hi:[1,0,1] neg_lo:[0,1,0] neg_hi:[0,1,0]
	v_pk_fma_f32 v[180:181], v[200:201], v[230:231], v[180:181] op_sel_hi:[1,0,1] neg_lo:[0,1,0] neg_hi:[0,1,0]
	ds_read_b128 v[198:201], v233 offset:2096
	s_waitcnt lgkmcnt(12)
	v_pk_fma_f32 v[182:183], v[202:203], v[230:231], v[182:183] op_sel_hi:[1,0,1] neg_lo:[0,1,0] neg_hi:[0,1,0]
	v_pk_fma_f32 v[184:185], v[204:205], v[230:231], v[184:185] op_sel_hi:[1,0,1] neg_lo:[0,1,0] neg_hi:[0,1,0]
	ds_read_b128 v[202:205], v233 offset:2112
	v_pk_fma_f32 v[186:187], v[206:207], v[230:231], v[186:187] op_sel_hi:[1,0,1] neg_lo:[0,1,0] neg_hi:[0,1,0]
	v_pk_fma_f32 v[188:189], v[208:209], v[230:231], v[188:189] op_sel_hi:[1,0,1] neg_lo:[0,1,0] neg_hi:[0,1,0]
	ds_read_b128 v[206:209], v233 offset:2128
	s_waitcnt lgkmcnt(13)
	v_pk_fma_f32 v[190:191], v[226:227], v[230:231], v[190:191] op_sel_hi:[1,0,1] neg_lo:[0,1,0] neg_hi:[0,1,0]
	v_pk_fma_f32 v[192:193], v[228:229], v[230:231], v[192:193] op_sel_hi:[1,0,1] neg_lo:[0,1,0] neg_hi:[0,1,0]
	ds_read_b128 v[226:229], v233 offset:2144
	v_mov_b32_e32 v230, v113
	v_cvt_pk_bf16_f32 v232, v230, v230
	global_store_short v28, v232, s[0:1]
	s_add_u32 s0, s0, 0x400
	s_addc_u32 s1, s1, 0
	s_waitcnt lgkmcnt(12)
	v_pk_fma_f32 v[114:115], v[38:39], v[230:231], v[114:115] op_sel_hi:[1,0,1] neg_lo:[0,1,0] neg_hi:[0,1,0]
	v_pk_fma_f32 v[116:117], v[40:41], v[230:231], v[116:117] op_sel_hi:[1,0,1] neg_lo:[0,1,0] neg_hi:[0,1,0]
	ds_read_b128 v[38:41], v233 offset:2208
	v_pk_fma_f32 v[118:119], v[42:43], v[230:231], v[118:119] op_sel_hi:[1,0,1] neg_lo:[0,1,0] neg_hi:[0,1,0]
	v_pk_fma_f32 v[120:121], v[44:45], v[230:231], v[120:121] op_sel_hi:[1,0,1] neg_lo:[0,1,0] neg_hi:[0,1,0]
	ds_read_b128 v[42:45], v233 offset:2224
	s_waitcnt lgkmcnt(12)
	v_pk_fma_f32 v[122:123], v[46:47], v[230:231], v[122:123] op_sel_hi:[1,0,1] neg_lo:[0,1,0] neg_hi:[0,1,0]
	v_pk_fma_f32 v[124:125], v[48:49], v[230:231], v[124:125] op_sel_hi:[1,0,1] neg_lo:[0,1,0] neg_hi:[0,1,0]
	ds_read_b128 v[46:49], v233 offset:2240
	v_pk_fma_f32 v[126:127], v[50:51], v[230:231], v[126:127] op_sel_hi:[1,0,1] neg_lo:[0,1,0] neg_hi:[0,1,0]
	v_pk_fma_f32 v[128:129], v[52:53], v[230:231], v[128:129] op_sel_hi:[1,0,1] neg_lo:[0,1,0] neg_hi:[0,1,0]
	ds_read_b128 v[50:53], v233 offset:2256
	s_waitcnt lgkmcnt(12)
	v_pk_fma_f32 v[130:131], v[54:55], v[230:231], v[130:131] op_sel_hi:[1,0,1] neg_lo:[0,1,0] neg_hi:[0,1,0]
	v_pk_fma_f32 v[132:133], v[56:57], v[230:231], v[132:133] op_sel_hi:[1,0,1] neg_lo:[0,1,0] neg_hi:[0,1,0]
	ds_read_b128 v[54:57], v233 offset:2272
	v_pk_fma_f32 v[134:135], v[58:59], v[230:231], v[134:135] op_sel_hi:[1,0,1] neg_lo:[0,1,0] neg_hi:[0,1,0]
	v_pk_fma_f32 v[136:137], v[60:61], v[230:231], v[136:137] op_sel_hi:[1,0,1] neg_lo:[0,1,0] neg_hi:[0,1,0]
	ds_read_b128 v[58:61], v233 offset:2288
	s_waitcnt lgkmcnt(12)
	v_pk_fma_f32 v[138:139], v[62:63], v[230:231], v[138:139] op_sel_hi:[1,0,1] neg_lo:[0,1,0] neg_hi:[0,1,0]
	v_pk_fma_f32 v[140:141], v[64:65], v[230:231], v[140:141] op_sel_hi:[1,0,1] neg_lo:[0,1,0] neg_hi:[0,1,0]
	ds_read_b128 v[62:65], v233 offset:2304
	v_pk_fma_f32 v[142:143], v[66:67], v[230:231], v[142:143] op_sel_hi:[1,0,1] neg_lo:[0,1,0] neg_hi:[0,1,0]
	v_pk_fma_f32 v[144:145], v[68:69], v[230:231], v[144:145] op_sel_hi:[1,0,1] neg_lo:[0,1,0] neg_hi:[0,1,0]
	ds_read_b128 v[66:69], v233 offset:2320
	s_waitcnt lgkmcnt(12)
	v_pk_fma_f32 v[146:147], v[70:71], v[230:231], v[146:147] op_sel_hi:[1,0,1] neg_lo:[0,1,0] neg_hi:[0,1,0]
	v_pk_fma_f32 v[148:149], v[72:73], v[230:231], v[148:149] op_sel_hi:[1,0,1] neg_lo:[0,1,0] neg_hi:[0,1,0]
	ds_read_b128 v[70:73], v233 offset:2336
	v_pk_fma_f32 v[150:151], v[194:195], v[230:231], v[150:151] op_sel_hi:[1,0,1] neg_lo:[0,1,0] neg_hi:[0,1,0]
	v_pk_fma_f32 v[152:153], v[196:197], v[230:231], v[152:153] op_sel_hi:[1,0,1] neg_lo:[0,1,0] neg_hi:[0,1,0]
	ds_read_b128 v[194:197], v233 offset:2352
	s_waitcnt lgkmcnt(12)
	v_pk_fma_f32 v[154:155], v[198:199], v[230:231], v[154:155] op_sel_hi:[1,0,1] neg_lo:[0,1,0] neg_hi:[0,1,0]
	v_pk_fma_f32 v[180:181], v[200:201], v[230:231], v[180:181] op_sel_hi:[1,0,1] neg_lo:[0,1,0] neg_hi:[0,1,0]
	ds_read_b128 v[198:201], v233 offset:2368
	v_pk_fma_f32 v[182:183], v[202:203], v[230:231], v[182:183] op_sel_hi:[1,0,1] neg_lo:[0,1,0] neg_hi:[0,1,0]
	v_pk_fma_f32 v[184:185], v[204:205], v[230:231], v[184:185] op_sel_hi:[1,0,1] neg_lo:[0,1,0] neg_hi:[0,1,0]
	ds_read_b128 v[202:205], v233 offset:2384
	s_waitcnt lgkmcnt(12)
	v_pk_fma_f32 v[186:187], v[206:207], v[230:231], v[186:187] op_sel_hi:[1,0,1] neg_lo:[0,1,0] neg_hi:[0,1,0]
	v_pk_fma_f32 v[188:189], v[208:209], v[230:231], v[188:189] op_sel_hi:[1,0,1] neg_lo:[0,1,0] neg_hi:[0,1,0]
	ds_read_b128 v[206:209], v233 offset:2400
	v_pk_fma_f32 v[190:191], v[226:227], v[230:231], v[190:191] op_sel_hi:[1,0,1] neg_lo:[0,1,0] neg_hi:[0,1,0]
	v_pk_fma_f32 v[192:193], v[228:229], v[230:231], v[192:193] op_sel_hi:[1,0,1] neg_lo:[0,1,0] neg_hi:[0,1,0]
	ds_read_b128 v[226:229], v233 offset:2416
	v_mov_b32_e32 v230, v114
	v_cvt_pk_bf16_f32 v232, v230, v230
	global_store_short v28, v232, s[0:1]
	s_add_u32 s0, s0, 0x400
	s_addc_u32 s1, s1, 0
	s_waitcnt lgkmcnt(12)
	v_pk_fma_f32 v[114:115], v[38:39], v[230:231], v[114:115] op_sel_hi:[1,0,1] neg_lo:[0,1,0] neg_hi:[0,1,0]
	v_pk_fma_f32 v[116:117], v[40:41], v[230:231], v[116:117] op_sel_hi:[1,0,1] neg_lo:[0,1,0] neg_hi:[0,1,0]
	ds_read_b128 v[38:41], v233 offset:2480
	v_pk_fma_f32 v[118:119], v[42:43], v[230:231], v[118:119] op_sel_hi:[1,0,1] neg_lo:[0,1,0] neg_hi:[0,1,0]
	v_pk_fma_f32 v[120:121], v[44:45], v[230:231], v[120:121] op_sel_hi:[1,0,1] neg_lo:[0,1,0] neg_hi:[0,1,0]
	ds_read_b128 v[42:45], v233 offset:2496
	s_waitcnt lgkmcnt(12)
	v_pk_fma_f32 v[122:123], v[46:47], v[230:231], v[122:123] op_sel_hi:[1,0,1] neg_lo:[0,1,0] neg_hi:[0,1,0]
	v_pk_fma_f32 v[124:125], v[48:49], v[230:231], v[124:125] op_sel_hi:[1,0,1] neg_lo:[0,1,0] neg_hi:[0,1,0]
	ds_read_b128 v[46:49], v233 offset:2512
	v_pk_fma_f32 v[126:127], v[50:51], v[230:231], v[126:127] op_sel_hi:[1,0,1] neg_lo:[0,1,0] neg_hi:[0,1,0]
	v_pk_fma_f32 v[128:129], v[52:53], v[230:231], v[128:129] op_sel_hi:[1,0,1] neg_lo:[0,1,0] neg_hi:[0,1,0]
	ds_read_b128 v[50:53], v233 offset:2528
	s_waitcnt lgkmcnt(12)
	v_pk_fma_f32 v[130:131], v[54:55], v[230:231], v[130:131] op_sel_hi:[1,0,1] neg_lo:[0,1,0] neg_hi:[0,1,0]
	v_pk_fma_f32 v[132:133], v[56:57], v[230:231], v[132:133] op_sel_hi:[1,0,1] neg_lo:[0,1,0] neg_hi:[0,1,0]
	ds_read_b128 v[54:57], v233 offset:2544
	v_pk_fma_f32 v[134:135], v[58:59], v[230:231], v[134:135] op_sel_hi:[1,0,1] neg_lo:[0,1,0] neg_hi:[0,1,0]
	v_pk_fma_f32 v[136:137], v[60:61], v[230:231], v[136:137] op_sel_hi:[1,0,1] neg_lo:[0,1,0] neg_hi:[0,1,0]
	ds_read_b128 v[58:61], v233 offset:2560
	s_waitcnt lgkmcnt(12)
	v_pk_fma_f32 v[138:139], v[62:63], v[230:231], v[138:139] op_sel_hi:[1,0,1] neg_lo:[0,1,0] neg_hi:[0,1,0]
	v_pk_fma_f32 v[140:141], v[64:65], v[230:231], v[140:141] op_sel_hi:[1,0,1] neg_lo:[0,1,0] neg_hi:[0,1,0]
	ds_read_b128 v[62:65], v233 offset:2576
	v_pk_fma_f32 v[142:143], v[66:67], v[230:231], v[142:143] op_sel_hi:[1,0,1] neg_lo:[0,1,0] neg_hi:[0,1,0]
	v_pk_fma_f32 v[144:145], v[68:69], v[230:231], v[144:145] op_sel_hi:[1,0,1] neg_lo:[0,1,0] neg_hi:[0,1,0]
	ds_read_b128 v[66:69], v233 offset:2592
	s_waitcnt lgkmcnt(12)
	v_pk_fma_f32 v[146:147], v[70:71], v[230:231], v[146:147] op_sel_hi:[1,0,1] neg_lo:[0,1,0] neg_hi:[0,1,0]
	v_pk_fma_f32 v[148:149], v[72:73], v[230:231], v[148:149] op_sel_hi:[1,0,1] neg_lo:[0,1,0] neg_hi:[0,1,0]
	ds_read_b128 v[70:73], v233 offset:2608
	v_pk_fma_f32 v[150:151], v[194:195], v[230:231], v[150:151] op_sel_hi:[1,0,1] neg_lo:[0,1,0] neg_hi:[0,1,0]
	v_pk_fma_f32 v[152:153], v[196:197], v[230:231], v[152:153] op_sel_hi:[1,0,1] neg_lo:[0,1,0] neg_hi:[0,1,0]
	ds_read_b128 v[194:197], v233 offset:2624
	s_waitcnt lgkmcnt(12)
	v_pk_fma_f32 v[154:155], v[198:199], v[230:231], v[154:155] op_sel_hi:[1,0,1] neg_lo:[0,1,0] neg_hi:[0,1,0]
	v_pk_fma_f32 v[180:181], v[200:201], v[230:231], v[180:181] op_sel_hi:[1,0,1] neg_lo:[0,1,0] neg_hi:[0,1,0]
	ds_read_b128 v[198:201], v233 offset:2640
	v_pk_fma_f32 v[182:183], v[202:203], v[230:231], v[182:183] op_sel_hi:[1,0,1] neg_lo:[0,1,0] neg_hi:[0,1,0]
	v_pk_fma_f32 v[184:185], v[204:205], v[230:231], v[184:185] op_sel_hi:[1,0,1] neg_lo:[0,1,0] neg_hi:[0,1,0]
	ds_read_b128 v[202:205], v233 offset:2656
	s_waitcnt lgkmcnt(12)
	v_pk_fma_f32 v[186:187], v[206:207], v[230:231], v[186:187] op_sel_hi:[1,0,1] neg_lo:[0,1,0] neg_hi:[0,1,0]
	v_pk_fma_f32 v[188:189], v[208:209], v[230:231], v[188:189] op_sel_hi:[1,0,1] neg_lo:[0,1,0] neg_hi:[0,1,0]
	ds_read_b128 v[206:209], v233 offset:2672
	v_pk_fma_f32 v[190:191], v[226:227], v[230:231], v[190:191] op_sel_hi:[1,0,1] neg_lo:[0,1,0] neg_hi:[0,1,0]
	v_pk_fma_f32 v[192:193], v[228:229], v[230:231], v[192:193] op_sel_hi:[1,0,1] neg_lo:[0,1,0] neg_hi:[0,1,0]
	ds_read_b128 v[226:229], v233 offset:2688
	v_mov_b32_e32 v230, v115
	v_cvt_pk_bf16_f32 v232, v230, v230
	global_store_short v28, v232, s[0:1]
	s_add_u32 s0, s0, 0x400
	s_addc_u32 s1, s1, 0
	s_waitcnt lgkmcnt(12)
	v_pk_fma_f32 v[116:117], v[40:41], v[230:231], v[116:117] op_sel_hi:[1,0,1] neg_lo:[0,1,0] neg_hi:[0,1,0]
	ds_read_b128 v[38:41], v233 offset:2752
	v_pk_fma_f32 v[118:119], v[42:43], v[230:231], v[118:119] op_sel_hi:[1,0,1] neg_lo:[0,1,0] neg_hi:[0,1,0]
	v_pk_fma_f32 v[120:121], v[44:45], v[230:231], v[120:121] op_sel_hi:[1,0,1] neg_lo:[0,1,0] neg_hi:[0,1,0]
	ds_read_b128 v[42:45], v233 offset:2768
	s_waitcnt lgkmcnt(12)
	v_pk_fma_f32 v[122:123], v[46:47], v[230:231], v[122:123] op_sel_hi:[1,0,1] neg_lo:[0,1,0] neg_hi:[0,1,0]
	v_pk_fma_f32 v[124:125], v[48:49], v[230:231], v[124:125] op_sel_hi:[1,0,1] neg_lo:[0,1,0] neg_hi:[0,1,0]
	ds_read_b128 v[46:49], v233 offset:2784
	v_pk_fma_f32 v[126:127], v[50:51], v[230:231], v[126:127] op_sel_hi:[1,0,1] neg_lo:[0,1,0] neg_hi:[0,1,0]
	v_pk_fma_f32 v[128:129], v[52:53], v[230:231], v[128:129] op_sel_hi:[1,0,1] neg_lo:[0,1,0] neg_hi:[0,1,0]
	ds_read_b128 v[50:53], v233 offset:2800
	s_waitcnt lgkmcnt(12)
	v_pk_fma_f32 v[130:131], v[54:55], v[230:231], v[130:131] op_sel_hi:[1,0,1] neg_lo:[0,1,0] neg_hi:[0,1,0]
	v_pk_fma_f32 v[132:133], v[56:57], v[230:231], v[132:133] op_sel_hi:[1,0,1] neg_lo:[0,1,0] neg_hi:[0,1,0]
	ds_read_b128 v[54:57], v233 offset:2816
	v_pk_fma_f32 v[134:135], v[58:59], v[230:231], v[134:135] op_sel_hi:[1,0,1] neg_lo:[0,1,0] neg_hi:[0,1,0]
	v_pk_fma_f32 v[136:137], v[60:61], v[230:231], v[136:137] op_sel_hi:[1,0,1] neg_lo:[0,1,0] neg_hi:[0,1,0]
	ds_read_b128 v[58:61], v233 offset:2832
	s_waitcnt lgkmcnt(12)
	v_pk_fma_f32 v[138:139], v[62:63], v[230:231], v[138:139] op_sel_hi:[1,0,1] neg_lo:[0,1,0] neg_hi:[0,1,0]
	v_pk_fma_f32 v[140:141], v[64:65], v[230:231], v[140:141] op_sel_hi:[1,0,1] neg_lo:[0,1,0] neg_hi:[0,1,0]
	ds_read_b128 v[62:65], v233 offset:2848
	v_pk_fma_f32 v[142:143], v[66:67], v[230:231], v[142:143] op_sel_hi:[1,0,1] neg_lo:[0,1,0] neg_hi:[0,1,0]
	v_pk_fma_f32 v[144:145], v[68:69], v[230:231], v[144:145] op_sel_hi:[1,0,1] neg_lo:[0,1,0] neg_hi:[0,1,0]
	ds_read_b128 v[66:69], v233 offset:2864
	s_waitcnt lgkmcnt(12)
	v_pk_fma_f32 v[146:147], v[70:71], v[230:231], v[146:147] op_sel_hi:[1,0,1] neg_lo:[0,1,0] neg_hi:[0,1,0]
	v_pk_fma_f32 v[148:149], v[72:73], v[230:231], v[148:149] op_sel_hi:[1,0,1] neg_lo:[0,1,0] neg_hi:[0,1,0]
	ds_read_b128 v[70:73], v233 offset:2880
	v_pk_fma_f32 v[150:151], v[194:195], v[230:231], v[150:151] op_sel_hi:[1,0,1] neg_lo:[0,1,0] neg_hi:[0,1,0]
	v_pk_fma_f32 v[152:153], v[196:197], v[230:231], v[152:153] op_sel_hi:[1,0,1] neg_lo:[0,1,0] neg_hi:[0,1,0]
	ds_read_b128 v[194:197], v233 offset:2896
	s_waitcnt lgkmcnt(12)
	v_pk_fma_f32 v[154:155], v[198:199], v[230:231], v[154:155] op_sel_hi:[1,0,1] neg_lo:[0,1,0] neg_hi:[0,1,0]
	v_pk_fma_f32 v[180:181], v[200:201], v[230:231], v[180:181] op_sel_hi:[1,0,1] neg_lo:[0,1,0] neg_hi:[0,1,0]
	ds_read_b128 v[198:201], v233 offset:2912
	v_pk_fma_f32 v[182:183], v[202:203], v[230:231], v[182:183] op_sel_hi:[1,0,1] neg_lo:[0,1,0] neg_hi:[0,1,0]
	v_pk_fma_f32 v[184:185], v[204:205], v[230:231], v[184:185] op_sel_hi:[1,0,1] neg_lo:[0,1,0] neg_hi:[0,1,0]
	ds_read_b128 v[202:205], v233 offset:2928
	s_waitcnt lgkmcnt(12)
	v_pk_fma_f32 v[186:187], v[206:207], v[230:231], v[186:187] op_sel_hi:[1,0,1] neg_lo:[0,1,0] neg_hi:[0,1,0]
	v_pk_fma_f32 v[188:189], v[208:209], v[230:231], v[188:189] op_sel_hi:[1,0,1] neg_lo:[0,1,0] neg_hi:[0,1,0]
	ds_read_b128 v[206:209], v233 offset:2944
	v_pk_fma_f32 v[190:191], v[226:227], v[230:231], v[190:191] op_sel_hi:[1,0,1] neg_lo:[0,1,0] neg_hi:[0,1,0]
	v_pk_fma_f32 v[192:193], v[228:229], v[230:231], v[192:193] op_sel_hi:[1,0,1] neg_lo:[0,1,0] neg_hi:[0,1,0]
	ds_read_b128 v[226:229], v233 offset:2960
	v_mov_b32_e32 v230, v116
	v_cvt_pk_bf16_f32 v232, v230, v230
	global_store_short v28, v232, s[0:1]
	s_add_u32 s0, s0, 0x400
	s_addc_u32 s1, s1, 0
	s_waitcnt lgkmcnt(12)
	v_pk_fma_f32 v[116:117], v[40:41], v[230:231], v[116:117] op_sel_hi:[1,0,1] neg_lo:[0,1,0] neg_hi:[0,1,0]
	v_pk_fma_f32 v[118:119], v[42:43], v[230:231], v[118:119] op_sel_hi:[1,0,1] neg_lo:[0,1,0] neg_hi:[0,1,0]
	v_pk_fma_f32 v[120:121], v[44:45], v[230:231], v[120:121] op_sel_hi:[1,0,1] neg_lo:[0,1,0] neg_hi:[0,1,0]
	ds_read_b128 v[42:45], v233 offset:3040
	s_waitcnt lgkmcnt(11)
	v_pk_fma_f32 v[122:123], v[46:47], v[230:231], v[122:123] op_sel_hi:[1,0,1] neg_lo:[0,1,0] neg_hi:[0,1,0]
	v_pk_fma_f32 v[124:125], v[48:49], v[230:231], v[124:125] op_sel_hi:[1,0,1] neg_lo:[0,1,0] neg_hi:[0,1,0]
	ds_read_b128 v[46:49], v233 offset:3056
	v_pk_fma_f32 v[126:127], v[50:51], v[230:231], v[126:127] op_sel_hi:[1,0,1] neg_lo:[0,1,0] neg_hi:[0,1,0]
	v_pk_fma_f32 v[128:129], v[52:53], v[230:231], v[128:129] op_sel_hi:[1,0,1] neg_lo:[0,1,0] neg_hi:[0,1,0]
	ds_read_b128 v[50:53], v233 offset:3072
	s_waitcnt lgkmcnt(11)
	v_pk_fma_f32 v[130:131], v[54:55], v[230:231], v[130:131] op_sel_hi:[1,0,1] neg_lo:[0,1,0] neg_hi:[0,1,0]
	v_pk_fma_f32 v[132:133], v[56:57], v[230:231], v[132:133] op_sel_hi:[1,0,1] neg_lo:[0,1,0] neg_hi:[0,1,0]
	ds_read_b128 v[54:57], v233 offset:3088
	v_pk_fma_f32 v[134:135], v[58:59], v[230:231], v[134:135] op_sel_hi:[1,0,1] neg_lo:[0,1,0] neg_hi:[0,1,0]
	v_pk_fma_f32 v[136:137], v[60:61], v[230:231], v[136:137] op_sel_hi:[1,0,1] neg_lo:[0,1,0] neg_hi:[0,1,0]
	ds_read_b128 v[58:61], v233 offset:3104
	s_waitcnt lgkmcnt(11)
	v_pk_fma_f32 v[138:139], v[62:63], v[230:231], v[138:139] op_sel_hi:[1,0,1] neg_lo:[0,1,0] neg_hi:[0,1,0]
	v_pk_fma_f32 v[140:141], v[64:65], v[230:231], v[140:141] op_sel_hi:[1,0,1] neg_lo:[0,1,0] neg_hi:[0,1,0]
	ds_read_b128 v[62:65], v233 offset:3120
	v_pk_fma_f32 v[142:143], v[66:67], v[230:231], v[142:143] op_sel_hi:[1,0,1] neg_lo:[0,1,0] neg_hi:[0,1,0]
	v_pk_fma_f32 v[144:145], v[68:69], v[230:231], v[144:145] op_sel_hi:[1,0,1] neg_lo:[0,1,0] neg_hi:[0,1,0]
	ds_read_b128 v[66:69], v233 offset:3136
	s_waitcnt lgkmcnt(11)
	v_pk_fma_f32 v[146:147], v[70:71], v[230:231], v[146:147] op_sel_hi:[1,0,1] neg_lo:[0,1,0] neg_hi:[0,1,0]
	v_pk_fma_f32 v[148:149], v[72:73], v[230:231], v[148:149] op_sel_hi:[1,0,1] neg_lo:[0,1,0] neg_hi:[0,1,0]
	ds_read_b128 v[70:73], v233 offset:3152
	v_pk_fma_f32 v[150:151], v[194:195], v[230:231], v[150:151] op_sel_hi:[1,0,1] neg_lo:[0,1,0] neg_hi:[0,1,0]
	v_pk_fma_f32 v[152:153], v[196:197], v[230:231], v[152:153] op_sel_hi:[1,0,1] neg_lo:[0,1,0] neg_hi:[0,1,0]
	ds_read_b128 v[194:197], v233 offset:3168
	s_waitcnt lgkmcnt(11)
	v_pk_fma_f32 v[154:155], v[198:199], v[230:231], v[154:155] op_sel_hi:[1,0,1] neg_lo:[0,1,0] neg_hi:[0,1,0]
	v_pk_fma_f32 v[180:181], v[200:201], v[230:231], v[180:181] op_sel_hi:[1,0,1] neg_lo:[0,1,0] neg_hi:[0,1,0]
	ds_read_b128 v[198:201], v233 offset:3184
	v_pk_fma_f32 v[182:183], v[202:203], v[230:231], v[182:183] op_sel_hi:[1,0,1] neg_lo:[0,1,0] neg_hi:[0,1,0]
	v_pk_fma_f32 v[184:185], v[204:205], v[230:231], v[184:185] op_sel_hi:[1,0,1] neg_lo:[0,1,0] neg_hi:[0,1,0]
	ds_read_b128 v[202:205], v233 offset:3200
	s_waitcnt lgkmcnt(11)
	v_pk_fma_f32 v[186:187], v[206:207], v[230:231], v[186:187] op_sel_hi:[1,0,1] neg_lo:[0,1,0] neg_hi:[0,1,0]
	v_pk_fma_f32 v[188:189], v[208:209], v[230:231], v[188:189] op_sel_hi:[1,0,1] neg_lo:[0,1,0] neg_hi:[0,1,0]
	ds_read_b128 v[206:209], v233 offset:3216
	v_pk_fma_f32 v[190:191], v[226:227], v[230:231], v[190:191] op_sel_hi:[1,0,1] neg_lo:[0,1,0] neg_hi:[0,1,0]
	v_pk_fma_f32 v[192:193], v[228:229], v[230:231], v[192:193] op_sel_hi:[1,0,1] neg_lo:[0,1,0] neg_hi:[0,1,0]
	ds_read_b128 v[226:229], v233 offset:3232
	v_mov_b32_e32 v230, v117
	v_cvt_pk_bf16_f32 v232, v230, v230
	global_store_short v28, v232, s[0:1]
	s_add_u32 s0, s0, 0x400
	s_addc_u32 s1, s1, 0
	s_waitcnt lgkmcnt(11)
	v_pk_fma_f32 v[118:119], v[42:43], v[230:231], v[118:119] op_sel_hi:[1,0,1] neg_lo:[0,1,0] neg_hi:[0,1,0]
	v_pk_fma_f32 v[120:121], v[44:45], v[230:231], v[120:121] op_sel_hi:[1,0,1] neg_lo:[0,1,0] neg_hi:[0,1,0]
	ds_read_b128 v[42:45], v233 offset:3312
	v_pk_fma_f32 v[122:123], v[46:47], v[230:231], v[122:123] op_sel_hi:[1,0,1] neg_lo:[0,1,0] neg_hi:[0,1,0]
	v_pk_fma_f32 v[124:125], v[48:49], v[230:231], v[124:125] op_sel_hi:[1,0,1] neg_lo:[0,1,0] neg_hi:[0,1,0]
	ds_read_b128 v[46:49], v233 offset:3328
	s_waitcnt lgkmcnt(11)
	v_pk_fma_f32 v[126:127], v[50:51], v[230:231], v[126:127] op_sel_hi:[1,0,1] neg_lo:[0,1,0] neg_hi:[0,1,0]
	v_pk_fma_f32 v[128:129], v[52:53], v[230:231], v[128:129] op_sel_hi:[1,0,1] neg_lo:[0,1,0] neg_hi:[0,1,0]
	ds_read_b128 v[50:53], v233 offset:3344
	v_pk_fma_f32 v[130:131], v[54:55], v[230:231], v[130:131] op_sel_hi:[1,0,1] neg_lo:[0,1,0] neg_hi:[0,1,0]
	v_pk_fma_f32 v[132:133], v[56:57], v[230:231], v[132:133] op_sel_hi:[1,0,1] neg_lo:[0,1,0] neg_hi:[0,1,0]
	ds_read_b128 v[54:57], v233 offset:3360
	s_waitcnt lgkmcnt(11)
	v_pk_fma_f32 v[134:135], v[58:59], v[230:231], v[134:135] op_sel_hi:[1,0,1] neg_lo:[0,1,0] neg_hi:[0,1,0]
	v_pk_fma_f32 v[136:137], v[60:61], v[230:231], v[136:137] op_sel_hi:[1,0,1] neg_lo:[0,1,0] neg_hi:[0,1,0]
	ds_read_b128 v[58:61], v233 offset:3376
	v_pk_fma_f32 v[138:139], v[62:63], v[230:231], v[138:139] op_sel_hi:[1,0,1] neg_lo:[0,1,0] neg_hi:[0,1,0]
	v_pk_fma_f32 v[140:141], v[64:65], v[230:231], v[140:141] op_sel_hi:[1,0,1] neg_lo:[0,1,0] neg_hi:[0,1,0]
	ds_read_b128 v[62:65], v233 offset:3392
	s_waitcnt lgkmcnt(11)
	v_pk_fma_f32 v[142:143], v[66:67], v[230:231], v[142:143] op_sel_hi:[1,0,1] neg_lo:[0,1,0] neg_hi:[0,1,0]
	v_pk_fma_f32 v[144:145], v[68:69], v[230:231], v[144:145] op_sel_hi:[1,0,1] neg_lo:[0,1,0] neg_hi:[0,1,0]
	ds_read_b128 v[66:69], v233 offset:3408
	v_pk_fma_f32 v[146:147], v[70:71], v[230:231], v[146:147] op_sel_hi:[1,0,1] neg_lo:[0,1,0] neg_hi:[0,1,0]
	v_pk_fma_f32 v[148:149], v[72:73], v[230:231], v[148:149] op_sel_hi:[1,0,1] neg_lo:[0,1,0] neg_hi:[0,1,0]
	ds_read_b128 v[70:73], v233 offset:3424
	s_waitcnt lgkmcnt(11)
	v_pk_fma_f32 v[150:151], v[194:195], v[230:231], v[150:151] op_sel_hi:[1,0,1] neg_lo:[0,1,0] neg_hi:[0,1,0]
	v_pk_fma_f32 v[152:153], v[196:197], v[230:231], v[152:153] op_sel_hi:[1,0,1] neg_lo:[0,1,0] neg_hi:[0,1,0]
	ds_read_b128 v[194:197], v233 offset:3440
	v_pk_fma_f32 v[154:155], v[198:199], v[230:231], v[154:155] op_sel_hi:[1,0,1] neg_lo:[0,1,0] neg_hi:[0,1,0]
	v_pk_fma_f32 v[180:181], v[200:201], v[230:231], v[180:181] op_sel_hi:[1,0,1] neg_lo:[0,1,0] neg_hi:[0,1,0]
	ds_read_b128 v[198:201], v233 offset:3456
	s_waitcnt lgkmcnt(11)
	v_pk_fma_f32 v[182:183], v[202:203], v[230:231], v[182:183] op_sel_hi:[1,0,1] neg_lo:[0,1,0] neg_hi:[0,1,0]
	v_pk_fma_f32 v[184:185], v[204:205], v[230:231], v[184:185] op_sel_hi:[1,0,1] neg_lo:[0,1,0] neg_hi:[0,1,0]
	ds_read_b128 v[202:205], v233 offset:3472
	v_pk_fma_f32 v[186:187], v[206:207], v[230:231], v[186:187] op_sel_hi:[1,0,1] neg_lo:[0,1,0] neg_hi:[0,1,0]
	v_pk_fma_f32 v[188:189], v[208:209], v[230:231], v[188:189] op_sel_hi:[1,0,1] neg_lo:[0,1,0] neg_hi:[0,1,0]
	ds_read_b128 v[206:209], v233 offset:3488
	s_waitcnt lgkmcnt(12)
	v_pk_fma_f32 v[190:191], v[226:227], v[230:231], v[190:191] op_sel_hi:[1,0,1] neg_lo:[0,1,0] neg_hi:[0,1,0]
	v_pk_fma_f32 v[192:193], v[228:229], v[230:231], v[192:193] op_sel_hi:[1,0,1] neg_lo:[0,1,0] neg_hi:[0,1,0]
	ds_read_b128 v[226:229], v233 offset:3504
	v_mov_b32_e32 v230, v118
	v_cvt_pk_bf16_f32 v232, v230, v230
	global_store_short v28, v232, s[0:1]
	s_add_u32 s0, s0, 0x400
	s_addc_u32 s1, s1, 0
	s_waitcnt lgkmcnt(11)
	v_pk_fma_f32 v[118:119], v[42:43], v[230:231], v[118:119] op_sel_hi:[1,0,1] neg_lo:[0,1,0] neg_hi:[0,1,0]
	v_pk_fma_f32 v[120:121], v[44:45], v[230:231], v[120:121] op_sel_hi:[1,0,1] neg_lo:[0,1,0] neg_hi:[0,1,0]
	ds_read_b128 v[42:45], v233 offset:3584
	v_pk_fma_f32 v[122:123], v[46:47], v[230:231], v[122:123] op_sel_hi:[1,0,1] neg_lo:[0,1,0] neg_hi:[0,1,0]
	v_pk_fma_f32 v[124:125], v[48:49], v[230:231], v[124:125] op_sel_hi:[1,0,1] neg_lo:[0,1,0] neg_hi:[0,1,0]
	ds_read_b128 v[46:49], v233 offset:3600
	s_waitcnt lgkmcnt(11)
	v_pk_fma_f32 v[126:127], v[50:51], v[230:231], v[126:127] op_sel_hi:[1,0,1] neg_lo:[0,1,0] neg_hi:[0,1,0]
	v_pk_fma_f32 v[128:129], v[52:53], v[230:231], v[128:129] op_sel_hi:[1,0,1] neg_lo:[0,1,0] neg_hi:[0,1,0]
	ds_read_b128 v[50:53], v233 offset:3616
	v_pk_fma_f32 v[130:131], v[54:55], v[230:231], v[130:131] op_sel_hi:[1,0,1] neg_lo:[0,1,0] neg_hi:[0,1,0]
	v_pk_fma_f32 v[132:133], v[56:57], v[230:231], v[132:133] op_sel_hi:[1,0,1] neg_lo:[0,1,0] neg_hi:[0,1,0]
	ds_read_b128 v[54:57], v233 offset:3632
	s_waitcnt lgkmcnt(11)
	v_pk_fma_f32 v[134:135], v[58:59], v[230:231], v[134:135] op_sel_hi:[1,0,1] neg_lo:[0,1,0] neg_hi:[0,1,0]
	v_pk_fma_f32 v[136:137], v[60:61], v[230:231], v[136:137] op_sel_hi:[1,0,1] neg_lo:[0,1,0] neg_hi:[0,1,0]
	ds_read_b128 v[58:61], v233 offset:3648
	v_pk_fma_f32 v[138:139], v[62:63], v[230:231], v[138:139] op_sel_hi:[1,0,1] neg_lo:[0,1,0] neg_hi:[0,1,0]
	v_pk_fma_f32 v[140:141], v[64:65], v[230:231], v[140:141] op_sel_hi:[1,0,1] neg_lo:[0,1,0] neg_hi:[0,1,0]
	ds_read_b128 v[62:65], v233 offset:3664
	s_waitcnt lgkmcnt(11)
	v_pk_fma_f32 v[142:143], v[66:67], v[230:231], v[142:143] op_sel_hi:[1,0,1] neg_lo:[0,1,0] neg_hi:[0,1,0]
	v_pk_fma_f32 v[144:145], v[68:69], v[230:231], v[144:145] op_sel_hi:[1,0,1] neg_lo:[0,1,0] neg_hi:[0,1,0]
	ds_read_b128 v[66:69], v233 offset:3680
	v_pk_fma_f32 v[146:147], v[70:71], v[230:231], v[146:147] op_sel_hi:[1,0,1] neg_lo:[0,1,0] neg_hi:[0,1,0]
	v_pk_fma_f32 v[148:149], v[72:73], v[230:231], v[148:149] op_sel_hi:[1,0,1] neg_lo:[0,1,0] neg_hi:[0,1,0]
	ds_read_b128 v[70:73], v233 offset:3696
	s_waitcnt lgkmcnt(11)
	v_pk_fma_f32 v[150:151], v[194:195], v[230:231], v[150:151] op_sel_hi:[1,0,1] neg_lo:[0,1,0] neg_hi:[0,1,0]
	v_pk_fma_f32 v[152:153], v[196:197], v[230:231], v[152:153] op_sel_hi:[1,0,1] neg_lo:[0,1,0] neg_hi:[0,1,0]
	ds_read_b128 v[194:197], v233 offset:3712
	v_pk_fma_f32 v[154:155], v[198:199], v[230:231], v[154:155] op_sel_hi:[1,0,1] neg_lo:[0,1,0] neg_hi:[0,1,0]
	v_pk_fma_f32 v[180:181], v[200:201], v[230:231], v[180:181] op_sel_hi:[1,0,1] neg_lo:[0,1,0] neg_hi:[0,1,0]
	ds_read_b128 v[198:201], v233 offset:3728
	s_waitcnt lgkmcnt(11)
	v_pk_fma_f32 v[182:183], v[202:203], v[230:231], v[182:183] op_sel_hi:[1,0,1] neg_lo:[0,1,0] neg_hi:[0,1,0]
	v_pk_fma_f32 v[184:185], v[204:205], v[230:231], v[184:185] op_sel_hi:[1,0,1] neg_lo:[0,1,0] neg_hi:[0,1,0]
	ds_read_b128 v[202:205], v233 offset:3744
	v_pk_fma_f32 v[186:187], v[206:207], v[230:231], v[186:187] op_sel_hi:[1,0,1] neg_lo:[0,1,0] neg_hi:[0,1,0]
	v_pk_fma_f32 v[188:189], v[208:209], v[230:231], v[188:189] op_sel_hi:[1,0,1] neg_lo:[0,1,0] neg_hi:[0,1,0]
	ds_read_b128 v[206:209], v233 offset:3760
	s_waitcnt lgkmcnt(12)
	v_pk_fma_f32 v[190:191], v[226:227], v[230:231], v[190:191] op_sel_hi:[1,0,1] neg_lo:[0,1,0] neg_hi:[0,1,0]
	v_pk_fma_f32 v[192:193], v[228:229], v[230:231], v[192:193] op_sel_hi:[1,0,1] neg_lo:[0,1,0] neg_hi:[0,1,0]
	ds_read_b128 v[226:229], v233 offset:3776
	v_mov_b32_e32 v230, v119
	v_cvt_pk_bf16_f32 v232, v230, v230
	global_store_short v28, v232, s[0:1]
	s_add_u32 s0, s0, 0x400
	s_addc_u32 s1, s1, 0
	s_waitcnt lgkmcnt(11)
	v_pk_fma_f32 v[120:121], v[44:45], v[230:231], v[120:121] op_sel_hi:[1,0,1] neg_lo:[0,1,0] neg_hi:[0,1,0]
	ds_read_b128 v[42:45], v233 offset:3856
	v_pk_fma_f32 v[122:123], v[46:47], v[230:231], v[122:123] op_sel_hi:[1,0,1] neg_lo:[0,1,0] neg_hi:[0,1,0]
	v_pk_fma_f32 v[124:125], v[48:49], v[230:231], v[124:125] op_sel_hi:[1,0,1] neg_lo:[0,1,0] neg_hi:[0,1,0]
	ds_read_b128 v[46:49], v233 offset:3872
	s_waitcnt lgkmcnt(11)
	v_pk_fma_f32 v[126:127], v[50:51], v[230:231], v[126:127] op_sel_hi:[1,0,1] neg_lo:[0,1,0] neg_hi:[0,1,0]
	v_pk_fma_f32 v[128:129], v[52:53], v[230:231], v[128:129] op_sel_hi:[1,0,1] neg_lo:[0,1,0] neg_hi:[0,1,0]
	ds_read_b128 v[50:53], v233 offset:3888
	v_pk_fma_f32 v[130:131], v[54:55], v[230:231], v[130:131] op_sel_hi:[1,0,1] neg_lo:[0,1,0] neg_hi:[0,1,0]
	v_pk_fma_f32 v[132:133], v[56:57], v[230:231], v[132:133] op_sel_hi:[1,0,1] neg_lo:[0,1,0] neg_hi:[0,1,0]
	ds_read_b128 v[54:57], v233 offset:3904
	s_waitcnt lgkmcnt(11)
	v_pk_fma_f32 v[134:135], v[58:59], v[230:231], v[134:135] op_sel_hi:[1,0,1] neg_lo:[0,1,0] neg_hi:[0,1,0]
	v_pk_fma_f32 v[136:137], v[60:61], v[230:231], v[136:137] op_sel_hi:[1,0,1] neg_lo:[0,1,0] neg_hi:[0,1,0]
	ds_read_b128 v[58:61], v233 offset:3920
	v_pk_fma_f32 v[138:139], v[62:63], v[230:231], v[138:139] op_sel_hi:[1,0,1] neg_lo:[0,1,0] neg_hi:[0,1,0]
	v_pk_fma_f32 v[140:141], v[64:65], v[230:231], v[140:141] op_sel_hi:[1,0,1] neg_lo:[0,1,0] neg_hi:[0,1,0]
	ds_read_b128 v[62:65], v233 offset:3936
	s_waitcnt lgkmcnt(11)
	v_pk_fma_f32 v[142:143], v[66:67], v[230:231], v[142:143] op_sel_hi:[1,0,1] neg_lo:[0,1,0] neg_hi:[0,1,0]
	v_pk_fma_f32 v[144:145], v[68:69], v[230:231], v[144:145] op_sel_hi:[1,0,1] neg_lo:[0,1,0] neg_hi:[0,1,0]
	ds_read_b128 v[66:69], v233 offset:3952
	v_pk_fma_f32 v[146:147], v[70:71], v[230:231], v[146:147] op_sel_hi:[1,0,1] neg_lo:[0,1,0] neg_hi:[0,1,0]
	v_pk_fma_f32 v[148:149], v[72:73], v[230:231], v[148:149] op_sel_hi:[1,0,1] neg_lo:[0,1,0] neg_hi:[0,1,0]
	ds_read_b128 v[70:73], v233 offset:3968
	s_waitcnt lgkmcnt(11)
	v_pk_fma_f32 v[150:151], v[194:195], v[230:231], v[150:151] op_sel_hi:[1,0,1] neg_lo:[0,1,0] neg_hi:[0,1,0]
	v_pk_fma_f32 v[152:153], v[196:197], v[230:231], v[152:153] op_sel_hi:[1,0,1] neg_lo:[0,1,0] neg_hi:[0,1,0]
	ds_read_b128 v[194:197], v233 offset:3984
	v_pk_fma_f32 v[154:155], v[198:199], v[230:231], v[154:155] op_sel_hi:[1,0,1] neg_lo:[0,1,0] neg_hi:[0,1,0]
	v_pk_fma_f32 v[180:181], v[200:201], v[230:231], v[180:181] op_sel_hi:[1,0,1] neg_lo:[0,1,0] neg_hi:[0,1,0]
	ds_read_b128 v[198:201], v233 offset:4000
	s_waitcnt lgkmcnt(11)
	v_pk_fma_f32 v[182:183], v[202:203], v[230:231], v[182:183] op_sel_hi:[1,0,1] neg_lo:[0,1,0] neg_hi:[0,1,0]
	v_pk_fma_f32 v[184:185], v[204:205], v[230:231], v[184:185] op_sel_hi:[1,0,1] neg_lo:[0,1,0] neg_hi:[0,1,0]
	ds_read_b128 v[202:205], v233 offset:4016
	v_pk_fma_f32 v[186:187], v[206:207], v[230:231], v[186:187] op_sel_hi:[1,0,1] neg_lo:[0,1,0] neg_hi:[0,1,0]
	v_pk_fma_f32 v[188:189], v[208:209], v[230:231], v[188:189] op_sel_hi:[1,0,1] neg_lo:[0,1,0] neg_hi:[0,1,0]
	ds_read_b128 v[206:209], v233 offset:4032
	s_waitcnt lgkmcnt(12)
	v_pk_fma_f32 v[190:191], v[226:227], v[230:231], v[190:191] op_sel_hi:[1,0,1] neg_lo:[0,1,0] neg_hi:[0,1,0]
	v_pk_fma_f32 v[192:193], v[228:229], v[230:231], v[192:193] op_sel_hi:[1,0,1] neg_lo:[0,1,0] neg_hi:[0,1,0]
	ds_read_b128 v[226:229], v233 offset:4048
	v_mov_b32_e32 v230, v120
	v_cvt_pk_bf16_f32 v232, v230, v230
	global_store_short v28, v232, s[0:1]
	s_add_u32 s0, s0, 0x400
	s_addc_u32 s1, s1, 0
	s_waitcnt lgkmcnt(11)
	v_pk_fma_f32 v[120:121], v[44:45], v[230:231], v[120:121] op_sel_hi:[1,0,1] neg_lo:[0,1,0] neg_hi:[0,1,0]
	v_pk_fma_f32 v[122:123], v[46:47], v[230:231], v[122:123] op_sel_hi:[1,0,1] neg_lo:[0,1,0] neg_hi:[0,1,0]
	v_pk_fma_f32 v[124:125], v[48:49], v[230:231], v[124:125] op_sel_hi:[1,0,1] neg_lo:[0,1,0] neg_hi:[0,1,0]
	ds_read_b128 v[46:49], v233 offset:4144
	s_waitcnt lgkmcnt(10)
	v_pk_fma_f32 v[126:127], v[50:51], v[230:231], v[126:127] op_sel_hi:[1,0,1] neg_lo:[0,1,0] neg_hi:[0,1,0]
	v_pk_fma_f32 v[128:129], v[52:53], v[230:231], v[128:129] op_sel_hi:[1,0,1] neg_lo:[0,1,0] neg_hi:[0,1,0]
	ds_read_b128 v[50:53], v233 offset:4160
	v_pk_fma_f32 v[130:131], v[54:55], v[230:231], v[130:131] op_sel_hi:[1,0,1] neg_lo:[0,1,0] neg_hi:[0,1,0]
	v_pk_fma_f32 v[132:133], v[56:57], v[230:231], v[132:133] op_sel_hi:[1,0,1] neg_lo:[0,1,0] neg_hi:[0,1,0]
	ds_read_b128 v[54:57], v233 offset:4176
	s_waitcnt lgkmcnt(10)
	v_pk_fma_f32 v[134:135], v[58:59], v[230:231], v[134:135] op_sel_hi:[1,0,1] neg_lo:[0,1,0] neg_hi:[0,1,0]
	v_pk_fma_f32 v[136:137], v[60:61], v[230:231], v[136:137] op_sel_hi:[1,0,1] neg_lo:[0,1,0] neg_hi:[0,1,0]
	ds_read_b128 v[58:61], v233 offset:4192
	v_pk_fma_f32 v[138:139], v[62:63], v[230:231], v[138:139] op_sel_hi:[1,0,1] neg_lo:[0,1,0] neg_hi:[0,1,0]
	v_pk_fma_f32 v[140:141], v[64:65], v[230:231], v[140:141] op_sel_hi:[1,0,1] neg_lo:[0,1,0] neg_hi:[0,1,0]
	ds_read_b128 v[62:65], v233 offset:4208
	s_waitcnt lgkmcnt(10)
	v_pk_fma_f32 v[142:143], v[66:67], v[230:231], v[142:143] op_sel_hi:[1,0,1] neg_lo:[0,1,0] neg_hi:[0,1,0]
	v_pk_fma_f32 v[144:145], v[68:69], v[230:231], v[144:145] op_sel_hi:[1,0,1] neg_lo:[0,1,0] neg_hi:[0,1,0]
	ds_read_b128 v[66:69], v233 offset:4224
	v_pk_fma_f32 v[146:147], v[70:71], v[230:231], v[146:147] op_sel_hi:[1,0,1] neg_lo:[0,1,0] neg_hi:[0,1,0]
	v_pk_fma_f32 v[148:149], v[72:73], v[230:231], v[148:149] op_sel_hi:[1,0,1] neg_lo:[0,1,0] neg_hi:[0,1,0]
	ds_read_b128 v[70:73], v233 offset:4240
	s_waitcnt lgkmcnt(10)
	v_pk_fma_f32 v[150:151], v[194:195], v[230:231], v[150:151] op_sel_hi:[1,0,1] neg_lo:[0,1,0] neg_hi:[0,1,0]
	v_pk_fma_f32 v[152:153], v[196:197], v[230:231], v[152:153] op_sel_hi:[1,0,1] neg_lo:[0,1,0] neg_hi:[0,1,0]
	ds_read_b128 v[194:197], v233 offset:4256
	v_pk_fma_f32 v[154:155], v[198:199], v[230:231], v[154:155] op_sel_hi:[1,0,1] neg_lo:[0,1,0] neg_hi:[0,1,0]
	v_pk_fma_f32 v[180:181], v[200:201], v[230:231], v[180:181] op_sel_hi:[1,0,1] neg_lo:[0,1,0] neg_hi:[0,1,0]
	ds_read_b128 v[198:201], v233 offset:4272
	s_waitcnt lgkmcnt(10)
	v_pk_fma_f32 v[182:183], v[202:203], v[230:231], v[182:183] op_sel_hi:[1,0,1] neg_lo:[0,1,0] neg_hi:[0,1,0]
	v_pk_fma_f32 v[184:185], v[204:205], v[230:231], v[184:185] op_sel_hi:[1,0,1] neg_lo:[0,1,0] neg_hi:[0,1,0]
	ds_read_b128 v[202:205], v233 offset:4288
	v_pk_fma_f32 v[186:187], v[206:207], v[230:231], v[186:187] op_sel_hi:[1,0,1] neg_lo:[0,1,0] neg_hi:[0,1,0]
	v_pk_fma_f32 v[188:189], v[208:209], v[230:231], v[188:189] op_sel_hi:[1,0,1] neg_lo:[0,1,0] neg_hi:[0,1,0]
	ds_read_b128 v[206:209], v233 offset:4304
	s_waitcnt lgkmcnt(11)
	v_pk_fma_f32 v[190:191], v[226:227], v[230:231], v[190:191] op_sel_hi:[1,0,1] neg_lo:[0,1,0] neg_hi:[0,1,0]
	v_pk_fma_f32 v[192:193], v[228:229], v[230:231], v[192:193] op_sel_hi:[1,0,1] neg_lo:[0,1,0] neg_hi:[0,1,0]
	ds_read_b128 v[226:229], v233 offset:4320
	v_mov_b32_e32 v230, v121
	v_cvt_pk_bf16_f32 v232, v230, v230
	global_store_short v28, v232, s[0:1]
	s_add_u32 s0, s0, 0x400
	s_addc_u32 s1, s1, 0
	s_waitcnt lgkmcnt(10)
	v_pk_fma_f32 v[122:123], v[46:47], v[230:231], v[122:123] op_sel_hi:[1,0,1] neg_lo:[0,1,0] neg_hi:[0,1,0]
	v_pk_fma_f32 v[124:125], v[48:49], v[230:231], v[124:125] op_sel_hi:[1,0,1] neg_lo:[0,1,0] neg_hi:[0,1,0]
	ds_read_b128 v[46:49], v233 offset:4416
	v_pk_fma_f32 v[126:127], v[50:51], v[230:231], v[126:127] op_sel_hi:[1,0,1] neg_lo:[0,1,0] neg_hi:[0,1,0]
	v_pk_fma_f32 v[128:129], v[52:53], v[230:231], v[128:129] op_sel_hi:[1,0,1] neg_lo:[0,1,0] neg_hi:[0,1,0]
	ds_read_b128 v[50:53], v233 offset:4432
	s_waitcnt lgkmcnt(10)
	v_pk_fma_f32 v[130:131], v[54:55], v[230:231], v[130:131] op_sel_hi:[1,0,1] neg_lo:[0,1,0] neg_hi:[0,1,0]
	v_pk_fma_f32 v[132:133], v[56:57], v[230:231], v[132:133] op_sel_hi:[1,0,1] neg_lo:[0,1,0] neg_hi:[0,1,0]
	ds_read_b128 v[54:57], v233 offset:4448
	v_pk_fma_f32 v[134:135], v[58:59], v[230:231], v[134:135] op_sel_hi:[1,0,1] neg_lo:[0,1,0] neg_hi:[0,1,0]
	v_pk_fma_f32 v[136:137], v[60:61], v[230:231], v[136:137] op_sel_hi:[1,0,1] neg_lo:[0,1,0] neg_hi:[0,1,0]
	ds_read_b128 v[58:61], v233 offset:4464
	s_waitcnt lgkmcnt(10)
	v_pk_fma_f32 v[138:139], v[62:63], v[230:231], v[138:139] op_sel_hi:[1,0,1] neg_lo:[0,1,0] neg_hi:[0,1,0]
	v_pk_fma_f32 v[140:141], v[64:65], v[230:231], v[140:141] op_sel_hi:[1,0,1] neg_lo:[0,1,0] neg_hi:[0,1,0]
	ds_read_b128 v[62:65], v233 offset:4480
	v_pk_fma_f32 v[142:143], v[66:67], v[230:231], v[142:143] op_sel_hi:[1,0,1] neg_lo:[0,1,0] neg_hi:[0,1,0]
	v_pk_fma_f32 v[144:145], v[68:69], v[230:231], v[144:145] op_sel_hi:[1,0,1] neg_lo:[0,1,0] neg_hi:[0,1,0]
	ds_read_b128 v[66:69], v233 offset:4496
	s_waitcnt lgkmcnt(10)
	v_pk_fma_f32 v[146:147], v[70:71], v[230:231], v[146:147] op_sel_hi:[1,0,1] neg_lo:[0,1,0] neg_hi:[0,1,0]
	v_pk_fma_f32 v[148:149], v[72:73], v[230:231], v[148:149] op_sel_hi:[1,0,1] neg_lo:[0,1,0] neg_hi:[0,1,0]
	ds_read_b128 v[70:73], v233 offset:4512
	v_pk_fma_f32 v[150:151], v[194:195], v[230:231], v[150:151] op_sel_hi:[1,0,1] neg_lo:[0,1,0] neg_hi:[0,1,0]
	v_pk_fma_f32 v[152:153], v[196:197], v[230:231], v[152:153] op_sel_hi:[1,0,1] neg_lo:[0,1,0] neg_hi:[0,1,0]
	ds_read_b128 v[194:197], v233 offset:4528
	s_waitcnt lgkmcnt(10)
	v_pk_fma_f32 v[154:155], v[198:199], v[230:231], v[154:155] op_sel_hi:[1,0,1] neg_lo:[0,1,0] neg_hi:[0,1,0]
	v_pk_fma_f32 v[180:181], v[200:201], v[230:231], v[180:181] op_sel_hi:[1,0,1] neg_lo:[0,1,0] neg_hi:[0,1,0]
	ds_read_b128 v[198:201], v233 offset:4544
	v_pk_fma_f32 v[182:183], v[202:203], v[230:231], v[182:183] op_sel_hi:[1,0,1] neg_lo:[0,1,0] neg_hi:[0,1,0]
	v_pk_fma_f32 v[184:185], v[204:205], v[230:231], v[184:185] op_sel_hi:[1,0,1] neg_lo:[0,1,0] neg_hi:[0,1,0]
	ds_read_b128 v[202:205], v233 offset:4560
	s_waitcnt lgkmcnt(10)
	v_pk_fma_f32 v[186:187], v[206:207], v[230:231], v[186:187] op_sel_hi:[1,0,1] neg_lo:[0,1,0] neg_hi:[0,1,0]
	v_pk_fma_f32 v[188:189], v[208:209], v[230:231], v[188:189] op_sel_hi:[1,0,1] neg_lo:[0,1,0] neg_hi:[0,1,0]
	ds_read_b128 v[206:209], v233 offset:4576
	v_pk_fma_f32 v[190:191], v[226:227], v[230:231], v[190:191] op_sel_hi:[1,0,1] neg_lo:[0,1,0] neg_hi:[0,1,0]
	v_pk_fma_f32 v[192:193], v[228:229], v[230:231], v[192:193] op_sel_hi:[1,0,1] neg_lo:[0,1,0] neg_hi:[0,1,0]
	ds_read_b128 v[226:229], v233 offset:4592
	v_mov_b32_e32 v230, v122
	v_cvt_pk_bf16_f32 v232, v230, v230
	global_store_short v28, v232, s[0:1]
	s_add_u32 s0, s0, 0x400
	s_addc_u32 s1, s1, 0
	s_waitcnt lgkmcnt(10)
	v_pk_fma_f32 v[122:123], v[46:47], v[230:231], v[122:123] op_sel_hi:[1,0,1] neg_lo:[0,1,0] neg_hi:[0,1,0]
	v_pk_fma_f32 v[124:125], v[48:49], v[230:231], v[124:125] op_sel_hi:[1,0,1] neg_lo:[0,1,0] neg_hi:[0,1,0]
	ds_read_b128 v[46:49], v233 offset:4688
	v_pk_fma_f32 v[126:127], v[50:51], v[230:231], v[126:127] op_sel_hi:[1,0,1] neg_lo:[0,1,0] neg_hi:[0,1,0]
	v_pk_fma_f32 v[128:129], v[52:53], v[230:231], v[128:129] op_sel_hi:[1,0,1] neg_lo:[0,1,0] neg_hi:[0,1,0]
	ds_read_b128 v[50:53], v233 offset:4704
	s_waitcnt lgkmcnt(10)
	v_pk_fma_f32 v[130:131], v[54:55], v[230:231], v[130:131] op_sel_hi:[1,0,1] neg_lo:[0,1,0] neg_hi:[0,1,0]
	v_pk_fma_f32 v[132:133], v[56:57], v[230:231], v[132:133] op_sel_hi:[1,0,1] neg_lo:[0,1,0] neg_hi:[0,1,0]
	ds_read_b128 v[54:57], v233 offset:4720
	v_pk_fma_f32 v[134:135], v[58:59], v[230:231], v[134:135] op_sel_hi:[1,0,1] neg_lo:[0,1,0] neg_hi:[0,1,0]
	v_pk_fma_f32 v[136:137], v[60:61], v[230:231], v[136:137] op_sel_hi:[1,0,1] neg_lo:[0,1,0] neg_hi:[0,1,0]
	ds_read_b128 v[58:61], v233 offset:4736
	s_waitcnt lgkmcnt(10)
	v_pk_fma_f32 v[138:139], v[62:63], v[230:231], v[138:139] op_sel_hi:[1,0,1] neg_lo:[0,1,0] neg_hi:[0,1,0]
	v_pk_fma_f32 v[140:141], v[64:65], v[230:231], v[140:141] op_sel_hi:[1,0,1] neg_lo:[0,1,0] neg_hi:[0,1,0]
	ds_read_b128 v[62:65], v233 offset:4752
	v_pk_fma_f32 v[142:143], v[66:67], v[230:231], v[142:143] op_sel_hi:[1,0,1] neg_lo:[0,1,0] neg_hi:[0,1,0]
	v_pk_fma_f32 v[144:145], v[68:69], v[230:231], v[144:145] op_sel_hi:[1,0,1] neg_lo:[0,1,0] neg_hi:[0,1,0]
	ds_read_b128 v[66:69], v233 offset:4768
	s_waitcnt lgkmcnt(10)
	v_pk_fma_f32 v[146:147], v[70:71], v[230:231], v[146:147] op_sel_hi:[1,0,1] neg_lo:[0,1,0] neg_hi:[0,1,0]
	v_pk_fma_f32 v[148:149], v[72:73], v[230:231], v[148:149] op_sel_hi:[1,0,1] neg_lo:[0,1,0] neg_hi:[0,1,0]
	ds_read_b128 v[70:73], v233 offset:4784
	v_pk_fma_f32 v[150:151], v[194:195], v[230:231], v[150:151] op_sel_hi:[1,0,1] neg_lo:[0,1,0] neg_hi:[0,1,0]
	v_pk_fma_f32 v[152:153], v[196:197], v[230:231], v[152:153] op_sel_hi:[1,0,1] neg_lo:[0,1,0] neg_hi:[0,1,0]
	ds_read_b128 v[194:197], v233 offset:4800
	s_waitcnt lgkmcnt(10)
	v_pk_fma_f32 v[154:155], v[198:199], v[230:231], v[154:155] op_sel_hi:[1,0,1] neg_lo:[0,1,0] neg_hi:[0,1,0]
	v_pk_fma_f32 v[180:181], v[200:201], v[230:231], v[180:181] op_sel_hi:[1,0,1] neg_lo:[0,1,0] neg_hi:[0,1,0]
	ds_read_b128 v[198:201], v233 offset:4816
	v_pk_fma_f32 v[182:183], v[202:203], v[230:231], v[182:183] op_sel_hi:[1,0,1] neg_lo:[0,1,0] neg_hi:[0,1,0]
	v_pk_fma_f32 v[184:185], v[204:205], v[230:231], v[184:185] op_sel_hi:[1,0,1] neg_lo:[0,1,0] neg_hi:[0,1,0]
	ds_read_b128 v[202:205], v233 offset:4832
	s_waitcnt lgkmcnt(10)
	v_pk_fma_f32 v[186:187], v[206:207], v[230:231], v[186:187] op_sel_hi:[1,0,1] neg_lo:[0,1,0] neg_hi:[0,1,0]
	v_pk_fma_f32 v[188:189], v[208:209], v[230:231], v[188:189] op_sel_hi:[1,0,1] neg_lo:[0,1,0] neg_hi:[0,1,0]
	ds_read_b128 v[206:209], v233 offset:4848
	v_pk_fma_f32 v[190:191], v[226:227], v[230:231], v[190:191] op_sel_hi:[1,0,1] neg_lo:[0,1,0] neg_hi:[0,1,0]
	v_pk_fma_f32 v[192:193], v[228:229], v[230:231], v[192:193] op_sel_hi:[1,0,1] neg_lo:[0,1,0] neg_hi:[0,1,0]
	ds_read_b128 v[226:229], v233 offset:4864
	v_mov_b32_e32 v230, v123
	v_cvt_pk_bf16_f32 v232, v230, v230
	global_store_short v28, v232, s[0:1]
	s_add_u32 s0, s0, 0x400
	s_addc_u32 s1, s1, 0
	s_waitcnt lgkmcnt(10)
	v_pk_fma_f32 v[124:125], v[48:49], v[230:231], v[124:125] op_sel_hi:[1,0,1] neg_lo:[0,1,0] neg_hi:[0,1,0]
	ds_read_b128 v[46:49], v233 offset:4960
	v_pk_fma_f32 v[126:127], v[50:51], v[230:231], v[126:127] op_sel_hi:[1,0,1] neg_lo:[0,1,0] neg_hi:[0,1,0]
	v_pk_fma_f32 v[128:129], v[52:53], v[230:231], v[128:129] op_sel_hi:[1,0,1] neg_lo:[0,1,0] neg_hi:[0,1,0]
	ds_read_b128 v[50:53], v233 offset:4976
	s_waitcnt lgkmcnt(10)
	v_pk_fma_f32 v[130:131], v[54:55], v[230:231], v[130:131] op_sel_hi:[1,0,1] neg_lo:[0,1,0] neg_hi:[0,1,0]
	v_pk_fma_f32 v[132:133], v[56:57], v[230:231], v[132:133] op_sel_hi:[1,0,1] neg_lo:[0,1,0] neg_hi:[0,1,0]
	ds_read_b128 v[54:57], v233 offset:4992
	v_pk_fma_f32 v[134:135], v[58:59], v[230:231], v[134:135] op_sel_hi:[1,0,1] neg_lo:[0,1,0] neg_hi:[0,1,0]
	v_pk_fma_f32 v[136:137], v[60:61], v[230:231], v[136:137] op_sel_hi:[1,0,1] neg_lo:[0,1,0] neg_hi:[0,1,0]
	ds_read_b128 v[58:61], v233 offset:5008
	s_waitcnt lgkmcnt(10)
	v_pk_fma_f32 v[138:139], v[62:63], v[230:231], v[138:139] op_sel_hi:[1,0,1] neg_lo:[0,1,0] neg_hi:[0,1,0]
	v_pk_fma_f32 v[140:141], v[64:65], v[230:231], v[140:141] op_sel_hi:[1,0,1] neg_lo:[0,1,0] neg_hi:[0,1,0]
	ds_read_b128 v[62:65], v233 offset:5024
	v_pk_fma_f32 v[142:143], v[66:67], v[230:231], v[142:143] op_sel_hi:[1,0,1] neg_lo:[0,1,0] neg_hi:[0,1,0]
	v_pk_fma_f32 v[144:145], v[68:69], v[230:231], v[144:145] op_sel_hi:[1,0,1] neg_lo:[0,1,0] neg_hi:[0,1,0]
	ds_read_b128 v[66:69], v233 offset:5040
	s_waitcnt lgkmcnt(10)
	v_pk_fma_f32 v[146:147], v[70:71], v[230:231], v[146:147] op_sel_hi:[1,0,1] neg_lo:[0,1,0] neg_hi:[0,1,0]
	v_pk_fma_f32 v[148:149], v[72:73], v[230:231], v[148:149] op_sel_hi:[1,0,1] neg_lo:[0,1,0] neg_hi:[0,1,0]
	ds_read_b128 v[70:73], v233 offset:5056
	v_pk_fma_f32 v[150:151], v[194:195], v[230:231], v[150:151] op_sel_hi:[1,0,1] neg_lo:[0,1,0] neg_hi:[0,1,0]
	v_pk_fma_f32 v[152:153], v[196:197], v[230:231], v[152:153] op_sel_hi:[1,0,1] neg_lo:[0,1,0] neg_hi:[0,1,0]
	ds_read_b128 v[194:197], v233 offset:5072
	s_waitcnt lgkmcnt(10)
	v_pk_fma_f32 v[154:155], v[198:199], v[230:231], v[154:155] op_sel_hi:[1,0,1] neg_lo:[0,1,0] neg_hi:[0,1,0]
	v_pk_fma_f32 v[180:181], v[200:201], v[230:231], v[180:181] op_sel_hi:[1,0,1] neg_lo:[0,1,0] neg_hi:[0,1,0]
	ds_read_b128 v[198:201], v233 offset:5088
	v_pk_fma_f32 v[182:183], v[202:203], v[230:231], v[182:183] op_sel_hi:[1,0,1] neg_lo:[0,1,0] neg_hi:[0,1,0]
	v_pk_fma_f32 v[184:185], v[204:205], v[230:231], v[184:185] op_sel_hi:[1,0,1] neg_lo:[0,1,0] neg_hi:[0,1,0]
	ds_read_b128 v[202:205], v233 offset:5104
	s_waitcnt lgkmcnt(10)
	v_pk_fma_f32 v[186:187], v[206:207], v[230:231], v[186:187] op_sel_hi:[1,0,1] neg_lo:[0,1,0] neg_hi:[0,1,0]
	v_pk_fma_f32 v[188:189], v[208:209], v[230:231], v[188:189] op_sel_hi:[1,0,1] neg_lo:[0,1,0] neg_hi:[0,1,0]
	ds_read_b128 v[206:209], v233 offset:5120
	v_pk_fma_f32 v[190:191], v[226:227], v[230:231], v[190:191] op_sel_hi:[1,0,1] neg_lo:[0,1,0] neg_hi:[0,1,0]
	v_pk_fma_f32 v[192:193], v[228:229], v[230:231], v[192:193] op_sel_hi:[1,0,1] neg_lo:[0,1,0] neg_hi:[0,1,0]
	ds_read_b128 v[226:229], v233 offset:5136
	v_mov_b32_e32 v230, v124
	v_cvt_pk_bf16_f32 v232, v230, v230
	global_store_short v28, v232, s[0:1]
	s_add_u32 s0, s0, 0x400
	s_addc_u32 s1, s1, 0
	s_waitcnt lgkmcnt(10)
	v_pk_fma_f32 v[124:125], v[48:49], v[230:231], v[124:125] op_sel_hi:[1,0,1] neg_lo:[0,1,0] neg_hi:[0,1,0]
	v_pk_fma_f32 v[126:127], v[50:51], v[230:231], v[126:127] op_sel_hi:[1,0,1] neg_lo:[0,1,0] neg_hi:[0,1,0]
	v_pk_fma_f32 v[128:129], v[52:53], v[230:231], v[128:129] op_sel_hi:[1,0,1] neg_lo:[0,1,0] neg_hi:[0,1,0]
	ds_read_b128 v[50:53], v233 offset:5248
	s_waitcnt lgkmcnt(9)
	v_pk_fma_f32 v[130:131], v[54:55], v[230:231], v[130:131] op_sel_hi:[1,0,1] neg_lo:[0,1,0] neg_hi:[0,1,0]
	v_pk_fma_f32 v[132:133], v[56:57], v[230:231], v[132:133] op_sel_hi:[1,0,1] neg_lo:[0,1,0] neg_hi:[0,1,0]
	ds_read_b128 v[54:57], v233 offset:5264
	v_pk_fma_f32 v[134:135], v[58:59], v[230:231], v[134:135] op_sel_hi:[1,0,1] neg_lo:[0,1,0] neg_hi:[0,1,0]
	v_pk_fma_f32 v[136:137], v[60:61], v[230:231], v[136:137] op_sel_hi:[1,0,1] neg_lo:[0,1,0] neg_hi:[0,1,0]
	ds_read_b128 v[58:61], v233 offset:5280
	s_waitcnt lgkmcnt(9)
	v_pk_fma_f32 v[138:139], v[62:63], v[230:231], v[138:139] op_sel_hi:[1,0,1] neg_lo:[0,1,0] neg_hi:[0,1,0]
	v_pk_fma_f32 v[140:141], v[64:65], v[230:231], v[140:141] op_sel_hi:[1,0,1] neg_lo:[0,1,0] neg_hi:[0,1,0]
	ds_read_b128 v[62:65], v233 offset:5296
	v_pk_fma_f32 v[142:143], v[66:67], v[230:231], v[142:143] op_sel_hi:[1,0,1] neg_lo:[0,1,0] neg_hi:[0,1,0]
	v_pk_fma_f32 v[144:145], v[68:69], v[230:231], v[144:145] op_sel_hi:[1,0,1] neg_lo:[0,1,0] neg_hi:[0,1,0]
	ds_read_b128 v[66:69], v233 offset:5312
	s_waitcnt lgkmcnt(9)
	v_pk_fma_f32 v[146:147], v[70:71], v[230:231], v[146:147] op_sel_hi:[1,0,1] neg_lo:[0,1,0] neg_hi:[0,1,0]
	v_pk_fma_f32 v[148:149], v[72:73], v[230:231], v[148:149] op_sel_hi:[1,0,1] neg_lo:[0,1,0] neg_hi:[0,1,0]
	ds_read_b128 v[70:73], v233 offset:5328
	v_pk_fma_f32 v[150:151], v[194:195], v[230:231], v[150:151] op_sel_hi:[1,0,1] neg_lo:[0,1,0] neg_hi:[0,1,0]
	v_pk_fma_f32 v[152:153], v[196:197], v[230:231], v[152:153] op_sel_hi:[1,0,1] neg_lo:[0,1,0] neg_hi:[0,1,0]
	ds_read_b128 v[194:197], v233 offset:5344
	s_waitcnt lgkmcnt(9)
	v_pk_fma_f32 v[154:155], v[198:199], v[230:231], v[154:155] op_sel_hi:[1,0,1] neg_lo:[0,1,0] neg_hi:[0,1,0]
	v_pk_fma_f32 v[180:181], v[200:201], v[230:231], v[180:181] op_sel_hi:[1,0,1] neg_lo:[0,1,0] neg_hi:[0,1,0]
	ds_read_b128 v[198:201], v233 offset:5360
	v_pk_fma_f32 v[182:183], v[202:203], v[230:231], v[182:183] op_sel_hi:[1,0,1] neg_lo:[0,1,0] neg_hi:[0,1,0]
	v_pk_fma_f32 v[184:185], v[204:205], v[230:231], v[184:185] op_sel_hi:[1,0,1] neg_lo:[0,1,0] neg_hi:[0,1,0]
	ds_read_b128 v[202:205], v233 offset:5376
	s_waitcnt lgkmcnt(9)
	v_pk_fma_f32 v[186:187], v[206:207], v[230:231], v[186:187] op_sel_hi:[1,0,1] neg_lo:[0,1,0] neg_hi:[0,1,0]
	v_pk_fma_f32 v[188:189], v[208:209], v[230:231], v[188:189] op_sel_hi:[1,0,1] neg_lo:[0,1,0] neg_hi:[0,1,0]
	ds_read_b128 v[206:209], v233 offset:5392
	v_pk_fma_f32 v[190:191], v[226:227], v[230:231], v[190:191] op_sel_hi:[1,0,1] neg_lo:[0,1,0] neg_hi:[0,1,0]
	v_pk_fma_f32 v[192:193], v[228:229], v[230:231], v[192:193] op_sel_hi:[1,0,1] neg_lo:[0,1,0] neg_hi:[0,1,0]
	ds_read_b128 v[226:229], v233 offset:5408
	v_mov_b32_e32 v230, v125
	v_cvt_pk_bf16_f32 v232, v230, v230
	global_store_short v28, v232, s[0:1]
	s_add_u32 s0, s0, 0x400
	s_addc_u32 s1, s1, 0
	s_waitcnt lgkmcnt(9)
	v_pk_fma_f32 v[126:127], v[50:51], v[230:231], v[126:127] op_sel_hi:[1,0,1] neg_lo:[0,1,0] neg_hi:[0,1,0]
	v_pk_fma_f32 v[128:129], v[52:53], v[230:231], v[128:129] op_sel_hi:[1,0,1] neg_lo:[0,1,0] neg_hi:[0,1,0]
	ds_read_b128 v[50:53], v233 offset:5520
	v_pk_fma_f32 v[130:131], v[54:55], v[230:231], v[130:131] op_sel_hi:[1,0,1] neg_lo:[0,1,0] neg_hi:[0,1,0]
	v_pk_fma_f32 v[132:133], v[56:57], v[230:231], v[132:133] op_sel_hi:[1,0,1] neg_lo:[0,1,0] neg_hi:[0,1,0]
	ds_read_b128 v[54:57], v233 offset:5536
	s_waitcnt lgkmcnt(9)
	v_pk_fma_f32 v[134:135], v[58:59], v[230:231], v[134:135] op_sel_hi:[1,0,1] neg_lo:[0,1,0] neg_hi:[0,1,0]
	v_pk_fma_f32 v[136:137], v[60:61], v[230:231], v[136:137] op_sel_hi:[1,0,1] neg_lo:[0,1,0] neg_hi:[0,1,0]
	ds_read_b128 v[58:61], v233 offset:5552
	v_pk_fma_f32 v[138:139], v[62:63], v[230:231], v[138:139] op_sel_hi:[1,0,1] neg_lo:[0,1,0] neg_hi:[0,1,0]
	v_pk_fma_f32 v[140:141], v[64:65], v[230:231], v[140:141] op_sel_hi:[1,0,1] neg_lo:[0,1,0] neg_hi:[0,1,0]
	ds_read_b128 v[62:65], v233 offset:5568
	s_waitcnt lgkmcnt(9)
	v_pk_fma_f32 v[142:143], v[66:67], v[230:231], v[142:143] op_sel_hi:[1,0,1] neg_lo:[0,1,0] neg_hi:[0,1,0]
	v_pk_fma_f32 v[144:145], v[68:69], v[230:231], v[144:145] op_sel_hi:[1,0,1] neg_lo:[0,1,0] neg_hi:[0,1,0]
	ds_read_b128 v[66:69], v233 offset:5584
	v_pk_fma_f32 v[146:147], v[70:71], v[230:231], v[146:147] op_sel_hi:[1,0,1] neg_lo:[0,1,0] neg_hi:[0,1,0]
	v_pk_fma_f32 v[148:149], v[72:73], v[230:231], v[148:149] op_sel_hi:[1,0,1] neg_lo:[0,1,0] neg_hi:[0,1,0]
	ds_read_b128 v[70:73], v233 offset:5600
	s_waitcnt lgkmcnt(9)
	v_pk_fma_f32 v[150:151], v[194:195], v[230:231], v[150:151] op_sel_hi:[1,0,1] neg_lo:[0,1,0] neg_hi:[0,1,0]
	v_pk_fma_f32 v[152:153], v[196:197], v[230:231], v[152:153] op_sel_hi:[1,0,1] neg_lo:[0,1,0] neg_hi:[0,1,0]
	ds_read_b128 v[194:197], v233 offset:5616
	v_pk_fma_f32 v[154:155], v[198:199], v[230:231], v[154:155] op_sel_hi:[1,0,1] neg_lo:[0,1,0] neg_hi:[0,1,0]
	v_pk_fma_f32 v[180:181], v[200:201], v[230:231], v[180:181] op_sel_hi:[1,0,1] neg_lo:[0,1,0] neg_hi:[0,1,0]
	ds_read_b128 v[198:201], v233 offset:5632
	s_waitcnt lgkmcnt(9)
	v_pk_fma_f32 v[182:183], v[202:203], v[230:231], v[182:183] op_sel_hi:[1,0,1] neg_lo:[0,1,0] neg_hi:[0,1,0]
	v_pk_fma_f32 v[184:185], v[204:205], v[230:231], v[184:185] op_sel_hi:[1,0,1] neg_lo:[0,1,0] neg_hi:[0,1,0]
	ds_read_b128 v[202:205], v233 offset:5648
	v_pk_fma_f32 v[186:187], v[206:207], v[230:231], v[186:187] op_sel_hi:[1,0,1] neg_lo:[0,1,0] neg_hi:[0,1,0]
	v_pk_fma_f32 v[188:189], v[208:209], v[230:231], v[188:189] op_sel_hi:[1,0,1] neg_lo:[0,1,0] neg_hi:[0,1,0]
	ds_read_b128 v[206:209], v233 offset:5664
	s_waitcnt lgkmcnt(10)
	v_pk_fma_f32 v[190:191], v[226:227], v[230:231], v[190:191] op_sel_hi:[1,0,1] neg_lo:[0,1,0] neg_hi:[0,1,0]
	v_pk_fma_f32 v[192:193], v[228:229], v[230:231], v[192:193] op_sel_hi:[1,0,1] neg_lo:[0,1,0] neg_hi:[0,1,0]
	ds_read_b128 v[226:229], v233 offset:5680
	v_mov_b32_e32 v230, v126
	v_cvt_pk_bf16_f32 v232, v230, v230
	global_store_short v28, v232, s[0:1]
	s_add_u32 s0, s0, 0x400
	s_addc_u32 s1, s1, 0
	s_waitcnt lgkmcnt(9)
	v_pk_fma_f32 v[126:127], v[50:51], v[230:231], v[126:127] op_sel_hi:[1,0,1] neg_lo:[0,1,0] neg_hi:[0,1,0]
	v_pk_fma_f32 v[128:129], v[52:53], v[230:231], v[128:129] op_sel_hi:[1,0,1] neg_lo:[0,1,0] neg_hi:[0,1,0]
	ds_read_b128 v[50:53], v233 offset:5792
	v_pk_fma_f32 v[130:131], v[54:55], v[230:231], v[130:131] op_sel_hi:[1,0,1] neg_lo:[0,1,0] neg_hi:[0,1,0]
	v_pk_fma_f32 v[132:133], v[56:57], v[230:231], v[132:133] op_sel_hi:[1,0,1] neg_lo:[0,1,0] neg_hi:[0,1,0]
	ds_read_b128 v[54:57], v233 offset:5808
	s_waitcnt lgkmcnt(9)
	v_pk_fma_f32 v[134:135], v[58:59], v[230:231], v[134:135] op_sel_hi:[1,0,1] neg_lo:[0,1,0] neg_hi:[0,1,0]
	v_pk_fma_f32 v[136:137], v[60:61], v[230:231], v[136:137] op_sel_hi:[1,0,1] neg_lo:[0,1,0] neg_hi:[0,1,0]
	ds_read_b128 v[58:61], v233 offset:5824
	v_pk_fma_f32 v[138:139], v[62:63], v[230:231], v[138:139] op_sel_hi:[1,0,1] neg_lo:[0,1,0] neg_hi:[0,1,0]
	v_pk_fma_f32 v[140:141], v[64:65], v[230:231], v[140:141] op_sel_hi:[1,0,1] neg_lo:[0,1,0] neg_hi:[0,1,0]
	ds_read_b128 v[62:65], v233 offset:5840
	s_waitcnt lgkmcnt(9)
	v_pk_fma_f32 v[142:143], v[66:67], v[230:231], v[142:143] op_sel_hi:[1,0,1] neg_lo:[0,1,0] neg_hi:[0,1,0]
	v_pk_fma_f32 v[144:145], v[68:69], v[230:231], v[144:145] op_sel_hi:[1,0,1] neg_lo:[0,1,0] neg_hi:[0,1,0]
	ds_read_b128 v[66:69], v233 offset:5856
	v_pk_fma_f32 v[146:147], v[70:71], v[230:231], v[146:147] op_sel_hi:[1,0,1] neg_lo:[0,1,0] neg_hi:[0,1,0]
	v_pk_fma_f32 v[148:149], v[72:73], v[230:231], v[148:149] op_sel_hi:[1,0,1] neg_lo:[0,1,0] neg_hi:[0,1,0]
	ds_read_b128 v[70:73], v233 offset:5872
	s_waitcnt lgkmcnt(9)
	v_pk_fma_f32 v[150:151], v[194:195], v[230:231], v[150:151] op_sel_hi:[1,0,1] neg_lo:[0,1,0] neg_hi:[0,1,0]
	v_pk_fma_f32 v[152:153], v[196:197], v[230:231], v[152:153] op_sel_hi:[1,0,1] neg_lo:[0,1,0] neg_hi:[0,1,0]
	ds_read_b128 v[194:197], v233 offset:5888
	v_pk_fma_f32 v[154:155], v[198:199], v[230:231], v[154:155] op_sel_hi:[1,0,1] neg_lo:[0,1,0] neg_hi:[0,1,0]
	v_pk_fma_f32 v[180:181], v[200:201], v[230:231], v[180:181] op_sel_hi:[1,0,1] neg_lo:[0,1,0] neg_hi:[0,1,0]
	ds_read_b128 v[198:201], v233 offset:5904
	s_waitcnt lgkmcnt(9)
	v_pk_fma_f32 v[182:183], v[202:203], v[230:231], v[182:183] op_sel_hi:[1,0,1] neg_lo:[0,1,0] neg_hi:[0,1,0]
	v_pk_fma_f32 v[184:185], v[204:205], v[230:231], v[184:185] op_sel_hi:[1,0,1] neg_lo:[0,1,0] neg_hi:[0,1,0]
	ds_read_b128 v[202:205], v233 offset:5920
	v_pk_fma_f32 v[186:187], v[206:207], v[230:231], v[186:187] op_sel_hi:[1,0,1] neg_lo:[0,1,0] neg_hi:[0,1,0]
	v_pk_fma_f32 v[188:189], v[208:209], v[230:231], v[188:189] op_sel_hi:[1,0,1] neg_lo:[0,1,0] neg_hi:[0,1,0]
	ds_read_b128 v[206:209], v233 offset:5936
	s_waitcnt lgkmcnt(10)
	v_pk_fma_f32 v[190:191], v[226:227], v[230:231], v[190:191] op_sel_hi:[1,0,1] neg_lo:[0,1,0] neg_hi:[0,1,0]
	v_pk_fma_f32 v[192:193], v[228:229], v[230:231], v[192:193] op_sel_hi:[1,0,1] neg_lo:[0,1,0] neg_hi:[0,1,0]
	ds_read_b128 v[226:229], v233 offset:5952
	v_mov_b32_e32 v230, v127
	v_cvt_pk_bf16_f32 v232, v230, v230
	global_store_short v28, v232, s[0:1]
	s_add_u32 s0, s0, 0x400
	s_addc_u32 s1, s1, 0
	s_waitcnt lgkmcnt(9)
	v_pk_fma_f32 v[128:129], v[52:53], v[230:231], v[128:129] op_sel_hi:[1,0,1] neg_lo:[0,1,0] neg_hi:[0,1,0]
	ds_read_b128 v[50:53], v233 offset:6064
	v_pk_fma_f32 v[130:131], v[54:55], v[230:231], v[130:131] op_sel_hi:[1,0,1] neg_lo:[0,1,0] neg_hi:[0,1,0]
	v_pk_fma_f32 v[132:133], v[56:57], v[230:231], v[132:133] op_sel_hi:[1,0,1] neg_lo:[0,1,0] neg_hi:[0,1,0]
	ds_read_b128 v[54:57], v233 offset:6080
	s_waitcnt lgkmcnt(9)
	v_pk_fma_f32 v[134:135], v[58:59], v[230:231], v[134:135] op_sel_hi:[1,0,1] neg_lo:[0,1,0] neg_hi:[0,1,0]
	v_pk_fma_f32 v[136:137], v[60:61], v[230:231], v[136:137] op_sel_hi:[1,0,1] neg_lo:[0,1,0] neg_hi:[0,1,0]
	ds_read_b128 v[58:61], v233 offset:6096
	v_pk_fma_f32 v[138:139], v[62:63], v[230:231], v[138:139] op_sel_hi:[1,0,1] neg_lo:[0,1,0] neg_hi:[0,1,0]
	v_pk_fma_f32 v[140:141], v[64:65], v[230:231], v[140:141] op_sel_hi:[1,0,1] neg_lo:[0,1,0] neg_hi:[0,1,0]
	ds_read_b128 v[62:65], v233 offset:6112
	s_waitcnt lgkmcnt(9)
	v_pk_fma_f32 v[142:143], v[66:67], v[230:231], v[142:143] op_sel_hi:[1,0,1] neg_lo:[0,1,0] neg_hi:[0,1,0]
	v_pk_fma_f32 v[144:145], v[68:69], v[230:231], v[144:145] op_sel_hi:[1,0,1] neg_lo:[0,1,0] neg_hi:[0,1,0]
	ds_read_b128 v[66:69], v233 offset:6128
	v_pk_fma_f32 v[146:147], v[70:71], v[230:231], v[146:147] op_sel_hi:[1,0,1] neg_lo:[0,1,0] neg_hi:[0,1,0]
	v_pk_fma_f32 v[148:149], v[72:73], v[230:231], v[148:149] op_sel_hi:[1,0,1] neg_lo:[0,1,0] neg_hi:[0,1,0]
	ds_read_b128 v[70:73], v233 offset:6144
	s_waitcnt lgkmcnt(9)
	v_pk_fma_f32 v[150:151], v[194:195], v[230:231], v[150:151] op_sel_hi:[1,0,1] neg_lo:[0,1,0] neg_hi:[0,1,0]
	v_pk_fma_f32 v[152:153], v[196:197], v[230:231], v[152:153] op_sel_hi:[1,0,1] neg_lo:[0,1,0] neg_hi:[0,1,0]
	ds_read_b128 v[194:197], v233 offset:6160
	v_pk_fma_f32 v[154:155], v[198:199], v[230:231], v[154:155] op_sel_hi:[1,0,1] neg_lo:[0,1,0] neg_hi:[0,1,0]
	v_pk_fma_f32 v[180:181], v[200:201], v[230:231], v[180:181] op_sel_hi:[1,0,1] neg_lo:[0,1,0] neg_hi:[0,1,0]
	ds_read_b128 v[198:201], v233 offset:6176
	s_waitcnt lgkmcnt(9)
	v_pk_fma_f32 v[182:183], v[202:203], v[230:231], v[182:183] op_sel_hi:[1,0,1] neg_lo:[0,1,0] neg_hi:[0,1,0]
	v_pk_fma_f32 v[184:185], v[204:205], v[230:231], v[184:185] op_sel_hi:[1,0,1] neg_lo:[0,1,0] neg_hi:[0,1,0]
	ds_read_b128 v[202:205], v233 offset:6192
	v_pk_fma_f32 v[186:187], v[206:207], v[230:231], v[186:187] op_sel_hi:[1,0,1] neg_lo:[0,1,0] neg_hi:[0,1,0]
	v_pk_fma_f32 v[188:189], v[208:209], v[230:231], v[188:189] op_sel_hi:[1,0,1] neg_lo:[0,1,0] neg_hi:[0,1,0]
	ds_read_b128 v[206:209], v233 offset:6208
	s_waitcnt lgkmcnt(10)
	v_pk_fma_f32 v[190:191], v[226:227], v[230:231], v[190:191] op_sel_hi:[1,0,1] neg_lo:[0,1,0] neg_hi:[0,1,0]
	v_pk_fma_f32 v[192:193], v[228:229], v[230:231], v[192:193] op_sel_hi:[1,0,1] neg_lo:[0,1,0] neg_hi:[0,1,0]
	ds_read_b128 v[226:229], v233 offset:6224
	v_mov_b32_e32 v230, v128
	v_cvt_pk_bf16_f32 v232, v230, v230
	global_store_short v28, v232, s[0:1]
	s_add_u32 s0, s0, 0x400
	s_addc_u32 s1, s1, 0
	s_waitcnt lgkmcnt(9)
	v_pk_fma_f32 v[128:129], v[52:53], v[230:231], v[128:129] op_sel_hi:[1,0,1] neg_lo:[0,1,0] neg_hi:[0,1,0]
	v_pk_fma_f32 v[130:131], v[54:55], v[230:231], v[130:131] op_sel_hi:[1,0,1] neg_lo:[0,1,0] neg_hi:[0,1,0]
	v_pk_fma_f32 v[132:133], v[56:57], v[230:231], v[132:133] op_sel_hi:[1,0,1] neg_lo:[0,1,0] neg_hi:[0,1,0]
	ds_read_b128 v[54:57], v233 offset:6352
	s_waitcnt lgkmcnt(8)
	v_pk_fma_f32 v[134:135], v[58:59], v[230:231], v[134:135] op_sel_hi:[1,0,1] neg_lo:[0,1,0] neg_hi:[0,1,0]
	v_pk_fma_f32 v[136:137], v[60:61], v[230:231], v[136:137] op_sel_hi:[1,0,1] neg_lo:[0,1,0] neg_hi:[0,1,0]
	ds_read_b128 v[58:61], v233 offset:6368
	v_pk_fma_f32 v[138:139], v[62:63], v[230:231], v[138:139] op_sel_hi:[1,0,1] neg_lo:[0,1,0] neg_hi:[0,1,0]
	v_pk_fma_f32 v[140:141], v[64:65], v[230:231], v[140:141] op_sel_hi:[1,0,1] neg_lo:[0,1,0] neg_hi:[0,1,0]
	ds_read_b128 v[62:65], v233 offset:6384
	s_waitcnt lgkmcnt(8)
	v_pk_fma_f32 v[142:143], v[66:67], v[230:231], v[142:143] op_sel_hi:[1,0,1] neg_lo:[0,1,0] neg_hi:[0,1,0]
	v_pk_fma_f32 v[144:145], v[68:69], v[230:231], v[144:145] op_sel_hi:[1,0,1] neg_lo:[0,1,0] neg_hi:[0,1,0]
	ds_read_b128 v[66:69], v233 offset:6400
	v_pk_fma_f32 v[146:147], v[70:71], v[230:231], v[146:147] op_sel_hi:[1,0,1] neg_lo:[0,1,0] neg_hi:[0,1,0]
	v_pk_fma_f32 v[148:149], v[72:73], v[230:231], v[148:149] op_sel_hi:[1,0,1] neg_lo:[0,1,0] neg_hi:[0,1,0]
	ds_read_b128 v[70:73], v233 offset:6416
	s_waitcnt lgkmcnt(8)
	v_pk_fma_f32 v[150:151], v[194:195], v[230:231], v[150:151] op_sel_hi:[1,0,1] neg_lo:[0,1,0] neg_hi:[0,1,0]
	v_pk_fma_f32 v[152:153], v[196:197], v[230:231], v[152:153] op_sel_hi:[1,0,1] neg_lo:[0,1,0] neg_hi:[0,1,0]
	ds_read_b128 v[194:197], v233 offset:6432
	v_pk_fma_f32 v[154:155], v[198:199], v[230:231], v[154:155] op_sel_hi:[1,0,1] neg_lo:[0,1,0] neg_hi:[0,1,0]
	v_pk_fma_f32 v[180:181], v[200:201], v[230:231], v[180:181] op_sel_hi:[1,0,1] neg_lo:[0,1,0] neg_hi:[0,1,0]
	ds_read_b128 v[198:201], v233 offset:6448
	s_waitcnt lgkmcnt(8)
	v_pk_fma_f32 v[182:183], v[202:203], v[230:231], v[182:183] op_sel_hi:[1,0,1] neg_lo:[0,1,0] neg_hi:[0,1,0]
	v_pk_fma_f32 v[184:185], v[204:205], v[230:231], v[184:185] op_sel_hi:[1,0,1] neg_lo:[0,1,0] neg_hi:[0,1,0]
	ds_read_b128 v[202:205], v233 offset:6464
	v_pk_fma_f32 v[186:187], v[206:207], v[230:231], v[186:187] op_sel_hi:[1,0,1] neg_lo:[0,1,0] neg_hi:[0,1,0]
	v_pk_fma_f32 v[188:189], v[208:209], v[230:231], v[188:189] op_sel_hi:[1,0,1] neg_lo:[0,1,0] neg_hi:[0,1,0]
	ds_read_b128 v[206:209], v233 offset:6480
	s_waitcnt lgkmcnt(9)
	v_pk_fma_f32 v[190:191], v[226:227], v[230:231], v[190:191] op_sel_hi:[1,0,1] neg_lo:[0,1,0] neg_hi:[0,1,0]
	v_pk_fma_f32 v[192:193], v[228:229], v[230:231], v[192:193] op_sel_hi:[1,0,1] neg_lo:[0,1,0] neg_hi:[0,1,0]
	ds_read_b128 v[226:229], v233 offset:6496
	v_mov_b32_e32 v230, v129
	v_cvt_pk_bf16_f32 v232, v230, v230
	global_store_short v28, v232, s[0:1]
	s_add_u32 s0, s0, 0x400
	s_addc_u32 s1, s1, 0
	s_waitcnt lgkmcnt(8)
	v_pk_fma_f32 v[130:131], v[54:55], v[230:231], v[130:131] op_sel_hi:[1,0,1] neg_lo:[0,1,0] neg_hi:[0,1,0]
	v_pk_fma_f32 v[132:133], v[56:57], v[230:231], v[132:133] op_sel_hi:[1,0,1] neg_lo:[0,1,0] neg_hi:[0,1,0]
	ds_read_b128 v[54:57], v233 offset:6624
	v_pk_fma_f32 v[134:135], v[58:59], v[230:231], v[134:135] op_sel_hi:[1,0,1] neg_lo:[0,1,0] neg_hi:[0,1,0]
	v_pk_fma_f32 v[136:137], v[60:61], v[230:231], v[136:137] op_sel_hi:[1,0,1] neg_lo:[0,1,0] neg_hi:[0,1,0]
	ds_read_b128 v[58:61], v233 offset:6640
	s_waitcnt lgkmcnt(8)
	v_pk_fma_f32 v[138:139], v[62:63], v[230:231], v[138:139] op_sel_hi:[1,0,1] neg_lo:[0,1,0] neg_hi:[0,1,0]
	v_pk_fma_f32 v[140:141], v[64:65], v[230:231], v[140:141] op_sel_hi:[1,0,1] neg_lo:[0,1,0] neg_hi:[0,1,0]
	ds_read_b128 v[62:65], v233 offset:6656
	v_pk_fma_f32 v[142:143], v[66:67], v[230:231], v[142:143] op_sel_hi:[1,0,1] neg_lo:[0,1,0] neg_hi:[0,1,0]
	v_pk_fma_f32 v[144:145], v[68:69], v[230:231], v[144:145] op_sel_hi:[1,0,1] neg_lo:[0,1,0] neg_hi:[0,1,0]
	ds_read_b128 v[66:69], v233 offset:6672
	s_waitcnt lgkmcnt(8)
	v_pk_fma_f32 v[146:147], v[70:71], v[230:231], v[146:147] op_sel_hi:[1,0,1] neg_lo:[0,1,0] neg_hi:[0,1,0]
	v_pk_fma_f32 v[148:149], v[72:73], v[230:231], v[148:149] op_sel_hi:[1,0,1] neg_lo:[0,1,0] neg_hi:[0,1,0]
	ds_read_b128 v[70:73], v233 offset:6688
	v_pk_fma_f32 v[150:151], v[194:195], v[230:231], v[150:151] op_sel_hi:[1,0,1] neg_lo:[0,1,0] neg_hi:[0,1,0]
	v_pk_fma_f32 v[152:153], v[196:197], v[230:231], v[152:153] op_sel_hi:[1,0,1] neg_lo:[0,1,0] neg_hi:[0,1,0]
	ds_read_b128 v[194:197], v233 offset:6704
	s_waitcnt lgkmcnt(8)
	v_pk_fma_f32 v[154:155], v[198:199], v[230:231], v[154:155] op_sel_hi:[1,0,1] neg_lo:[0,1,0] neg_hi:[0,1,0]
	v_pk_fma_f32 v[180:181], v[200:201], v[230:231], v[180:181] op_sel_hi:[1,0,1] neg_lo:[0,1,0] neg_hi:[0,1,0]
	ds_read_b128 v[198:201], v233 offset:6720
	v_pk_fma_f32 v[182:183], v[202:203], v[230:231], v[182:183] op_sel_hi:[1,0,1] neg_lo:[0,1,0] neg_hi:[0,1,0]
	v_pk_fma_f32 v[184:185], v[204:205], v[230:231], v[184:185] op_sel_hi:[1,0,1] neg_lo:[0,1,0] neg_hi:[0,1,0]
	ds_read_b128 v[202:205], v233 offset:6736
	s_waitcnt lgkmcnt(8)
	v_pk_fma_f32 v[186:187], v[206:207], v[230:231], v[186:187] op_sel_hi:[1,0,1] neg_lo:[0,1,0] neg_hi:[0,1,0]
	v_pk_fma_f32 v[188:189], v[208:209], v[230:231], v[188:189] op_sel_hi:[1,0,1] neg_lo:[0,1,0] neg_hi:[0,1,0]
	ds_read_b128 v[206:209], v233 offset:6752
	v_pk_fma_f32 v[190:191], v[226:227], v[230:231], v[190:191] op_sel_hi:[1,0,1] neg_lo:[0,1,0] neg_hi:[0,1,0]
	v_pk_fma_f32 v[192:193], v[228:229], v[230:231], v[192:193] op_sel_hi:[1,0,1] neg_lo:[0,1,0] neg_hi:[0,1,0]
	ds_read_b128 v[226:229], v233 offset:6768
	v_mov_b32_e32 v230, v130
	v_cvt_pk_bf16_f32 v232, v230, v230
	global_store_short v28, v232, s[0:1]
	s_add_u32 s0, s0, 0x400
	s_addc_u32 s1, s1, 0
	s_waitcnt lgkmcnt(8)
	v_pk_fma_f32 v[130:131], v[54:55], v[230:231], v[130:131] op_sel_hi:[1,0,1] neg_lo:[0,1,0] neg_hi:[0,1,0]
	v_pk_fma_f32 v[132:133], v[56:57], v[230:231], v[132:133] op_sel_hi:[1,0,1] neg_lo:[0,1,0] neg_hi:[0,1,0]
	ds_read_b128 v[54:57], v233 offset:6896
	v_pk_fma_f32 v[134:135], v[58:59], v[230:231], v[134:135] op_sel_hi:[1,0,1] neg_lo:[0,1,0] neg_hi:[0,1,0]
	v_pk_fma_f32 v[136:137], v[60:61], v[230:231], v[136:137] op_sel_hi:[1,0,1] neg_lo:[0,1,0] neg_hi:[0,1,0]
	ds_read_b128 v[58:61], v233 offset:6912
	s_waitcnt lgkmcnt(8)
	v_pk_fma_f32 v[138:139], v[62:63], v[230:231], v[138:139] op_sel_hi:[1,0,1] neg_lo:[0,1,0] neg_hi:[0,1,0]
	v_pk_fma_f32 v[140:141], v[64:65], v[230:231], v[140:141] op_sel_hi:[1,0,1] neg_lo:[0,1,0] neg_hi:[0,1,0]
	ds_read_b128 v[62:65], v233 offset:6928
	v_pk_fma_f32 v[142:143], v[66:67], v[230:231], v[142:143] op_sel_hi:[1,0,1] neg_lo:[0,1,0] neg_hi:[0,1,0]
	v_pk_fma_f32 v[144:145], v[68:69], v[230:231], v[144:145] op_sel_hi:[1,0,1] neg_lo:[0,1,0] neg_hi:[0,1,0]
	ds_read_b128 v[66:69], v233 offset:6944
	s_waitcnt lgkmcnt(8)
	v_pk_fma_f32 v[146:147], v[70:71], v[230:231], v[146:147] op_sel_hi:[1,0,1] neg_lo:[0,1,0] neg_hi:[0,1,0]
	v_pk_fma_f32 v[148:149], v[72:73], v[230:231], v[148:149] op_sel_hi:[1,0,1] neg_lo:[0,1,0] neg_hi:[0,1,0]
	ds_read_b128 v[70:73], v233 offset:6960
	v_pk_fma_f32 v[150:151], v[194:195], v[230:231], v[150:151] op_sel_hi:[1,0,1] neg_lo:[0,1,0] neg_hi:[0,1,0]
	v_pk_fma_f32 v[152:153], v[196:197], v[230:231], v[152:153] op_sel_hi:[1,0,1] neg_lo:[0,1,0] neg_hi:[0,1,0]
	ds_read_b128 v[194:197], v233 offset:6976
	s_waitcnt lgkmcnt(8)
	v_pk_fma_f32 v[154:155], v[198:199], v[230:231], v[154:155] op_sel_hi:[1,0,1] neg_lo:[0,1,0] neg_hi:[0,1,0]
	v_pk_fma_f32 v[180:181], v[200:201], v[230:231], v[180:181] op_sel_hi:[1,0,1] neg_lo:[0,1,0] neg_hi:[0,1,0]
	ds_read_b128 v[198:201], v233 offset:6992
	v_pk_fma_f32 v[182:183], v[202:203], v[230:231], v[182:183] op_sel_hi:[1,0,1] neg_lo:[0,1,0] neg_hi:[0,1,0]
	v_pk_fma_f32 v[184:185], v[204:205], v[230:231], v[184:185] op_sel_hi:[1,0,1] neg_lo:[0,1,0] neg_hi:[0,1,0]
	ds_read_b128 v[202:205], v233 offset:7008
	s_waitcnt lgkmcnt(8)
	v_pk_fma_f32 v[186:187], v[206:207], v[230:231], v[186:187] op_sel_hi:[1,0,1] neg_lo:[0,1,0] neg_hi:[0,1,0]
	v_pk_fma_f32 v[188:189], v[208:209], v[230:231], v[188:189] op_sel_hi:[1,0,1] neg_lo:[0,1,0] neg_hi:[0,1,0]
	ds_read_b128 v[206:209], v233 offset:7024
	v_pk_fma_f32 v[190:191], v[226:227], v[230:231], v[190:191] op_sel_hi:[1,0,1] neg_lo:[0,1,0] neg_hi:[0,1,0]
	v_pk_fma_f32 v[192:193], v[228:229], v[230:231], v[192:193] op_sel_hi:[1,0,1] neg_lo:[0,1,0] neg_hi:[0,1,0]
	ds_read_b128 v[226:229], v233 offset:7040
	v_mov_b32_e32 v230, v131
	v_cvt_pk_bf16_f32 v232, v230, v230
	global_store_short v28, v232, s[0:1]
	s_add_u32 s0, s0, 0x400
	s_addc_u32 s1, s1, 0
	s_waitcnt lgkmcnt(8)
	v_pk_fma_f32 v[132:133], v[56:57], v[230:231], v[132:133] op_sel_hi:[1,0,1] neg_lo:[0,1,0] neg_hi:[0,1,0]
	ds_read_b128 v[54:57], v233 offset:7168
	v_pk_fma_f32 v[134:135], v[58:59], v[230:231], v[134:135] op_sel_hi:[1,0,1] neg_lo:[0,1,0] neg_hi:[0,1,0]
	v_pk_fma_f32 v[136:137], v[60:61], v[230:231], v[136:137] op_sel_hi:[1,0,1] neg_lo:[0,1,0] neg_hi:[0,1,0]
	ds_read_b128 v[58:61], v233 offset:7184
	s_waitcnt lgkmcnt(8)
	v_pk_fma_f32 v[138:139], v[62:63], v[230:231], v[138:139] op_sel_hi:[1,0,1] neg_lo:[0,1,0] neg_hi:[0,1,0]
	v_pk_fma_f32 v[140:141], v[64:65], v[230:231], v[140:141] op_sel_hi:[1,0,1] neg_lo:[0,1,0] neg_hi:[0,1,0]
	ds_read_b128 v[62:65], v233 offset:7200
	v_pk_fma_f32 v[142:143], v[66:67], v[230:231], v[142:143] op_sel_hi:[1,0,1] neg_lo:[0,1,0] neg_hi:[0,1,0]
	v_pk_fma_f32 v[144:145], v[68:69], v[230:231], v[144:145] op_sel_hi:[1,0,1] neg_lo:[0,1,0] neg_hi:[0,1,0]
	ds_read_b128 v[66:69], v233 offset:7216
	s_waitcnt lgkmcnt(8)
	v_pk_fma_f32 v[146:147], v[70:71], v[230:231], v[146:147] op_sel_hi:[1,0,1] neg_lo:[0,1,0] neg_hi:[0,1,0]
	v_pk_fma_f32 v[148:149], v[72:73], v[230:231], v[148:149] op_sel_hi:[1,0,1] neg_lo:[0,1,0] neg_hi:[0,1,0]
	ds_read_b128 v[70:73], v233 offset:7232
	v_pk_fma_f32 v[150:151], v[194:195], v[230:231], v[150:151] op_sel_hi:[1,0,1] neg_lo:[0,1,0] neg_hi:[0,1,0]
	v_pk_fma_f32 v[152:153], v[196:197], v[230:231], v[152:153] op_sel_hi:[1,0,1] neg_lo:[0,1,0] neg_hi:[0,1,0]
	ds_read_b128 v[194:197], v233 offset:7248
	s_waitcnt lgkmcnt(8)
	v_pk_fma_f32 v[154:155], v[198:199], v[230:231], v[154:155] op_sel_hi:[1,0,1] neg_lo:[0,1,0] neg_hi:[0,1,0]
	v_pk_fma_f32 v[180:181], v[200:201], v[230:231], v[180:181] op_sel_hi:[1,0,1] neg_lo:[0,1,0] neg_hi:[0,1,0]
	ds_read_b128 v[198:201], v233 offset:7264
	v_pk_fma_f32 v[182:183], v[202:203], v[230:231], v[182:183] op_sel_hi:[1,0,1] neg_lo:[0,1,0] neg_hi:[0,1,0]
	v_pk_fma_f32 v[184:185], v[204:205], v[230:231], v[184:185] op_sel_hi:[1,0,1] neg_lo:[0,1,0] neg_hi:[0,1,0]
	ds_read_b128 v[202:205], v233 offset:7280
	s_waitcnt lgkmcnt(8)
	v_pk_fma_f32 v[186:187], v[206:207], v[230:231], v[186:187] op_sel_hi:[1,0,1] neg_lo:[0,1,0] neg_hi:[0,1,0]
	v_pk_fma_f32 v[188:189], v[208:209], v[230:231], v[188:189] op_sel_hi:[1,0,1] neg_lo:[0,1,0] neg_hi:[0,1,0]
	ds_read_b128 v[206:209], v233 offset:7296
	v_pk_fma_f32 v[190:191], v[226:227], v[230:231], v[190:191] op_sel_hi:[1,0,1] neg_lo:[0,1,0] neg_hi:[0,1,0]
	v_pk_fma_f32 v[192:193], v[228:229], v[230:231], v[192:193] op_sel_hi:[1,0,1] neg_lo:[0,1,0] neg_hi:[0,1,0]
	ds_read_b128 v[226:229], v233 offset:7312
	v_mov_b32_e32 v230, v132
	v_cvt_pk_bf16_f32 v232, v230, v230
	global_store_short v28, v232, s[0:1]
	s_add_u32 s0, s0, 0x400
	s_addc_u32 s1, s1, 0
	s_waitcnt lgkmcnt(8)
	v_pk_fma_f32 v[132:133], v[56:57], v[230:231], v[132:133] op_sel_hi:[1,0,1] neg_lo:[0,1,0] neg_hi:[0,1,0]
	v_pk_fma_f32 v[134:135], v[58:59], v[230:231], v[134:135] op_sel_hi:[1,0,1] neg_lo:[0,1,0] neg_hi:[0,1,0]
	v_pk_fma_f32 v[136:137], v[60:61], v[230:231], v[136:137] op_sel_hi:[1,0,1] neg_lo:[0,1,0] neg_hi:[0,1,0]
	ds_read_b128 v[58:61], v233 offset:7456
	s_waitcnt lgkmcnt(7)
	v_pk_fma_f32 v[138:139], v[62:63], v[230:231], v[138:139] op_sel_hi:[1,0,1] neg_lo:[0,1,0] neg_hi:[0,1,0]
	v_pk_fma_f32 v[140:141], v[64:65], v[230:231], v[140:141] op_sel_hi:[1,0,1] neg_lo:[0,1,0] neg_hi:[0,1,0]
	ds_read_b128 v[62:65], v233 offset:7472
	v_pk_fma_f32 v[142:143], v[66:67], v[230:231], v[142:143] op_sel_hi:[1,0,1] neg_lo:[0,1,0] neg_hi:[0,1,0]
	v_pk_fma_f32 v[144:145], v[68:69], v[230:231], v[144:145] op_sel_hi:[1,0,1] neg_lo:[0,1,0] neg_hi:[0,1,0]
	ds_read_b128 v[66:69], v233 offset:7488
	s_waitcnt lgkmcnt(7)
	v_pk_fma_f32 v[146:147], v[70:71], v[230:231], v[146:147] op_sel_hi:[1,0,1] neg_lo:[0,1,0] neg_hi:[0,1,0]
	v_pk_fma_f32 v[148:149], v[72:73], v[230:231], v[148:149] op_sel_hi:[1,0,1] neg_lo:[0,1,0] neg_hi:[0,1,0]
	ds_read_b128 v[70:73], v233 offset:7504
	v_pk_fma_f32 v[150:151], v[194:195], v[230:231], v[150:151] op_sel_hi:[1,0,1] neg_lo:[0,1,0] neg_hi:[0,1,0]
	v_pk_fma_f32 v[152:153], v[196:197], v[230:231], v[152:153] op_sel_hi:[1,0,1] neg_lo:[0,1,0] neg_hi:[0,1,0]
	ds_read_b128 v[194:197], v233 offset:7520
	s_waitcnt lgkmcnt(7)
	v_pk_fma_f32 v[154:155], v[198:199], v[230:231], v[154:155] op_sel_hi:[1,0,1] neg_lo:[0,1,0] neg_hi:[0,1,0]
	v_pk_fma_f32 v[180:181], v[200:201], v[230:231], v[180:181] op_sel_hi:[1,0,1] neg_lo:[0,1,0] neg_hi:[0,1,0]
	ds_read_b128 v[198:201], v233 offset:7536
	v_pk_fma_f32 v[182:183], v[202:203], v[230:231], v[182:183] op_sel_hi:[1,0,1] neg_lo:[0,1,0] neg_hi:[0,1,0]
	v_pk_fma_f32 v[184:185], v[204:205], v[230:231], v[184:185] op_sel_hi:[1,0,1] neg_lo:[0,1,0] neg_hi:[0,1,0]
	ds_read_b128 v[202:205], v233 offset:7552
	s_waitcnt lgkmcnt(7)
	v_pk_fma_f32 v[186:187], v[206:207], v[230:231], v[186:187] op_sel_hi:[1,0,1] neg_lo:[0,1,0] neg_hi:[0,1,0]
	v_pk_fma_f32 v[188:189], v[208:209], v[230:231], v[188:189] op_sel_hi:[1,0,1] neg_lo:[0,1,0] neg_hi:[0,1,0]
	ds_read_b128 v[206:209], v233 offset:7568
	v_pk_fma_f32 v[190:191], v[226:227], v[230:231], v[190:191] op_sel_hi:[1,0,1] neg_lo:[0,1,0] neg_hi:[0,1,0]
	v_pk_fma_f32 v[192:193], v[228:229], v[230:231], v[192:193] op_sel_hi:[1,0,1] neg_lo:[0,1,0] neg_hi:[0,1,0]
	ds_read_b128 v[226:229], v233 offset:7584
	v_mov_b32_e32 v230, v133
	v_cvt_pk_bf16_f32 v232, v230, v230
	global_store_short v28, v232, s[0:1]
	s_add_u32 s0, s0, 0x400
	s_addc_u32 s1, s1, 0
	s_waitcnt lgkmcnt(7)
	v_pk_fma_f32 v[134:135], v[58:59], v[230:231], v[134:135] op_sel_hi:[1,0,1] neg_lo:[0,1,0] neg_hi:[0,1,0]
	v_pk_fma_f32 v[136:137], v[60:61], v[230:231], v[136:137] op_sel_hi:[1,0,1] neg_lo:[0,1,0] neg_hi:[0,1,0]
	ds_read_b128 v[58:61], v233 offset:7728
	v_pk_fma_f32 v[138:139], v[62:63], v[230:231], v[138:139] op_sel_hi:[1,0,1] neg_lo:[0,1,0] neg_hi:[0,1,0]
	v_pk_fma_f32 v[140:141], v[64:65], v[230:231], v[140:141] op_sel_hi:[1,0,1] neg_lo:[0,1,0] neg_hi:[0,1,0]
	ds_read_b128 v[62:65], v233 offset:7744
	s_waitcnt lgkmcnt(7)
	v_pk_fma_f32 v[142:143], v[66:67], v[230:231], v[142:143] op_sel_hi:[1,0,1] neg_lo:[0,1,0] neg_hi:[0,1,0]
	v_pk_fma_f32 v[144:145], v[68:69], v[230:231], v[144:145] op_sel_hi:[1,0,1] neg_lo:[0,1,0] neg_hi:[0,1,0]
	ds_read_b128 v[66:69], v233 offset:7760
	v_pk_fma_f32 v[146:147], v[70:71], v[230:231], v[146:147] op_sel_hi:[1,0,1] neg_lo:[0,1,0] neg_hi:[0,1,0]
	v_pk_fma_f32 v[148:149], v[72:73], v[230:231], v[148:149] op_sel_hi:[1,0,1] neg_lo:[0,1,0] neg_hi:[0,1,0]
	ds_read_b128 v[70:73], v233 offset:7776
	s_waitcnt lgkmcnt(7)
	v_pk_fma_f32 v[150:151], v[194:195], v[230:231], v[150:151] op_sel_hi:[1,0,1] neg_lo:[0,1,0] neg_hi:[0,1,0]
	v_pk_fma_f32 v[152:153], v[196:197], v[230:231], v[152:153] op_sel_hi:[1,0,1] neg_lo:[0,1,0] neg_hi:[0,1,0]
	ds_read_b128 v[194:197], v233 offset:7792
	v_pk_fma_f32 v[154:155], v[198:199], v[230:231], v[154:155] op_sel_hi:[1,0,1] neg_lo:[0,1,0] neg_hi:[0,1,0]
	v_pk_fma_f32 v[180:181], v[200:201], v[230:231], v[180:181] op_sel_hi:[1,0,1] neg_lo:[0,1,0] neg_hi:[0,1,0]
	ds_read_b128 v[198:201], v233 offset:7808
	s_waitcnt lgkmcnt(7)
	v_pk_fma_f32 v[182:183], v[202:203], v[230:231], v[182:183] op_sel_hi:[1,0,1] neg_lo:[0,1,0] neg_hi:[0,1,0]
	v_pk_fma_f32 v[184:185], v[204:205], v[230:231], v[184:185] op_sel_hi:[1,0,1] neg_lo:[0,1,0] neg_hi:[0,1,0]
	ds_read_b128 v[202:205], v233 offset:7824
	v_pk_fma_f32 v[186:187], v[206:207], v[230:231], v[186:187] op_sel_hi:[1,0,1] neg_lo:[0,1,0] neg_hi:[0,1,0]
	v_pk_fma_f32 v[188:189], v[208:209], v[230:231], v[188:189] op_sel_hi:[1,0,1] neg_lo:[0,1,0] neg_hi:[0,1,0]
	ds_read_b128 v[206:209], v233 offset:7840
	s_waitcnt lgkmcnt(8)
	v_pk_fma_f32 v[190:191], v[226:227], v[230:231], v[190:191] op_sel_hi:[1,0,1] neg_lo:[0,1,0] neg_hi:[0,1,0]
	v_pk_fma_f32 v[192:193], v[228:229], v[230:231], v[192:193] op_sel_hi:[1,0,1] neg_lo:[0,1,0] neg_hi:[0,1,0]
	ds_read_b128 v[226:229], v233 offset:7856
	v_mov_b32_e32 v230, v134
	v_cvt_pk_bf16_f32 v232, v230, v230
	global_store_short v28, v232, s[0:1]
	s_add_u32 s0, s0, 0x400
	s_addc_u32 s1, s1, 0
	s_waitcnt lgkmcnt(7)
	v_pk_fma_f32 v[134:135], v[58:59], v[230:231], v[134:135] op_sel_hi:[1,0,1] neg_lo:[0,1,0] neg_hi:[0,1,0]
	v_pk_fma_f32 v[136:137], v[60:61], v[230:231], v[136:137] op_sel_hi:[1,0,1] neg_lo:[0,1,0] neg_hi:[0,1,0]
	ds_read_b128 v[58:61], v233 offset:8000
	v_pk_fma_f32 v[138:139], v[62:63], v[230:231], v[138:139] op_sel_hi:[1,0,1] neg_lo:[0,1,0] neg_hi:[0,1,0]
	v_pk_fma_f32 v[140:141], v[64:65], v[230:231], v[140:141] op_sel_hi:[1,0,1] neg_lo:[0,1,0] neg_hi:[0,1,0]
	ds_read_b128 v[62:65], v233 offset:8016
	s_waitcnt lgkmcnt(7)
	v_pk_fma_f32 v[142:143], v[66:67], v[230:231], v[142:143] op_sel_hi:[1,0,1] neg_lo:[0,1,0] neg_hi:[0,1,0]
	v_pk_fma_f32 v[144:145], v[68:69], v[230:231], v[144:145] op_sel_hi:[1,0,1] neg_lo:[0,1,0] neg_hi:[0,1,0]
	ds_read_b128 v[66:69], v233 offset:8032
	v_pk_fma_f32 v[146:147], v[70:71], v[230:231], v[146:147] op_sel_hi:[1,0,1] neg_lo:[0,1,0] neg_hi:[0,1,0]
	v_pk_fma_f32 v[148:149], v[72:73], v[230:231], v[148:149] op_sel_hi:[1,0,1] neg_lo:[0,1,0] neg_hi:[0,1,0]
	ds_read_b128 v[70:73], v233 offset:8048
	s_waitcnt lgkmcnt(7)
	v_pk_fma_f32 v[150:151], v[194:195], v[230:231], v[150:151] op_sel_hi:[1,0,1] neg_lo:[0,1,0] neg_hi:[0,1,0]
	v_pk_fma_f32 v[152:153], v[196:197], v[230:231], v[152:153] op_sel_hi:[1,0,1] neg_lo:[0,1,0] neg_hi:[0,1,0]
	ds_read_b128 v[194:197], v233 offset:8064
	v_pk_fma_f32 v[154:155], v[198:199], v[230:231], v[154:155] op_sel_hi:[1,0,1] neg_lo:[0,1,0] neg_hi:[0,1,0]
	v_pk_fma_f32 v[180:181], v[200:201], v[230:231], v[180:181] op_sel_hi:[1,0,1] neg_lo:[0,1,0] neg_hi:[0,1,0]
	ds_read_b128 v[198:201], v233 offset:8080
	s_waitcnt lgkmcnt(7)
	v_pk_fma_f32 v[182:183], v[202:203], v[230:231], v[182:183] op_sel_hi:[1,0,1] neg_lo:[0,1,0] neg_hi:[0,1,0]
	v_pk_fma_f32 v[184:185], v[204:205], v[230:231], v[184:185] op_sel_hi:[1,0,1] neg_lo:[0,1,0] neg_hi:[0,1,0]
	ds_read_b128 v[202:205], v233 offset:8096
	v_pk_fma_f32 v[186:187], v[206:207], v[230:231], v[186:187] op_sel_hi:[1,0,1] neg_lo:[0,1,0] neg_hi:[0,1,0]
	v_pk_fma_f32 v[188:189], v[208:209], v[230:231], v[188:189] op_sel_hi:[1,0,1] neg_lo:[0,1,0] neg_hi:[0,1,0]
	ds_read_b128 v[206:209], v233 offset:8112
	s_waitcnt lgkmcnt(8)
	v_pk_fma_f32 v[190:191], v[226:227], v[230:231], v[190:191] op_sel_hi:[1,0,1] neg_lo:[0,1,0] neg_hi:[0,1,0]
	v_pk_fma_f32 v[192:193], v[228:229], v[230:231], v[192:193] op_sel_hi:[1,0,1] neg_lo:[0,1,0] neg_hi:[0,1,0]
	ds_read_b128 v[226:229], v233 offset:8128
	v_mov_b32_e32 v230, v135
	v_cvt_pk_bf16_f32 v232, v230, v230
	global_store_short v28, v232, s[0:1]
	s_add_u32 s0, s0, 0x400
	s_addc_u32 s1, s1, 0
	s_waitcnt lgkmcnt(7)
	v_pk_fma_f32 v[136:137], v[60:61], v[230:231], v[136:137] op_sel_hi:[1,0,1] neg_lo:[0,1,0] neg_hi:[0,1,0]
	ds_read_b128 v[58:61], v233 offset:8272
	v_pk_fma_f32 v[138:139], v[62:63], v[230:231], v[138:139] op_sel_hi:[1,0,1] neg_lo:[0,1,0] neg_hi:[0,1,0]
	v_pk_fma_f32 v[140:141], v[64:65], v[230:231], v[140:141] op_sel_hi:[1,0,1] neg_lo:[0,1,0] neg_hi:[0,1,0]
	ds_read_b128 v[62:65], v233 offset:8288
	s_waitcnt lgkmcnt(7)
	v_pk_fma_f32 v[142:143], v[66:67], v[230:231], v[142:143] op_sel_hi:[1,0,1] neg_lo:[0,1,0] neg_hi:[0,1,0]
	v_pk_fma_f32 v[144:145], v[68:69], v[230:231], v[144:145] op_sel_hi:[1,0,1] neg_lo:[0,1,0] neg_hi:[0,1,0]
	ds_read_b128 v[66:69], v233 offset:8304
	v_pk_fma_f32 v[146:147], v[70:71], v[230:231], v[146:147] op_sel_hi:[1,0,1] neg_lo:[0,1,0] neg_hi:[0,1,0]
	v_pk_fma_f32 v[148:149], v[72:73], v[230:231], v[148:149] op_sel_hi:[1,0,1] neg_lo:[0,1,0] neg_hi:[0,1,0]
	ds_read_b128 v[70:73], v233 offset:8320
	s_waitcnt lgkmcnt(7)
	v_pk_fma_f32 v[150:151], v[194:195], v[230:231], v[150:151] op_sel_hi:[1,0,1] neg_lo:[0,1,0] neg_hi:[0,1,0]
	v_pk_fma_f32 v[152:153], v[196:197], v[230:231], v[152:153] op_sel_hi:[1,0,1] neg_lo:[0,1,0] neg_hi:[0,1,0]
	ds_read_b128 v[194:197], v233 offset:8336
	v_pk_fma_f32 v[154:155], v[198:199], v[230:231], v[154:155] op_sel_hi:[1,0,1] neg_lo:[0,1,0] neg_hi:[0,1,0]
	v_pk_fma_f32 v[180:181], v[200:201], v[230:231], v[180:181] op_sel_hi:[1,0,1] neg_lo:[0,1,0] neg_hi:[0,1,0]
	ds_read_b128 v[198:201], v233 offset:8352
	s_waitcnt lgkmcnt(7)
	v_pk_fma_f32 v[182:183], v[202:203], v[230:231], v[182:183] op_sel_hi:[1,0,1] neg_lo:[0,1,0] neg_hi:[0,1,0]
	v_pk_fma_f32 v[184:185], v[204:205], v[230:231], v[184:185] op_sel_hi:[1,0,1] neg_lo:[0,1,0] neg_hi:[0,1,0]
	ds_read_b128 v[202:205], v233 offset:8368
	v_pk_fma_f32 v[186:187], v[206:207], v[230:231], v[186:187] op_sel_hi:[1,0,1] neg_lo:[0,1,0] neg_hi:[0,1,0]
	v_pk_fma_f32 v[188:189], v[208:209], v[230:231], v[188:189] op_sel_hi:[1,0,1] neg_lo:[0,1,0] neg_hi:[0,1,0]
	ds_read_b128 v[206:209], v233 offset:8384
	s_waitcnt lgkmcnt(8)
	v_pk_fma_f32 v[190:191], v[226:227], v[230:231], v[190:191] op_sel_hi:[1,0,1] neg_lo:[0,1,0] neg_hi:[0,1,0]
	v_pk_fma_f32 v[192:193], v[228:229], v[230:231], v[192:193] op_sel_hi:[1,0,1] neg_lo:[0,1,0] neg_hi:[0,1,0]
	ds_read_b128 v[226:229], v233 offset:8400
	v_mov_b32_e32 v230, v136
	v_cvt_pk_bf16_f32 v232, v230, v230
	global_store_short v28, v232, s[0:1]
	s_add_u32 s0, s0, 0x400
	s_addc_u32 s1, s1, 0
	s_waitcnt lgkmcnt(7)
	v_pk_fma_f32 v[136:137], v[60:61], v[230:231], v[136:137] op_sel_hi:[1,0,1] neg_lo:[0,1,0] neg_hi:[0,1,0]
	v_pk_fma_f32 v[138:139], v[62:63], v[230:231], v[138:139] op_sel_hi:[1,0,1] neg_lo:[0,1,0] neg_hi:[0,1,0]
	v_pk_fma_f32 v[140:141], v[64:65], v[230:231], v[140:141] op_sel_hi:[1,0,1] neg_lo:[0,1,0] neg_hi:[0,1,0]
	ds_read_b128 v[62:65], v233 offset:8560
	s_waitcnt lgkmcnt(6)
	v_pk_fma_f32 v[142:143], v[66:67], v[230:231], v[142:143] op_sel_hi:[1,0,1] neg_lo:[0,1,0] neg_hi:[0,1,0]
	v_pk_fma_f32 v[144:145], v[68:69], v[230:231], v[144:145] op_sel_hi:[1,0,1] neg_lo:[0,1,0] neg_hi:[0,1,0]
	ds_read_b128 v[66:69], v233 offset:8576
	v_pk_fma_f32 v[146:147], v[70:71], v[230:231], v[146:147] op_sel_hi:[1,0,1] neg_lo:[0,1,0] neg_hi:[0,1,0]
	v_pk_fma_f32 v[148:149], v[72:73], v[230:231], v[148:149] op_sel_hi:[1,0,1] neg_lo:[0,1,0] neg_hi:[0,1,0]
	ds_read_b128 v[70:73], v233 offset:8592
	s_waitcnt lgkmcnt(6)
	v_pk_fma_f32 v[150:151], v[194:195], v[230:231], v[150:151] op_sel_hi:[1,0,1] neg_lo:[0,1,0] neg_hi:[0,1,0]
	v_pk_fma_f32 v[152:153], v[196:197], v[230:231], v[152:153] op_sel_hi:[1,0,1] neg_lo:[0,1,0] neg_hi:[0,1,0]
	ds_read_b128 v[194:197], v233 offset:8608
	v_pk_fma_f32 v[154:155], v[198:199], v[230:231], v[154:155] op_sel_hi:[1,0,1] neg_lo:[0,1,0] neg_hi:[0,1,0]
	v_pk_fma_f32 v[180:181], v[200:201], v[230:231], v[180:181] op_sel_hi:[1,0,1] neg_lo:[0,1,0] neg_hi:[0,1,0]
	ds_read_b128 v[198:201], v233 offset:8624
	s_waitcnt lgkmcnt(6)
	v_pk_fma_f32 v[182:183], v[202:203], v[230:231], v[182:183] op_sel_hi:[1,0,1] neg_lo:[0,1,0] neg_hi:[0,1,0]
	v_pk_fma_f32 v[184:185], v[204:205], v[230:231], v[184:185] op_sel_hi:[1,0,1] neg_lo:[0,1,0] neg_hi:[0,1,0]
	ds_read_b128 v[202:205], v233 offset:8640
	v_pk_fma_f32 v[186:187], v[206:207], v[230:231], v[186:187] op_sel_hi:[1,0,1] neg_lo:[0,1,0] neg_hi:[0,1,0]
	v_pk_fma_f32 v[188:189], v[208:209], v[230:231], v[188:189] op_sel_hi:[1,0,1] neg_lo:[0,1,0] neg_hi:[0,1,0]
	ds_read_b128 v[206:209], v233 offset:8656
	s_waitcnt lgkmcnt(7)
	v_pk_fma_f32 v[190:191], v[226:227], v[230:231], v[190:191] op_sel_hi:[1,0,1] neg_lo:[0,1,0] neg_hi:[0,1,0]
	v_pk_fma_f32 v[192:193], v[228:229], v[230:231], v[192:193] op_sel_hi:[1,0,1] neg_lo:[0,1,0] neg_hi:[0,1,0]
	ds_read_b128 v[226:229], v233 offset:8672
	v_mov_b32_e32 v230, v137
	v_cvt_pk_bf16_f32 v232, v230, v230
	global_store_short v28, v232, s[0:1]
	s_add_u32 s0, s0, 0x400
	s_addc_u32 s1, s1, 0
	s_waitcnt lgkmcnt(6)
	v_pk_fma_f32 v[138:139], v[62:63], v[230:231], v[138:139] op_sel_hi:[1,0,1] neg_lo:[0,1,0] neg_hi:[0,1,0]
	v_pk_fma_f32 v[140:141], v[64:65], v[230:231], v[140:141] op_sel_hi:[1,0,1] neg_lo:[0,1,0] neg_hi:[0,1,0]
	ds_read_b128 v[62:65], v233 offset:8832
	v_pk_fma_f32 v[142:143], v[66:67], v[230:231], v[142:143] op_sel_hi:[1,0,1] neg_lo:[0,1,0] neg_hi:[0,1,0]
	v_pk_fma_f32 v[144:145], v[68:69], v[230:231], v[144:145] op_sel_hi:[1,0,1] neg_lo:[0,1,0] neg_hi:[0,1,0]
	ds_read_b128 v[66:69], v233 offset:8848
	s_waitcnt lgkmcnt(6)
	v_pk_fma_f32 v[146:147], v[70:71], v[230:231], v[146:147] op_sel_hi:[1,0,1] neg_lo:[0,1,0] neg_hi:[0,1,0]
	v_pk_fma_f32 v[148:149], v[72:73], v[230:231], v[148:149] op_sel_hi:[1,0,1] neg_lo:[0,1,0] neg_hi:[0,1,0]
	ds_read_b128 v[70:73], v233 offset:8864
	v_pk_fma_f32 v[150:151], v[194:195], v[230:231], v[150:151] op_sel_hi:[1,0,1] neg_lo:[0,1,0] neg_hi:[0,1,0]
	v_pk_fma_f32 v[152:153], v[196:197], v[230:231], v[152:153] op_sel_hi:[1,0,1] neg_lo:[0,1,0] neg_hi:[0,1,0]
	ds_read_b128 v[194:197], v233 offset:8880
	s_waitcnt lgkmcnt(6)
	v_pk_fma_f32 v[154:155], v[198:199], v[230:231], v[154:155] op_sel_hi:[1,0,1] neg_lo:[0,1,0] neg_hi:[0,1,0]
	v_pk_fma_f32 v[180:181], v[200:201], v[230:231], v[180:181] op_sel_hi:[1,0,1] neg_lo:[0,1,0] neg_hi:[0,1,0]
	ds_read_b128 v[198:201], v233 offset:8896
	v_pk_fma_f32 v[182:183], v[202:203], v[230:231], v[182:183] op_sel_hi:[1,0,1] neg_lo:[0,1,0] neg_hi:[0,1,0]
	v_pk_fma_f32 v[184:185], v[204:205], v[230:231], v[184:185] op_sel_hi:[1,0,1] neg_lo:[0,1,0] neg_hi:[0,1,0]
	ds_read_b128 v[202:205], v233 offset:8912
	s_waitcnt lgkmcnt(6)
	v_pk_fma_f32 v[186:187], v[206:207], v[230:231], v[186:187] op_sel_hi:[1,0,1] neg_lo:[0,1,0] neg_hi:[0,1,0]
	v_pk_fma_f32 v[188:189], v[208:209], v[230:231], v[188:189] op_sel_hi:[1,0,1] neg_lo:[0,1,0] neg_hi:[0,1,0]
	ds_read_b128 v[206:209], v233 offset:8928
	v_pk_fma_f32 v[190:191], v[226:227], v[230:231], v[190:191] op_sel_hi:[1,0,1] neg_lo:[0,1,0] neg_hi:[0,1,0]
	v_pk_fma_f32 v[192:193], v[228:229], v[230:231], v[192:193] op_sel_hi:[1,0,1] neg_lo:[0,1,0] neg_hi:[0,1,0]
	ds_read_b128 v[226:229], v233 offset:8944
	v_mov_b32_e32 v230, v138
	v_cvt_pk_bf16_f32 v232, v230, v230
	global_store_short v28, v232, s[0:1]
	s_add_u32 s0, s0, 0x400
	s_addc_u32 s1, s1, 0
	s_waitcnt lgkmcnt(6)
	v_pk_fma_f32 v[138:139], v[62:63], v[230:231], v[138:139] op_sel_hi:[1,0,1] neg_lo:[0,1,0] neg_hi:[0,1,0]
	v_pk_fma_f32 v[140:141], v[64:65], v[230:231], v[140:141] op_sel_hi:[1,0,1] neg_lo:[0,1,0] neg_hi:[0,1,0]
	ds_read_b128 v[62:65], v233 offset:9104
	v_pk_fma_f32 v[142:143], v[66:67], v[230:231], v[142:143] op_sel_hi:[1,0,1] neg_lo:[0,1,0] neg_hi:[0,1,0]
	v_pk_fma_f32 v[144:145], v[68:69], v[230:231], v[144:145] op_sel_hi:[1,0,1] neg_lo:[0,1,0] neg_hi:[0,1,0]
	ds_read_b128 v[66:69], v233 offset:9120
	s_waitcnt lgkmcnt(6)
	v_pk_fma_f32 v[146:147], v[70:71], v[230:231], v[146:147] op_sel_hi:[1,0,1] neg_lo:[0,1,0] neg_hi:[0,1,0]
	v_pk_fma_f32 v[148:149], v[72:73], v[230:231], v[148:149] op_sel_hi:[1,0,1] neg_lo:[0,1,0] neg_hi:[0,1,0]
	ds_read_b128 v[70:73], v233 offset:9136
	v_pk_fma_f32 v[150:151], v[194:195], v[230:231], v[150:151] op_sel_hi:[1,0,1] neg_lo:[0,1,0] neg_hi:[0,1,0]
	v_pk_fma_f32 v[152:153], v[196:197], v[230:231], v[152:153] op_sel_hi:[1,0,1] neg_lo:[0,1,0] neg_hi:[0,1,0]
	ds_read_b128 v[194:197], v233 offset:9152
	s_waitcnt lgkmcnt(6)
	v_pk_fma_f32 v[154:155], v[198:199], v[230:231], v[154:155] op_sel_hi:[1,0,1] neg_lo:[0,1,0] neg_hi:[0,1,0]
	v_pk_fma_f32 v[180:181], v[200:201], v[230:231], v[180:181] op_sel_hi:[1,0,1] neg_lo:[0,1,0] neg_hi:[0,1,0]
	ds_read_b128 v[198:201], v233 offset:9168
	v_pk_fma_f32 v[182:183], v[202:203], v[230:231], v[182:183] op_sel_hi:[1,0,1] neg_lo:[0,1,0] neg_hi:[0,1,0]
	v_pk_fma_f32 v[184:185], v[204:205], v[230:231], v[184:185] op_sel_hi:[1,0,1] neg_lo:[0,1,0] neg_hi:[0,1,0]
	ds_read_b128 v[202:205], v233 offset:9184
	s_waitcnt lgkmcnt(6)
	v_pk_fma_f32 v[186:187], v[206:207], v[230:231], v[186:187] op_sel_hi:[1,0,1] neg_lo:[0,1,0] neg_hi:[0,1,0]
	v_pk_fma_f32 v[188:189], v[208:209], v[230:231], v[188:189] op_sel_hi:[1,0,1] neg_lo:[0,1,0] neg_hi:[0,1,0]
	ds_read_b128 v[206:209], v233 offset:9200
	v_pk_fma_f32 v[190:191], v[226:227], v[230:231], v[190:191] op_sel_hi:[1,0,1] neg_lo:[0,1,0] neg_hi:[0,1,0]
	v_pk_fma_f32 v[192:193], v[228:229], v[230:231], v[192:193] op_sel_hi:[1,0,1] neg_lo:[0,1,0] neg_hi:[0,1,0]
	ds_read_b128 v[226:229], v233 offset:9216
	v_mov_b32_e32 v230, v139
	v_cvt_pk_bf16_f32 v232, v230, v230
	global_store_short v28, v232, s[0:1]
	s_add_u32 s0, s0, 0x400
	s_addc_u32 s1, s1, 0
	s_waitcnt lgkmcnt(6)
	v_pk_fma_f32 v[140:141], v[64:65], v[230:231], v[140:141] op_sel_hi:[1,0,1] neg_lo:[0,1,0] neg_hi:[0,1,0]
	ds_read_b128 v[62:65], v233 offset:9376
	v_pk_fma_f32 v[142:143], v[66:67], v[230:231], v[142:143] op_sel_hi:[1,0,1] neg_lo:[0,1,0] neg_hi:[0,1,0]
	v_pk_fma_f32 v[144:145], v[68:69], v[230:231], v[144:145] op_sel_hi:[1,0,1] neg_lo:[0,1,0] neg_hi:[0,1,0]
	ds_read_b128 v[66:69], v233 offset:9392
	s_waitcnt lgkmcnt(6)
	v_pk_fma_f32 v[146:147], v[70:71], v[230:231], v[146:147] op_sel_hi:[1,0,1] neg_lo:[0,1,0] neg_hi:[0,1,0]
	v_pk_fma_f32 v[148:149], v[72:73], v[230:231], v[148:149] op_sel_hi:[1,0,1] neg_lo:[0,1,0] neg_hi:[0,1,0]
	ds_read_b128 v[70:73], v233 offset:9408
	v_pk_fma_f32 v[150:151], v[194:195], v[230:231], v[150:151] op_sel_hi:[1,0,1] neg_lo:[0,1,0] neg_hi:[0,1,0]
	v_pk_fma_f32 v[152:153], v[196:197], v[230:231], v[152:153] op_sel_hi:[1,0,1] neg_lo:[0,1,0] neg_hi:[0,1,0]
	ds_read_b128 v[194:197], v233 offset:9424
	s_waitcnt lgkmcnt(6)
	v_pk_fma_f32 v[154:155], v[198:199], v[230:231], v[154:155] op_sel_hi:[1,0,1] neg_lo:[0,1,0] neg_hi:[0,1,0]
	v_pk_fma_f32 v[180:181], v[200:201], v[230:231], v[180:181] op_sel_hi:[1,0,1] neg_lo:[0,1,0] neg_hi:[0,1,0]
	ds_read_b128 v[198:201], v233 offset:9440
	v_pk_fma_f32 v[182:183], v[202:203], v[230:231], v[182:183] op_sel_hi:[1,0,1] neg_lo:[0,1,0] neg_hi:[0,1,0]
	v_pk_fma_f32 v[184:185], v[204:205], v[230:231], v[184:185] op_sel_hi:[1,0,1] neg_lo:[0,1,0] neg_hi:[0,1,0]
	ds_read_b128 v[202:205], v233 offset:9456
	s_waitcnt lgkmcnt(6)
	v_pk_fma_f32 v[186:187], v[206:207], v[230:231], v[186:187] op_sel_hi:[1,0,1] neg_lo:[0,1,0] neg_hi:[0,1,0]
	v_pk_fma_f32 v[188:189], v[208:209], v[230:231], v[188:189] op_sel_hi:[1,0,1] neg_lo:[0,1,0] neg_hi:[0,1,0]
	ds_read_b128 v[206:209], v233 offset:9472
	v_pk_fma_f32 v[190:191], v[226:227], v[230:231], v[190:191] op_sel_hi:[1,0,1] neg_lo:[0,1,0] neg_hi:[0,1,0]
	v_pk_fma_f32 v[192:193], v[228:229], v[230:231], v[192:193] op_sel_hi:[1,0,1] neg_lo:[0,1,0] neg_hi:[0,1,0]
	ds_read_b128 v[226:229], v233 offset:9488
	v_mov_b32_e32 v230, v140
	v_cvt_pk_bf16_f32 v232, v230, v230
	global_store_short v28, v232, s[0:1]
	s_add_u32 s0, s0, 0x400
	s_addc_u32 s1, s1, 0
	s_waitcnt lgkmcnt(6)
	v_pk_fma_f32 v[140:141], v[64:65], v[230:231], v[140:141] op_sel_hi:[1,0,1] neg_lo:[0,1,0] neg_hi:[0,1,0]
	v_pk_fma_f32 v[142:143], v[66:67], v[230:231], v[142:143] op_sel_hi:[1,0,1] neg_lo:[0,1,0] neg_hi:[0,1,0]
	v_pk_fma_f32 v[144:145], v[68:69], v[230:231], v[144:145] op_sel_hi:[1,0,1] neg_lo:[0,1,0] neg_hi:[0,1,0]
	ds_read_b128 v[66:69], v233 offset:9664
	s_waitcnt lgkmcnt(5)
	v_pk_fma_f32 v[146:147], v[70:71], v[230:231], v[146:147] op_sel_hi:[1,0,1] neg_lo:[0,1,0] neg_hi:[0,1,0]
	v_pk_fma_f32 v[148:149], v[72:73], v[230:231], v[148:149] op_sel_hi:[1,0,1] neg_lo:[0,1,0] neg_hi:[0,1,0]
	ds_read_b128 v[70:73], v233 offset:9680
	v_pk_fma_f32 v[150:151], v[194:195], v[230:231], v[150:151] op_sel_hi:[1,0,1] neg_lo:[0,1,0] neg_hi:[0,1,0]
	v_pk_fma_f32 v[152:153], v[196:197], v[230:231], v[152:153] op_sel_hi:[1,0,1] neg_lo:[0,1,0] neg_hi:[0,1,0]
	ds_read_b128 v[194:197], v233 offset:9696
	s_waitcnt lgkmcnt(5)
	v_pk_fma_f32 v[154:155], v[198:199], v[230:231], v[154:155] op_sel_hi:[1,0,1] neg_lo:[0,1,0] neg_hi:[0,1,0]
	v_pk_fma_f32 v[180:181], v[200:201], v[230:231], v[180:181] op_sel_hi:[1,0,1] neg_lo:[0,1,0] neg_hi:[0,1,0]
	ds_read_b128 v[198:201], v233 offset:9712
	v_pk_fma_f32 v[182:183], v[202:203], v[230:231], v[182:183] op_sel_hi:[1,0,1] neg_lo:[0,1,0] neg_hi:[0,1,0]
	v_pk_fma_f32 v[184:185], v[204:205], v[230:231], v[184:185] op_sel_hi:[1,0,1] neg_lo:[0,1,0] neg_hi:[0,1,0]
	ds_read_b128 v[202:205], v233 offset:9728
	s_waitcnt lgkmcnt(5)
	v_pk_fma_f32 v[186:187], v[206:207], v[230:231], v[186:187] op_sel_hi:[1,0,1] neg_lo:[0,1,0] neg_hi:[0,1,0]
	v_pk_fma_f32 v[188:189], v[208:209], v[230:231], v[188:189] op_sel_hi:[1,0,1] neg_lo:[0,1,0] neg_hi:[0,1,0]
	ds_read_b128 v[206:209], v233 offset:9744
	v_pk_fma_f32 v[190:191], v[226:227], v[230:231], v[190:191] op_sel_hi:[1,0,1] neg_lo:[0,1,0] neg_hi:[0,1,0]
	v_pk_fma_f32 v[192:193], v[228:229], v[230:231], v[192:193] op_sel_hi:[1,0,1] neg_lo:[0,1,0] neg_hi:[0,1,0]
	ds_read_b128 v[226:229], v233 offset:9760
	v_mov_b32_e32 v230, v141
	v_cvt_pk_bf16_f32 v232, v230, v230
	global_store_short v28, v232, s[0:1]
	s_add_u32 s0, s0, 0x400
	s_addc_u32 s1, s1, 0
	s_waitcnt lgkmcnt(5)
	v_pk_fma_f32 v[142:143], v[66:67], v[230:231], v[142:143] op_sel_hi:[1,0,1] neg_lo:[0,1,0] neg_hi:[0,1,0]
	v_pk_fma_f32 v[144:145], v[68:69], v[230:231], v[144:145] op_sel_hi:[1,0,1] neg_lo:[0,1,0] neg_hi:[0,1,0]
	ds_read_b128 v[66:69], v233 offset:9936
	v_pk_fma_f32 v[146:147], v[70:71], v[230:231], v[146:147] op_sel_hi:[1,0,1] neg_lo:[0,1,0] neg_hi:[0,1,0]
	v_pk_fma_f32 v[148:149], v[72:73], v[230:231], v[148:149] op_sel_hi:[1,0,1] neg_lo:[0,1,0] neg_hi:[0,1,0]
	ds_read_b128 v[70:73], v233 offset:9952
	s_waitcnt lgkmcnt(5)
	v_pk_fma_f32 v[150:151], v[194:195], v[230:231], v[150:151] op_sel_hi:[1,0,1] neg_lo:[0,1,0] neg_hi:[0,1,0]
	v_pk_fma_f32 v[152:153], v[196:197], v[230:231], v[152:153] op_sel_hi:[1,0,1] neg_lo:[0,1,0] neg_hi:[0,1,0]
	ds_read_b128 v[194:197], v233 offset:9968
	v_pk_fma_f32 v[154:155], v[198:199], v[230:231], v[154:155] op_sel_hi:[1,0,1] neg_lo:[0,1,0] neg_hi:[0,1,0]
	v_pk_fma_f32 v[180:181], v[200:201], v[230:231], v[180:181] op_sel_hi:[1,0,1] neg_lo:[0,1,0] neg_hi:[0,1,0]
	ds_read_b128 v[198:201], v233 offset:9984
	s_waitcnt lgkmcnt(5)
	v_pk_fma_f32 v[182:183], v[202:203], v[230:231], v[182:183] op_sel_hi:[1,0,1] neg_lo:[0,1,0] neg_hi:[0,1,0]
	v_pk_fma_f32 v[184:185], v[204:205], v[230:231], v[184:185] op_sel_hi:[1,0,1] neg_lo:[0,1,0] neg_hi:[0,1,0]
	ds_read_b128 v[202:205], v233 offset:10000
	v_pk_fma_f32 v[186:187], v[206:207], v[230:231], v[186:187] op_sel_hi:[1,0,1] neg_lo:[0,1,0] neg_hi:[0,1,0]
	v_pk_fma_f32 v[188:189], v[208:209], v[230:231], v[188:189] op_sel_hi:[1,0,1] neg_lo:[0,1,0] neg_hi:[0,1,0]
	ds_read_b128 v[206:209], v233 offset:10016
	s_waitcnt lgkmcnt(6)
	v_pk_fma_f32 v[190:191], v[226:227], v[230:231], v[190:191] op_sel_hi:[1,0,1] neg_lo:[0,1,0] neg_hi:[0,1,0]
	v_pk_fma_f32 v[192:193], v[228:229], v[230:231], v[192:193] op_sel_hi:[1,0,1] neg_lo:[0,1,0] neg_hi:[0,1,0]
	ds_read_b128 v[226:229], v233 offset:10032
	v_mov_b32_e32 v230, v142
	v_cvt_pk_bf16_f32 v232, v230, v230
	global_store_short v28, v232, s[0:1]
	s_add_u32 s0, s0, 0x400
	s_addc_u32 s1, s1, 0
	s_waitcnt lgkmcnt(5)
	v_pk_fma_f32 v[142:143], v[66:67], v[230:231], v[142:143] op_sel_hi:[1,0,1] neg_lo:[0,1,0] neg_hi:[0,1,0]
	v_pk_fma_f32 v[144:145], v[68:69], v[230:231], v[144:145] op_sel_hi:[1,0,1] neg_lo:[0,1,0] neg_hi:[0,1,0]
	ds_read_b128 v[66:69], v233 offset:10208
	v_pk_fma_f32 v[146:147], v[70:71], v[230:231], v[146:147] op_sel_hi:[1,0,1] neg_lo:[0,1,0] neg_hi:[0,1,0]
	v_pk_fma_f32 v[148:149], v[72:73], v[230:231], v[148:149] op_sel_hi:[1,0,1] neg_lo:[0,1,0] neg_hi:[0,1,0]
	ds_read_b128 v[70:73], v233 offset:10224
	s_waitcnt lgkmcnt(5)
	v_pk_fma_f32 v[150:151], v[194:195], v[230:231], v[150:151] op_sel_hi:[1,0,1] neg_lo:[0,1,0] neg_hi:[0,1,0]
	v_pk_fma_f32 v[152:153], v[196:197], v[230:231], v[152:153] op_sel_hi:[1,0,1] neg_lo:[0,1,0] neg_hi:[0,1,0]
	ds_read_b128 v[194:197], v233 offset:10240
	v_pk_fma_f32 v[154:155], v[198:199], v[230:231], v[154:155] op_sel_hi:[1,0,1] neg_lo:[0,1,0] neg_hi:[0,1,0]
	v_pk_fma_f32 v[180:181], v[200:201], v[230:231], v[180:181] op_sel_hi:[1,0,1] neg_lo:[0,1,0] neg_hi:[0,1,0]
	ds_read_b128 v[198:201], v233 offset:10256
	s_waitcnt lgkmcnt(5)
	v_pk_fma_f32 v[182:183], v[202:203], v[230:231], v[182:183] op_sel_hi:[1,0,1] neg_lo:[0,1,0] neg_hi:[0,1,0]
	v_pk_fma_f32 v[184:185], v[204:205], v[230:231], v[184:185] op_sel_hi:[1,0,1] neg_lo:[0,1,0] neg_hi:[0,1,0]
	ds_read_b128 v[202:205], v233 offset:10272
	v_pk_fma_f32 v[186:187], v[206:207], v[230:231], v[186:187] op_sel_hi:[1,0,1] neg_lo:[0,1,0] neg_hi:[0,1,0]
	v_pk_fma_f32 v[188:189], v[208:209], v[230:231], v[188:189] op_sel_hi:[1,0,1] neg_lo:[0,1,0] neg_hi:[0,1,0]
	ds_read_b128 v[206:209], v233 offset:10288
	s_waitcnt lgkmcnt(6)
	v_pk_fma_f32 v[190:191], v[226:227], v[230:231], v[190:191] op_sel_hi:[1,0,1] neg_lo:[0,1,0] neg_hi:[0,1,0]
	v_pk_fma_f32 v[192:193], v[228:229], v[230:231], v[192:193] op_sel_hi:[1,0,1] neg_lo:[0,1,0] neg_hi:[0,1,0]
	ds_read_b128 v[226:229], v233 offset:10304
	v_mov_b32_e32 v230, v143
	v_cvt_pk_bf16_f32 v232, v230, v230
	global_store_short v28, v232, s[0:1]
	s_add_u32 s0, s0, 0x400
	s_addc_u32 s1, s1, 0
	s_waitcnt lgkmcnt(5)
	v_pk_fma_f32 v[144:145], v[68:69], v[230:231], v[144:145] op_sel_hi:[1,0,1] neg_lo:[0,1,0] neg_hi:[0,1,0]
	ds_read_b128 v[66:69], v233 offset:10480
	v_pk_fma_f32 v[146:147], v[70:71], v[230:231], v[146:147] op_sel_hi:[1,0,1] neg_lo:[0,1,0] neg_hi:[0,1,0]
	v_pk_fma_f32 v[148:149], v[72:73], v[230:231], v[148:149] op_sel_hi:[1,0,1] neg_lo:[0,1,0] neg_hi:[0,1,0]
	ds_read_b128 v[70:73], v233 offset:10496
	s_waitcnt lgkmcnt(5)
	v_pk_fma_f32 v[150:151], v[194:195], v[230:231], v[150:151] op_sel_hi:[1,0,1] neg_lo:[0,1,0] neg_hi:[0,1,0]
	v_pk_fma_f32 v[152:153], v[196:197], v[230:231], v[152:153] op_sel_hi:[1,0,1] neg_lo:[0,1,0] neg_hi:[0,1,0]
	ds_read_b128 v[194:197], v233 offset:10512
	v_pk_fma_f32 v[154:155], v[198:199], v[230:231], v[154:155] op_sel_hi:[1,0,1] neg_lo:[0,1,0] neg_hi:[0,1,0]
	v_pk_fma_f32 v[180:181], v[200:201], v[230:231], v[180:181] op_sel_hi:[1,0,1] neg_lo:[0,1,0] neg_hi:[0,1,0]
	ds_read_b128 v[198:201], v233 offset:10528
	s_waitcnt lgkmcnt(5)
	v_pk_fma_f32 v[182:183], v[202:203], v[230:231], v[182:183] op_sel_hi:[1,0,1] neg_lo:[0,1,0] neg_hi:[0,1,0]
	v_pk_fma_f32 v[184:185], v[204:205], v[230:231], v[184:185] op_sel_hi:[1,0,1] neg_lo:[0,1,0] neg_hi:[0,1,0]
	ds_read_b128 v[202:205], v233 offset:10544
	v_pk_fma_f32 v[186:187], v[206:207], v[230:231], v[186:187] op_sel_hi:[1,0,1] neg_lo:[0,1,0] neg_hi:[0,1,0]
	v_pk_fma_f32 v[188:189], v[208:209], v[230:231], v[188:189] op_sel_hi:[1,0,1] neg_lo:[0,1,0] neg_hi:[0,1,0]
	ds_read_b128 v[206:209], v233 offset:10560
	s_waitcnt lgkmcnt(6)
	v_pk_fma_f32 v[190:191], v[226:227], v[230:231], v[190:191] op_sel_hi:[1,0,1] neg_lo:[0,1,0] neg_hi:[0,1,0]
	v_pk_fma_f32 v[192:193], v[228:229], v[230:231], v[192:193] op_sel_hi:[1,0,1] neg_lo:[0,1,0] neg_hi:[0,1,0]
	ds_read_b128 v[226:229], v233 offset:10576
	v_mov_b32_e32 v230, v144
	v_cvt_pk_bf16_f32 v232, v230, v230
	global_store_short v28, v232, s[0:1]
	s_add_u32 s0, s0, 0x400
	s_addc_u32 s1, s1, 0
	s_waitcnt lgkmcnt(5)
	v_pk_fma_f32 v[144:145], v[68:69], v[230:231], v[144:145] op_sel_hi:[1,0,1] neg_lo:[0,1,0] neg_hi:[0,1,0]
	v_pk_fma_f32 v[146:147], v[70:71], v[230:231], v[146:147] op_sel_hi:[1,0,1] neg_lo:[0,1,0] neg_hi:[0,1,0]
	v_pk_fma_f32 v[148:149], v[72:73], v[230:231], v[148:149] op_sel_hi:[1,0,1] neg_lo:[0,1,0] neg_hi:[0,1,0]
	ds_read_b128 v[70:73], v233 offset:10768
	s_waitcnt lgkmcnt(4)
	v_pk_fma_f32 v[150:151], v[194:195], v[230:231], v[150:151] op_sel_hi:[1,0,1] neg_lo:[0,1,0] neg_hi:[0,1,0]
	v_pk_fma_f32 v[152:153], v[196:197], v[230:231], v[152:153] op_sel_hi:[1,0,1] neg_lo:[0,1,0] neg_hi:[0,1,0]
	ds_read_b128 v[194:197], v233 offset:10784
	v_pk_fma_f32 v[154:155], v[198:199], v[230:231], v[154:155] op_sel_hi:[1,0,1] neg_lo:[0,1,0] neg_hi:[0,1,0]
	v_pk_fma_f32 v[180:181], v[200:201], v[230:231], v[180:181] op_sel_hi:[1,0,1] neg_lo:[0,1,0] neg_hi:[0,1,0]
	ds_read_b128 v[198:201], v233 offset:10800
	s_waitcnt lgkmcnt(4)
	v_pk_fma_f32 v[182:183], v[202:203], v[230:231], v[182:183] op_sel_hi:[1,0,1] neg_lo:[0,1,0] neg_hi:[0,1,0]
	v_pk_fma_f32 v[184:185], v[204:205], v[230:231], v[184:185] op_sel_hi:[1,0,1] neg_lo:[0,1,0] neg_hi:[0,1,0]
	ds_read_b128 v[202:205], v233 offset:10816
	v_pk_fma_f32 v[186:187], v[206:207], v[230:231], v[186:187] op_sel_hi:[1,0,1] neg_lo:[0,1,0] neg_hi:[0,1,0]
	v_pk_fma_f32 v[188:189], v[208:209], v[230:231], v[188:189] op_sel_hi:[1,0,1] neg_lo:[0,1,0] neg_hi:[0,1,0]
	ds_read_b128 v[206:209], v233 offset:10832
	s_waitcnt lgkmcnt(5)
	v_pk_fma_f32 v[190:191], v[226:227], v[230:231], v[190:191] op_sel_hi:[1,0,1] neg_lo:[0,1,0] neg_hi:[0,1,0]
	v_pk_fma_f32 v[192:193], v[228:229], v[230:231], v[192:193] op_sel_hi:[1,0,1] neg_lo:[0,1,0] neg_hi:[0,1,0]
	ds_read_b128 v[226:229], v233 offset:10848
	v_mov_b32_e32 v230, v145
	v_cvt_pk_bf16_f32 v232, v230, v230
	global_store_short v28, v232, s[0:1]
	s_add_u32 s0, s0, 0x400
	s_addc_u32 s1, s1, 0
	s_waitcnt lgkmcnt(4)
	v_pk_fma_f32 v[146:147], v[70:71], v[230:231], v[146:147] op_sel_hi:[1,0,1] neg_lo:[0,1,0] neg_hi:[0,1,0]
	v_pk_fma_f32 v[148:149], v[72:73], v[230:231], v[148:149] op_sel_hi:[1,0,1] neg_lo:[0,1,0] neg_hi:[0,1,0]
	ds_read_b128 v[70:73], v233 offset:11040
	v_pk_fma_f32 v[150:151], v[194:195], v[230:231], v[150:151] op_sel_hi:[1,0,1] neg_lo:[0,1,0] neg_hi:[0,1,0]
	v_pk_fma_f32 v[152:153], v[196:197], v[230:231], v[152:153] op_sel_hi:[1,0,1] neg_lo:[0,1,0] neg_hi:[0,1,0]
	ds_read_b128 v[194:197], v233 offset:11056
	s_waitcnt lgkmcnt(4)
	v_pk_fma_f32 v[154:155], v[198:199], v[230:231], v[154:155] op_sel_hi:[1,0,1] neg_lo:[0,1,0] neg_hi:[0,1,0]
	v_pk_fma_f32 v[180:181], v[200:201], v[230:231], v[180:181] op_sel_hi:[1,0,1] neg_lo:[0,1,0] neg_hi:[0,1,0]
	ds_read_b128 v[198:201], v233 offset:11072
	v_pk_fma_f32 v[182:183], v[202:203], v[230:231], v[182:183] op_sel_hi:[1,0,1] neg_lo:[0,1,0] neg_hi:[0,1,0]
	v_pk_fma_f32 v[184:185], v[204:205], v[230:231], v[184:185] op_sel_hi:[1,0,1] neg_lo:[0,1,0] neg_hi:[0,1,0]
	ds_read_b128 v[202:205], v233 offset:11088
	s_waitcnt lgkmcnt(4)
	v_pk_fma_f32 v[186:187], v[206:207], v[230:231], v[186:187] op_sel_hi:[1,0,1] neg_lo:[0,1,0] neg_hi:[0,1,0]
	v_pk_fma_f32 v[188:189], v[208:209], v[230:231], v[188:189] op_sel_hi:[1,0,1] neg_lo:[0,1,0] neg_hi:[0,1,0]
	ds_read_b128 v[206:209], v233 offset:11104
	v_pk_fma_f32 v[190:191], v[226:227], v[230:231], v[190:191] op_sel_hi:[1,0,1] neg_lo:[0,1,0] neg_hi:[0,1,0]
	v_pk_fma_f32 v[192:193], v[228:229], v[230:231], v[192:193] op_sel_hi:[1,0,1] neg_lo:[0,1,0] neg_hi:[0,1,0]
	ds_read_b128 v[226:229], v233 offset:11120
	v_mov_b32_e32 v230, v146
	v_cvt_pk_bf16_f32 v232, v230, v230
	global_store_short v28, v232, s[0:1]
	s_add_u32 s0, s0, 0x400
	s_addc_u32 s1, s1, 0
	s_waitcnt lgkmcnt(4)
	v_pk_fma_f32 v[146:147], v[70:71], v[230:231], v[146:147] op_sel_hi:[1,0,1] neg_lo:[0,1,0] neg_hi:[0,1,0]
	v_pk_fma_f32 v[148:149], v[72:73], v[230:231], v[148:149] op_sel_hi:[1,0,1] neg_lo:[0,1,0] neg_hi:[0,1,0]
	ds_read_b128 v[70:73], v233 offset:11312
	v_pk_fma_f32 v[150:151], v[194:195], v[230:231], v[150:151] op_sel_hi:[1,0,1] neg_lo:[0,1,0] neg_hi:[0,1,0]
	v_pk_fma_f32 v[152:153], v[196:197], v[230:231], v[152:153] op_sel_hi:[1,0,1] neg_lo:[0,1,0] neg_hi:[0,1,0]
	ds_read_b128 v[194:197], v233 offset:11328
	s_waitcnt lgkmcnt(4)
	v_pk_fma_f32 v[154:155], v[198:199], v[230:231], v[154:155] op_sel_hi:[1,0,1] neg_lo:[0,1,0] neg_hi:[0,1,0]
	v_pk_fma_f32 v[180:181], v[200:201], v[230:231], v[180:181] op_sel_hi:[1,0,1] neg_lo:[0,1,0] neg_hi:[0,1,0]
	ds_read_b128 v[198:201], v233 offset:11344
	v_pk_fma_f32 v[182:183], v[202:203], v[230:231], v[182:183] op_sel_hi:[1,0,1] neg_lo:[0,1,0] neg_hi:[0,1,0]
	v_pk_fma_f32 v[184:185], v[204:205], v[230:231], v[184:185] op_sel_hi:[1,0,1] neg_lo:[0,1,0] neg_hi:[0,1,0]
	ds_read_b128 v[202:205], v233 offset:11360
	s_waitcnt lgkmcnt(4)
	v_pk_fma_f32 v[186:187], v[206:207], v[230:231], v[186:187] op_sel_hi:[1,0,1] neg_lo:[0,1,0] neg_hi:[0,1,0]
	v_pk_fma_f32 v[188:189], v[208:209], v[230:231], v[188:189] op_sel_hi:[1,0,1] neg_lo:[0,1,0] neg_hi:[0,1,0]
	ds_read_b128 v[206:209], v233 offset:11376
	v_pk_fma_f32 v[190:191], v[226:227], v[230:231], v[190:191] op_sel_hi:[1,0,1] neg_lo:[0,1,0] neg_hi:[0,1,0]
	v_pk_fma_f32 v[192:193], v[228:229], v[230:231], v[192:193] op_sel_hi:[1,0,1] neg_lo:[0,1,0] neg_hi:[0,1,0]
	ds_read_b128 v[226:229], v233 offset:11392
	v_mov_b32_e32 v230, v147
	v_cvt_pk_bf16_f32 v232, v230, v230
	global_store_short v28, v232, s[0:1]
	s_add_u32 s0, s0, 0x400
	s_addc_u32 s1, s1, 0
	s_waitcnt lgkmcnt(4)
	v_pk_fma_f32 v[148:149], v[72:73], v[230:231], v[148:149] op_sel_hi:[1,0,1] neg_lo:[0,1,0] neg_hi:[0,1,0]
	ds_read_b128 v[70:73], v233 offset:11584
	v_pk_fma_f32 v[150:151], v[194:195], v[230:231], v[150:151] op_sel_hi:[1,0,1] neg_lo:[0,1,0] neg_hi:[0,1,0]
	v_pk_fma_f32 v[152:153], v[196:197], v[230:231], v[152:153] op_sel_hi:[1,0,1] neg_lo:[0,1,0] neg_hi:[0,1,0]
	ds_read_b128 v[194:197], v233 offset:11600
	s_waitcnt lgkmcnt(4)
	v_pk_fma_f32 v[154:155], v[198:199], v[230:231], v[154:155] op_sel_hi:[1,0,1] neg_lo:[0,1,0] neg_hi:[0,1,0]
	v_pk_fma_f32 v[180:181], v[200:201], v[230:231], v[180:181] op_sel_hi:[1,0,1] neg_lo:[0,1,0] neg_hi:[0,1,0]
	ds_read_b128 v[198:201], v233 offset:11616
	v_pk_fma_f32 v[182:183], v[202:203], v[230:231], v[182:183] op_sel_hi:[1,0,1] neg_lo:[0,1,0] neg_hi:[0,1,0]
	v_pk_fma_f32 v[184:185], v[204:205], v[230:231], v[184:185] op_sel_hi:[1,0,1] neg_lo:[0,1,0] neg_hi:[0,1,0]
	ds_read_b128 v[202:205], v233 offset:11632
	s_waitcnt lgkmcnt(4)
	v_pk_fma_f32 v[186:187], v[206:207], v[230:231], v[186:187] op_sel_hi:[1,0,1] neg_lo:[0,1,0] neg_hi:[0,1,0]
	v_pk_fma_f32 v[188:189], v[208:209], v[230:231], v[188:189] op_sel_hi:[1,0,1] neg_lo:[0,1,0] neg_hi:[0,1,0]
	ds_read_b128 v[206:209], v233 offset:11648
	v_pk_fma_f32 v[190:191], v[226:227], v[230:231], v[190:191] op_sel_hi:[1,0,1] neg_lo:[0,1,0] neg_hi:[0,1,0]
	v_pk_fma_f32 v[192:193], v[228:229], v[230:231], v[192:193] op_sel_hi:[1,0,1] neg_lo:[0,1,0] neg_hi:[0,1,0]
	ds_read_b128 v[226:229], v233 offset:11664
	v_mov_b32_e32 v230, v148
	v_cvt_pk_bf16_f32 v232, v230, v230
	global_store_short v28, v232, s[0:1]
	s_add_u32 s0, s0, 0x400
	s_addc_u32 s1, s1, 0
	s_waitcnt lgkmcnt(4)
	v_pk_fma_f32 v[148:149], v[72:73], v[230:231], v[148:149] op_sel_hi:[1,0,1] neg_lo:[0,1,0] neg_hi:[0,1,0]
	v_pk_fma_f32 v[150:151], v[194:195], v[230:231], v[150:151] op_sel_hi:[1,0,1] neg_lo:[0,1,0] neg_hi:[0,1,0]
	v_pk_fma_f32 v[152:153], v[196:197], v[230:231], v[152:153] op_sel_hi:[1,0,1] neg_lo:[0,1,0] neg_hi:[0,1,0]
	ds_read_b128 v[194:197], v233 offset:11872
	s_waitcnt lgkmcnt(3)
	v_pk_fma_f32 v[154:155], v[198:199], v[230:231], v[154:155] op_sel_hi:[1,0,1] neg_lo:[0,1,0] neg_hi:[0,1,0]
	v_pk_fma_f32 v[180:181], v[200:201], v[230:231], v[180:181] op_sel_hi:[1,0,1] neg_lo:[0,1,0] neg_hi:[0,1,0]
	ds_read_b128 v[198:201], v233 offset:11888
	v_pk_fma_f32 v[182:183], v[202:203], v[230:231], v[182:183] op_sel_hi:[1,0,1] neg_lo:[0,1,0] neg_hi:[0,1,0]
	v_pk_fma_f32 v[184:185], v[204:205], v[230:231], v[184:185] op_sel_hi:[1,0,1] neg_lo:[0,1,0] neg_hi:[0,1,0]
	ds_read_b128 v[202:205], v233 offset:11904
	s_waitcnt lgkmcnt(3)
	v_pk_fma_f32 v[186:187], v[206:207], v[230:231], v[186:187] op_sel_hi:[1,0,1] neg_lo:[0,1,0] neg_hi:[0,1,0]
	v_pk_fma_f32 v[188:189], v[208:209], v[230:231], v[188:189] op_sel_hi:[1,0,1] neg_lo:[0,1,0] neg_hi:[0,1,0]
	ds_read_b128 v[206:209], v233 offset:11920
	v_pk_fma_f32 v[190:191], v[226:227], v[230:231], v[190:191] op_sel_hi:[1,0,1] neg_lo:[0,1,0] neg_hi:[0,1,0]
	v_pk_fma_f32 v[192:193], v[228:229], v[230:231], v[192:193] op_sel_hi:[1,0,1] neg_lo:[0,1,0] neg_hi:[0,1,0]
	ds_read_b128 v[226:229], v233 offset:11936
	v_mov_b32_e32 v230, v149
	v_cvt_pk_bf16_f32 v232, v230, v230
	global_store_short v28, v232, s[0:1]
	s_add_u32 s0, s0, 0x400
	s_addc_u32 s1, s1, 0
	s_waitcnt lgkmcnt(3)
	v_pk_fma_f32 v[150:151], v[194:195], v[230:231], v[150:151] op_sel_hi:[1,0,1] neg_lo:[0,1,0] neg_hi:[0,1,0]
	v_pk_fma_f32 v[152:153], v[196:197], v[230:231], v[152:153] op_sel_hi:[1,0,1] neg_lo:[0,1,0] neg_hi:[0,1,0]
	ds_read_b128 v[194:197], v233 offset:12144
	v_pk_fma_f32 v[154:155], v[198:199], v[230:231], v[154:155] op_sel_hi:[1,0,1] neg_lo:[0,1,0] neg_hi:[0,1,0]
	v_pk_fma_f32 v[180:181], v[200:201], v[230:231], v[180:181] op_sel_hi:[1,0,1] neg_lo:[0,1,0] neg_hi:[0,1,0]
	ds_read_b128 v[198:201], v233 offset:12160
	s_waitcnt lgkmcnt(3)
	v_pk_fma_f32 v[182:183], v[202:203], v[230:231], v[182:183] op_sel_hi:[1,0,1] neg_lo:[0,1,0] neg_hi:[0,1,0]
	v_pk_fma_f32 v[184:185], v[204:205], v[230:231], v[184:185] op_sel_hi:[1,0,1] neg_lo:[0,1,0] neg_hi:[0,1,0]
	ds_read_b128 v[202:205], v233 offset:12176
	v_pk_fma_f32 v[186:187], v[206:207], v[230:231], v[186:187] op_sel_hi:[1,0,1] neg_lo:[0,1,0] neg_hi:[0,1,0]
	v_pk_fma_f32 v[188:189], v[208:209], v[230:231], v[188:189] op_sel_hi:[1,0,1] neg_lo:[0,1,0] neg_hi:[0,1,0]
	ds_read_b128 v[206:209], v233 offset:12192
	s_waitcnt lgkmcnt(4)
	v_pk_fma_f32 v[190:191], v[226:227], v[230:231], v[190:191] op_sel_hi:[1,0,1] neg_lo:[0,1,0] neg_hi:[0,1,0]
	v_pk_fma_f32 v[192:193], v[228:229], v[230:231], v[192:193] op_sel_hi:[1,0,1] neg_lo:[0,1,0] neg_hi:[0,1,0]
	ds_read_b128 v[226:229], v233 offset:12208
	v_mov_b32_e32 v230, v150
	v_cvt_pk_bf16_f32 v232, v230, v230
	global_store_short v28, v232, s[0:1]
	s_add_u32 s0, s0, 0x400
	s_addc_u32 s1, s1, 0
	s_waitcnt lgkmcnt(3)
	v_pk_fma_f32 v[150:151], v[194:195], v[230:231], v[150:151] op_sel_hi:[1,0,1] neg_lo:[0,1,0] neg_hi:[0,1,0]
	v_pk_fma_f32 v[152:153], v[196:197], v[230:231], v[152:153] op_sel_hi:[1,0,1] neg_lo:[0,1,0] neg_hi:[0,1,0]
	ds_read_b128 v[194:197], v233 offset:12416
	v_pk_fma_f32 v[154:155], v[198:199], v[230:231], v[154:155] op_sel_hi:[1,0,1] neg_lo:[0,1,0] neg_hi:[0,1,0]
	v_pk_fma_f32 v[180:181], v[200:201], v[230:231], v[180:181] op_sel_hi:[1,0,1] neg_lo:[0,1,0] neg_hi:[0,1,0]
	ds_read_b128 v[198:201], v233 offset:12432
	s_waitcnt lgkmcnt(3)
	v_pk_fma_f32 v[182:183], v[202:203], v[230:231], v[182:183] op_sel_hi:[1,0,1] neg_lo:[0,1,0] neg_hi:[0,1,0]
	v_pk_fma_f32 v[184:185], v[204:205], v[230:231], v[184:185] op_sel_hi:[1,0,1] neg_lo:[0,1,0] neg_hi:[0,1,0]
	ds_read_b128 v[202:205], v233 offset:12448
	v_pk_fma_f32 v[186:187], v[206:207], v[230:231], v[186:187] op_sel_hi:[1,0,1] neg_lo:[0,1,0] neg_hi:[0,1,0]
	v_pk_fma_f32 v[188:189], v[208:209], v[230:231], v[188:189] op_sel_hi:[1,0,1] neg_lo:[0,1,0] neg_hi:[0,1,0]
	ds_read_b128 v[206:209], v233 offset:12464
	s_waitcnt lgkmcnt(4)
	v_pk_fma_f32 v[190:191], v[226:227], v[230:231], v[190:191] op_sel_hi:[1,0,1] neg_lo:[0,1,0] neg_hi:[0,1,0]
	v_pk_fma_f32 v[192:193], v[228:229], v[230:231], v[192:193] op_sel_hi:[1,0,1] neg_lo:[0,1,0] neg_hi:[0,1,0]
	ds_read_b128 v[226:229], v233 offset:12480
	v_mov_b32_e32 v230, v151
	v_cvt_pk_bf16_f32 v232, v230, v230
	global_store_short v28, v232, s[0:1]
	s_add_u32 s0, s0, 0x400
	s_addc_u32 s1, s1, 0
	s_waitcnt lgkmcnt(3)
	v_pk_fma_f32 v[152:153], v[196:197], v[230:231], v[152:153] op_sel_hi:[1,0,1] neg_lo:[0,1,0] neg_hi:[0,1,0]
	ds_read_b128 v[194:197], v233 offset:12688
	v_pk_fma_f32 v[154:155], v[198:199], v[230:231], v[154:155] op_sel_hi:[1,0,1] neg_lo:[0,1,0] neg_hi:[0,1,0]
	v_pk_fma_f32 v[180:181], v[200:201], v[230:231], v[180:181] op_sel_hi:[1,0,1] neg_lo:[0,1,0] neg_hi:[0,1,0]
	ds_read_b128 v[198:201], v233 offset:12704
	s_waitcnt lgkmcnt(3)
	v_pk_fma_f32 v[182:183], v[202:203], v[230:231], v[182:183] op_sel_hi:[1,0,1] neg_lo:[0,1,0] neg_hi:[0,1,0]
	v_pk_fma_f32 v[184:185], v[204:205], v[230:231], v[184:185] op_sel_hi:[1,0,1] neg_lo:[0,1,0] neg_hi:[0,1,0]
	ds_read_b128 v[202:205], v233 offset:12720
	v_pk_fma_f32 v[186:187], v[206:207], v[230:231], v[186:187] op_sel_hi:[1,0,1] neg_lo:[0,1,0] neg_hi:[0,1,0]
	v_pk_fma_f32 v[188:189], v[208:209], v[230:231], v[188:189] op_sel_hi:[1,0,1] neg_lo:[0,1,0] neg_hi:[0,1,0]
	ds_read_b128 v[206:209], v233 offset:12736
	s_waitcnt lgkmcnt(4)
	v_pk_fma_f32 v[190:191], v[226:227], v[230:231], v[190:191] op_sel_hi:[1,0,1] neg_lo:[0,1,0] neg_hi:[0,1,0]
	v_pk_fma_f32 v[192:193], v[228:229], v[230:231], v[192:193] op_sel_hi:[1,0,1] neg_lo:[0,1,0] neg_hi:[0,1,0]
	ds_read_b128 v[226:229], v233 offset:12752
	v_mov_b32_e32 v230, v152
	v_cvt_pk_bf16_f32 v232, v230, v230
	global_store_short v28, v232, s[0:1]
	s_add_u32 s0, s0, 0x400
	s_addc_u32 s1, s1, 0
	s_waitcnt lgkmcnt(3)
	v_pk_fma_f32 v[152:153], v[196:197], v[230:231], v[152:153] op_sel_hi:[1,0,1] neg_lo:[0,1,0] neg_hi:[0,1,0]
	v_pk_fma_f32 v[154:155], v[198:199], v[230:231], v[154:155] op_sel_hi:[1,0,1] neg_lo:[0,1,0] neg_hi:[0,1,0]
	v_pk_fma_f32 v[180:181], v[200:201], v[230:231], v[180:181] op_sel_hi:[1,0,1] neg_lo:[0,1,0] neg_hi:[0,1,0]
	ds_read_b128 v[198:201], v233 offset:12976
	s_waitcnt lgkmcnt(2)
	v_pk_fma_f32 v[182:183], v[202:203], v[230:231], v[182:183] op_sel_hi:[1,0,1] neg_lo:[0,1,0] neg_hi:[0,1,0]
	v_pk_fma_f32 v[184:185], v[204:205], v[230:231], v[184:185] op_sel_hi:[1,0,1] neg_lo:[0,1,0] neg_hi:[0,1,0]
	ds_read_b128 v[202:205], v233 offset:12992
	v_pk_fma_f32 v[186:187], v[206:207], v[230:231], v[186:187] op_sel_hi:[1,0,1] neg_lo:[0,1,0] neg_hi:[0,1,0]
	v_pk_fma_f32 v[188:189], v[208:209], v[230:231], v[188:189] op_sel_hi:[1,0,1] neg_lo:[0,1,0] neg_hi:[0,1,0]
	ds_read_b128 v[206:209], v233 offset:13008
	s_waitcnt lgkmcnt(3)
	v_pk_fma_f32 v[190:191], v[226:227], v[230:231], v[190:191] op_sel_hi:[1,0,1] neg_lo:[0,1,0] neg_hi:[0,1,0]
	v_pk_fma_f32 v[192:193], v[228:229], v[230:231], v[192:193] op_sel_hi:[1,0,1] neg_lo:[0,1,0] neg_hi:[0,1,0]
	ds_read_b128 v[226:229], v233 offset:13024
	v_mov_b32_e32 v230, v153
	v_cvt_pk_bf16_f32 v232, v230, v230
	global_store_short v28, v232, s[0:1]
	s_add_u32 s0, s0, 0x400
	s_addc_u32 s1, s1, 0
	s_waitcnt lgkmcnt(2)
	v_pk_fma_f32 v[154:155], v[198:199], v[230:231], v[154:155] op_sel_hi:[1,0,1] neg_lo:[0,1,0] neg_hi:[0,1,0]
	v_pk_fma_f32 v[180:181], v[200:201], v[230:231], v[180:181] op_sel_hi:[1,0,1] neg_lo:[0,1,0] neg_hi:[0,1,0]
	ds_read_b128 v[198:201], v233 offset:13248
	v_pk_fma_f32 v[182:183], v[202:203], v[230:231], v[182:183] op_sel_hi:[1,0,1] neg_lo:[0,1,0] neg_hi:[0,1,0]
	v_pk_fma_f32 v[184:185], v[204:205], v[230:231], v[184:185] op_sel_hi:[1,0,1] neg_lo:[0,1,0] neg_hi:[0,1,0]
	ds_read_b128 v[202:205], v233 offset:13264
	s_waitcnt lgkmcnt(2)
	v_pk_fma_f32 v[186:187], v[206:207], v[230:231], v[186:187] op_sel_hi:[1,0,1] neg_lo:[0,1,0] neg_hi:[0,1,0]
	v_pk_fma_f32 v[188:189], v[208:209], v[230:231], v[188:189] op_sel_hi:[1,0,1] neg_lo:[0,1,0] neg_hi:[0,1,0]
	ds_read_b128 v[206:209], v233 offset:13280
	v_pk_fma_f32 v[190:191], v[226:227], v[230:231], v[190:191] op_sel_hi:[1,0,1] neg_lo:[0,1,0] neg_hi:[0,1,0]
	v_pk_fma_f32 v[192:193], v[228:229], v[230:231], v[192:193] op_sel_hi:[1,0,1] neg_lo:[0,1,0] neg_hi:[0,1,0]
	ds_read_b128 v[226:229], v233 offset:13296
	v_mov_b32_e32 v230, v154
	v_cvt_pk_bf16_f32 v232, v230, v230
	global_store_short v28, v232, s[0:1]
	s_add_u32 s0, s0, 0x400
	s_addc_u32 s1, s1, 0
	s_waitcnt lgkmcnt(2)
	v_pk_fma_f32 v[154:155], v[198:199], v[230:231], v[154:155] op_sel_hi:[1,0,1] neg_lo:[0,1,0] neg_hi:[0,1,0]
	v_pk_fma_f32 v[180:181], v[200:201], v[230:231], v[180:181] op_sel_hi:[1,0,1] neg_lo:[0,1,0] neg_hi:[0,1,0]
	ds_read_b128 v[198:201], v233 offset:13520
	v_pk_fma_f32 v[182:183], v[202:203], v[230:231], v[182:183] op_sel_hi:[1,0,1] neg_lo:[0,1,0] neg_hi:[0,1,0]
	v_pk_fma_f32 v[184:185], v[204:205], v[230:231], v[184:185] op_sel_hi:[1,0,1] neg_lo:[0,1,0] neg_hi:[0,1,0]
	ds_read_b128 v[202:205], v233 offset:13536
	s_waitcnt lgkmcnt(2)
	v_pk_fma_f32 v[186:187], v[206:207], v[230:231], v[186:187] op_sel_hi:[1,0,1] neg_lo:[0,1,0] neg_hi:[0,1,0]
	v_pk_fma_f32 v[188:189], v[208:209], v[230:231], v[188:189] op_sel_hi:[1,0,1] neg_lo:[0,1,0] neg_hi:[0,1,0]
	ds_read_b128 v[206:209], v233 offset:13552
	v_pk_fma_f32 v[190:191], v[226:227], v[230:231], v[190:191] op_sel_hi:[1,0,1] neg_lo:[0,1,0] neg_hi:[0,1,0]
	v_pk_fma_f32 v[192:193], v[228:229], v[230:231], v[192:193] op_sel_hi:[1,0,1] neg_lo:[0,1,0] neg_hi:[0,1,0]
	ds_read_b128 v[226:229], v233 offset:13568
	v_mov_b32_e32 v230, v155
	v_cvt_pk_bf16_f32 v232, v230, v230
	global_store_short v28, v232, s[0:1]
	s_add_u32 s0, s0, 0x400
	s_addc_u32 s1, s1, 0
	s_waitcnt lgkmcnt(2)
	v_pk_fma_f32 v[180:181], v[200:201], v[230:231], v[180:181] op_sel_hi:[1,0,1] neg_lo:[0,1,0] neg_hi:[0,1,0]
	ds_read_b128 v[198:201], v233 offset:13792
	v_pk_fma_f32 v[182:183], v[202:203], v[230:231], v[182:183] op_sel_hi:[1,0,1] neg_lo:[0,1,0] neg_hi:[0,1,0]
	v_pk_fma_f32 v[184:185], v[204:205], v[230:231], v[184:185] op_sel_hi:[1,0,1] neg_lo:[0,1,0] neg_hi:[0,1,0]
	ds_read_b128 v[202:205], v233 offset:13808
	s_waitcnt lgkmcnt(2)
	v_pk_fma_f32 v[186:187], v[206:207], v[230:231], v[186:187] op_sel_hi:[1,0,1] neg_lo:[0,1,0] neg_hi:[0,1,0]
	v_pk_fma_f32 v[188:189], v[208:209], v[230:231], v[188:189] op_sel_hi:[1,0,1] neg_lo:[0,1,0] neg_hi:[0,1,0]
	ds_read_b128 v[206:209], v233 offset:13824
	v_pk_fma_f32 v[190:191], v[226:227], v[230:231], v[190:191] op_sel_hi:[1,0,1] neg_lo:[0,1,0] neg_hi:[0,1,0]
	v_pk_fma_f32 v[192:193], v[228:229], v[230:231], v[192:193] op_sel_hi:[1,0,1] neg_lo:[0,1,0] neg_hi:[0,1,0]
	ds_read_b128 v[226:229], v233 offset:13840
	v_mov_b32_e32 v230, v180
	v_cvt_pk_bf16_f32 v232, v230, v230
	global_store_short v28, v232, s[0:1]
	s_add_u32 s0, s0, 0x400
	s_addc_u32 s1, s1, 0
	s_waitcnt lgkmcnt(2)
	v_pk_fma_f32 v[180:181], v[200:201], v[230:231], v[180:181] op_sel_hi:[1,0,1] neg_lo:[0,1,0] neg_hi:[0,1,0]
	v_pk_fma_f32 v[182:183], v[202:203], v[230:231], v[182:183] op_sel_hi:[1,0,1] neg_lo:[0,1,0] neg_hi:[0,1,0]
	v_pk_fma_f32 v[184:185], v[204:205], v[230:231], v[184:185] op_sel_hi:[1,0,1] neg_lo:[0,1,0] neg_hi:[0,1,0]
	ds_read_b128 v[202:205], v233 offset:14080
	s_waitcnt lgkmcnt(1)
	v_pk_fma_f32 v[186:187], v[206:207], v[230:231], v[186:187] op_sel_hi:[1,0,1] neg_lo:[0,1,0] neg_hi:[0,1,0]
	v_pk_fma_f32 v[188:189], v[208:209], v[230:231], v[188:189] op_sel_hi:[1,0,1] neg_lo:[0,1,0] neg_hi:[0,1,0]
	ds_read_b128 v[206:209], v233 offset:14096
	v_pk_fma_f32 v[190:191], v[226:227], v[230:231], v[190:191] op_sel_hi:[1,0,1] neg_lo:[0,1,0] neg_hi:[0,1,0]
	v_pk_fma_f32 v[192:193], v[228:229], v[230:231], v[192:193] op_sel_hi:[1,0,1] neg_lo:[0,1,0] neg_hi:[0,1,0]
	ds_read_b128 v[226:229], v233 offset:14112
	v_mov_b32_e32 v230, v181
	v_cvt_pk_bf16_f32 v232, v230, v230
	global_store_short v28, v232, s[0:1]
	s_add_u32 s0, s0, 0x400
	s_addc_u32 s1, s1, 0
	s_waitcnt lgkmcnt(1)
	v_pk_fma_f32 v[182:183], v[202:203], v[230:231], v[182:183] op_sel_hi:[1,0,1] neg_lo:[0,1,0] neg_hi:[0,1,0]
	v_pk_fma_f32 v[184:185], v[204:205], v[230:231], v[184:185] op_sel_hi:[1,0,1] neg_lo:[0,1,0] neg_hi:[0,1,0]
	ds_read_b128 v[202:205], v233 offset:14352
	v_pk_fma_f32 v[186:187], v[206:207], v[230:231], v[186:187] op_sel_hi:[1,0,1] neg_lo:[0,1,0] neg_hi:[0,1,0]
	v_pk_fma_f32 v[188:189], v[208:209], v[230:231], v[188:189] op_sel_hi:[1,0,1] neg_lo:[0,1,0] neg_hi:[0,1,0]
	ds_read_b128 v[206:209], v233 offset:14368
	s_waitcnt lgkmcnt(2)
	v_pk_fma_f32 v[190:191], v[226:227], v[230:231], v[190:191] op_sel_hi:[1,0,1] neg_lo:[0,1,0] neg_hi:[0,1,0]
	v_pk_fma_f32 v[192:193], v[228:229], v[230:231], v[192:193] op_sel_hi:[1,0,1] neg_lo:[0,1,0] neg_hi:[0,1,0]
	ds_read_b128 v[226:229], v233 offset:14384
	v_mov_b32_e32 v230, v182
	v_cvt_pk_bf16_f32 v232, v230, v230
	global_store_short v28, v232, s[0:1]
	s_add_u32 s0, s0, 0x400
	s_addc_u32 s1, s1, 0
	s_waitcnt lgkmcnt(1)
	v_pk_fma_f32 v[182:183], v[202:203], v[230:231], v[182:183] op_sel_hi:[1,0,1] neg_lo:[0,1,0] neg_hi:[0,1,0]
	v_pk_fma_f32 v[184:185], v[204:205], v[230:231], v[184:185] op_sel_hi:[1,0,1] neg_lo:[0,1,0] neg_hi:[0,1,0]
	ds_read_b128 v[202:205], v233 offset:14624
	v_pk_fma_f32 v[186:187], v[206:207], v[230:231], v[186:187] op_sel_hi:[1,0,1] neg_lo:[0,1,0] neg_hi:[0,1,0]
	v_pk_fma_f32 v[188:189], v[208:209], v[230:231], v[188:189] op_sel_hi:[1,0,1] neg_lo:[0,1,0] neg_hi:[0,1,0]
	ds_read_b128 v[206:209], v233 offset:14640
	s_waitcnt lgkmcnt(2)
	v_pk_fma_f32 v[190:191], v[226:227], v[230:231], v[190:191] op_sel_hi:[1,0,1] neg_lo:[0,1,0] neg_hi:[0,1,0]
	v_pk_fma_f32 v[192:193], v[228:229], v[230:231], v[192:193] op_sel_hi:[1,0,1] neg_lo:[0,1,0] neg_hi:[0,1,0]
	ds_read_b128 v[226:229], v233 offset:14656
	v_mov_b32_e32 v230, v183
	v_cvt_pk_bf16_f32 v232, v230, v230
	global_store_short v28, v232, s[0:1]
	s_add_u32 s0, s0, 0x400
	s_addc_u32 s1, s1, 0
	s_waitcnt lgkmcnt(1)
	v_pk_fma_f32 v[184:185], v[204:205], v[230:231], v[184:185] op_sel_hi:[1,0,1] neg_lo:[0,1,0] neg_hi:[0,1,0]
	ds_read_b128 v[202:205], v233 offset:14896
	v_pk_fma_f32 v[186:187], v[206:207], v[230:231], v[186:187] op_sel_hi:[1,0,1] neg_lo:[0,1,0] neg_hi:[0,1,0]
	v_pk_fma_f32 v[188:189], v[208:209], v[230:231], v[188:189] op_sel_hi:[1,0,1] neg_lo:[0,1,0] neg_hi:[0,1,0]
	ds_read_b128 v[206:209], v233 offset:14912
	s_waitcnt lgkmcnt(2)
	v_pk_fma_f32 v[190:191], v[226:227], v[230:231], v[190:191] op_sel_hi:[1,0,1] neg_lo:[0,1,0] neg_hi:[0,1,0]
	v_pk_fma_f32 v[192:193], v[228:229], v[230:231], v[192:193] op_sel_hi:[1,0,1] neg_lo:[0,1,0] neg_hi:[0,1,0]
	ds_read_b128 v[226:229], v233 offset:14928
	v_mov_b32_e32 v230, v184
	v_cvt_pk_bf16_f32 v232, v230, v230
	global_store_short v28, v232, s[0:1]
	s_add_u32 s0, s0, 0x400
	s_addc_u32 s1, s1, 0
	s_waitcnt lgkmcnt(1)
	v_pk_fma_f32 v[184:185], v[204:205], v[230:231], v[184:185] op_sel_hi:[1,0,1] neg_lo:[0,1,0] neg_hi:[0,1,0]
	v_pk_fma_f32 v[186:187], v[206:207], v[230:231], v[186:187] op_sel_hi:[1,0,1] neg_lo:[0,1,0] neg_hi:[0,1,0]
	v_pk_fma_f32 v[188:189], v[208:209], v[230:231], v[188:189] op_sel_hi:[1,0,1] neg_lo:[0,1,0] neg_hi:[0,1,0]
	ds_read_b128 v[206:209], v233 offset:15184
	s_waitcnt lgkmcnt(1)
	v_pk_fma_f32 v[190:191], v[226:227], v[230:231], v[190:191] op_sel_hi:[1,0,1] neg_lo:[0,1,0] neg_hi:[0,1,0]
	v_pk_fma_f32 v[192:193], v[228:229], v[230:231], v[192:193] op_sel_hi:[1,0,1] neg_lo:[0,1,0] neg_hi:[0,1,0]
	ds_read_b128 v[226:229], v233 offset:15200
	v_mov_b32_e32 v230, v185
	v_cvt_pk_bf16_f32 v232, v230, v230
	global_store_short v28, v232, s[0:1]
	s_add_u32 s0, s0, 0x400
	s_addc_u32 s1, s1, 0
	s_waitcnt lgkmcnt(0)
	v_pk_fma_f32 v[186:187], v[206:207], v[230:231], v[186:187] op_sel_hi:[1,0,1] neg_lo:[0,1,0] neg_hi:[0,1,0]
	v_pk_fma_f32 v[188:189], v[208:209], v[230:231], v[188:189] op_sel_hi:[1,0,1] neg_lo:[0,1,0] neg_hi:[0,1,0]
	ds_read_b128 v[206:209], v233 offset:15456
	v_pk_fma_f32 v[190:191], v[226:227], v[230:231], v[190:191] op_sel_hi:[1,0,1] neg_lo:[0,1,0] neg_hi:[0,1,0]
	v_pk_fma_f32 v[192:193], v[228:229], v[230:231], v[192:193] op_sel_hi:[1,0,1] neg_lo:[0,1,0] neg_hi:[0,1,0]
	ds_read_b128 v[226:229], v233 offset:15472
	v_mov_b32_e32 v230, v186
	v_cvt_pk_bf16_f32 v232, v230, v230
	global_store_short v28, v232, s[0:1]
	s_add_u32 s0, s0, 0x400
	s_addc_u32 s1, s1, 0
	s_waitcnt lgkmcnt(0)
	v_pk_fma_f32 v[186:187], v[206:207], v[230:231], v[186:187] op_sel_hi:[1,0,1] neg_lo:[0,1,0] neg_hi:[0,1,0]
	v_pk_fma_f32 v[188:189], v[208:209], v[230:231], v[188:189] op_sel_hi:[1,0,1] neg_lo:[0,1,0] neg_hi:[0,1,0]
	ds_read_b128 v[206:209], v233 offset:15728
	v_pk_fma_f32 v[190:191], v[226:227], v[230:231], v[190:191] op_sel_hi:[1,0,1] neg_lo:[0,1,0] neg_hi:[0,1,0]
	v_pk_fma_f32 v[192:193], v[228:229], v[230:231], v[192:193] op_sel_hi:[1,0,1] neg_lo:[0,1,0] neg_hi:[0,1,0]
	ds_read_b128 v[226:229], v233 offset:15744
	v_mov_b32_e32 v230, v187
	v_cvt_pk_bf16_f32 v232, v230, v230
	global_store_short v28, v232, s[0:1]
	s_add_u32 s0, s0, 0x400
	s_addc_u32 s1, s1, 0
	s_waitcnt lgkmcnt(0)
	v_pk_fma_f32 v[188:189], v[208:209], v[230:231], v[188:189] op_sel_hi:[1,0,1] neg_lo:[0,1,0] neg_hi:[0,1,0]
	ds_read_b128 v[206:209], v233 offset:16000
	v_pk_fma_f32 v[190:191], v[226:227], v[230:231], v[190:191] op_sel_hi:[1,0,1] neg_lo:[0,1,0] neg_hi:[0,1,0]
	v_pk_fma_f32 v[192:193], v[228:229], v[230:231], v[192:193] op_sel_hi:[1,0,1] neg_lo:[0,1,0] neg_hi:[0,1,0]
	ds_read_b128 v[226:229], v233 offset:16016
	v_mov_b32_e32 v230, v188
	v_cvt_pk_bf16_f32 v232, v230, v230
	global_store_short v28, v232, s[0:1]
	s_add_u32 s0, s0, 0x400
	s_addc_u32 s1, s1, 0
	s_waitcnt lgkmcnt(0)
	v_pk_fma_f32 v[188:189], v[208:209], v[230:231], v[188:189] op_sel_hi:[1,0,1] neg_lo:[0,1,0] neg_hi:[0,1,0]
	v_pk_fma_f32 v[190:191], v[226:227], v[230:231], v[190:191] op_sel_hi:[1,0,1] neg_lo:[0,1,0] neg_hi:[0,1,0]
	v_pk_fma_f32 v[192:193], v[228:229], v[230:231], v[192:193] op_sel_hi:[1,0,1] neg_lo:[0,1,0] neg_hi:[0,1,0]
	ds_read_b128 v[226:229], v233 offset:16288
	v_mov_b32_e32 v230, v189
	v_cvt_pk_bf16_f32 v232, v230, v230
	global_store_short v28, v232, s[0:1]
	s_add_u32 s0, s0, 0x400
	s_addc_u32 s1, s1, 0
	s_waitcnt lgkmcnt(0)
	v_pk_fma_f32 v[190:191], v[226:227], v[230:231], v[190:191] op_sel_hi:[1,0,1] neg_lo:[0,1,0] neg_hi:[0,1,0]
	v_pk_fma_f32 v[192:193], v[228:229], v[230:231], v[192:193] op_sel_hi:[1,0,1] neg_lo:[0,1,0] neg_hi:[0,1,0]
	ds_read_b128 v[226:229], v233 offset:16560
	v_mov_b32_e32 v230, v190
	v_cvt_pk_bf16_f32 v232, v230, v230
	global_store_short v28, v232, s[0:1]
	s_add_u32 s0, s0, 0x400
	s_addc_u32 s1, s1, 0
	s_waitcnt lgkmcnt(0)
	v_pk_fma_f32 v[190:191], v[226:227], v[230:231], v[190:191] op_sel_hi:[1,0,1] neg_lo:[0,1,0] neg_hi:[0,1,0]
	v_pk_fma_f32 v[192:193], v[228:229], v[230:231], v[192:193] op_sel_hi:[1,0,1] neg_lo:[0,1,0] neg_hi:[0,1,0]
	ds_read_b128 v[226:229], v233 offset:16832
	v_mov_b32_e32 v230, v191
	v_cvt_pk_bf16_f32 v232, v230, v230
	global_store_short v28, v232, s[0:1]
	s_add_u32 s0, s0, 0x400
	s_addc_u32 s1, s1, 0
	s_waitcnt lgkmcnt(0)
	v_pk_fma_f32 v[192:193], v[228:229], v[230:231], v[192:193] op_sel_hi:[1,0,1] neg_lo:[0,1,0] neg_hi:[0,1,0]
	ds_read_b128 v[226:229], v233 offset:17104
	v_mov_b32_e32 v230, v192
	v_cvt_pk_bf16_f32 v232, v230, v230
	global_store_short v28, v232, s[0:1]
	s_add_u32 s0, s0, 0x400
	s_addc_u32 s1, s1, 0
	s_waitcnt lgkmcnt(0)
	v_pk_fma_f32 v[192:193], v[228:229], v[230:231], v[192:193] op_sel_hi:[1,0,1] neg_lo:[0,1,0] neg_hi:[0,1,0]
	v_cvt_pk_bf16_f32 v232, v193, v193
	global_store_short v28, v232, s[0:1]

.LBB0_560:
	s_and_b64 vcc, exec, s[0:1]
	s_cbranch_vccz .LBB0_426
	s_branch .Lfs_start
